# mix_out Y stores widened (permlane32_swap); hand-written S5 chunk scan; phase-B weight-conversion jobs rotated over waves; merge: half of the parked branch tile kept in VGPRs (borrowed long-lived regs
# speedup vs baseline: 1.1196x; 1.0144x over previous
.Lgs_227:
	s_or_b64 exec, exec, s[4:5]
	s_lshl_b32 s38, s2, 9
	v_mov_b32_e32 v4, v224
	s_barrier
	s_mov_b64 s[4:5], s[78:79]
	v_readfirstlane_b32 s0, v4
	s_ashr_i32 s40, s0, 6
	s_mul_i32 s0, s40, 0x2100
	s_add_i32 s41, s0, 0
	s_mov_b64 s[0:1], s[78:79]
	s_load_dwordx2 s[0:1], s[0:1], 0x100
	s_load_dwordx2 s[8:9], s[4:5], 0x40
	s_lshl_b32 s70, s2, 3
	s_lshl_b32 s63, s64, 3
	s_add_i32 s39, s40, s70
	s_sub_i32 s81, s39, 0xe0
	s_and_b32 s81, s81, 0x7ff
	s_sub_i32 s82, s39, 0x140
	s_and_b32 s82, s82, 0x7ff
	s_sub_i32 s83, s39, 0x2c0
	s_and_b32 s83, s83, 0x7ff
	s_sub_i32 s84, s39, 0x4b0
	s_and_b32 s84, s84, 0x7ff
	s_sub_i32 s85, s39, 0x2b0
	s_and_b32 s85, s85, 0x7ff
	s_sub_i32 s86, s39, 0x330
	s_and_b32 s86, s86, 0x7ff
	s_sub_i32 s87, s39, 0x3f0
	s_and_b32 s87, s87, 0x7ff
	s_sub_i32 s88, s39, 0x5f0
	s_and_b32 s88, s88, 0x7ff
	s_sub_i32 s89, s39, 0xf0
	s_and_b32 s89, s89, 0x7ff
	s_sub_i32 s90, s39, 0x670
	s_and_b32 s90, s90, 0x7ff
	v_and_b32_e32 v0, 63, v4
	s_cmpk_lt_i32 s39, 0xe0
	s_cselect_b64 s[4:5], -1, 0
	s_cmpk_gt_i32 s39, 0xdf
	v_lshrrev_b32_e32 v12, 5, v0
	v_lshlrev_b32_e32 v15, 2, v4
	v_lshrrev_b32_e32 v13, 3, v0
	v_lshlrev_b32_e32 v14, 3, v0
	s_cbranch_scc1 .LBB0_68
	v_and_b32_e32 v2, 0x7c, v15
	v_mov_b32_e32 v3, 0
	s_waitcnt lgkmcnt(0)
	v_lshl_add_u64 v[0:1], s[8:9], 0, v[2:3]
	v_add_u32_e32 v6, s41, v2
	v_mul_u32_u24_e32 v7, 0x84, v12
	v_and_b32_e32 v2, 56, v14
	v_mul_u32_u24_e32 v5, 0x84, v2
	v_lshlrev_b32_e32 v2, 1, v2
	v_lshlrev_b32_e32 v8, 2, v13
	s_lshl_b32 s3, s2, 8
	s_lshl_b32 s6, s40, 5
	v_add_u32_e32 v6, v6, v7
	v_lshl_add_u64 v[2:3], s[0:1], 0, v[2:3]
	v_add3_u32 v5, s41, v5, v8
	s_add_i32 s3, s3, s6
	s_lshl_b32 s12, s64, 8
	s_movk_i32 s13, 0x5880
	v_add_u32_e32 v7, 0x400, v6
	v_add_u32_e32 v8, 0x800, v6
	v_add_u32_e32 v9, 0xc00, v6
	v_add_u32_e32 v10, 0x1000, v6
	v_add_u32_e32 v11, 0x1400, v6
	v_add_u32_e32 v16, 0x1800, v6
	v_add_u32_e32 v17, 0x1c00, v6
	s_mov_b32 s14, s39

.LBB0_68:
	s_cmpk_lt_i32 s81, 0x60
	s_cselect_b64 s[10:11], -1, 0
	s_cmpk_gt_i32 s81, 0x5f
	s_cbranch_scc1 .LBB0_71
	v_and_b32_e32 v2, 0x7c, v15
	v_mov_b32_e32 v3, 0
	s_waitcnt lgkmcnt(0)
	v_lshl_add_u64 v[0:1], s[8:9], 0, v[2:3]
	v_add_u32_e32 v6, s41, v2
	v_mul_u32_u24_e32 v7, 0x84, v12
	v_and_b32_e32 v2, 56, v14
	v_mul_u32_u24_e32 v5, 0x84, v2
	v_lshlrev_b32_e32 v2, 1, v2
	v_lshlrev_b32_e32 v8, 2, v13
	s_lshl_b32 s3, s81, 5
	s_mov_b32 s6, 0
	v_add_u32_e32 v6, v6, v7
	v_lshl_add_u64 v[2:3], s[0:1], 0, v[2:3]
	v_add3_u32 v5, s41, v5, v8
	s_add_i32 s3, s3, s6
	s_lshl_b32 s7, s64, 8
	s_movk_i32 s12, 0x5880
	s_mov_b32 s6, 0x3e13cd3a
	v_add_u32_e32 v7, 0x400, v6
	v_add_u32_e32 v8, 0x800, v6
	v_add_u32_e32 v9, 0xc00, v6
	v_add_u32_e32 v10, 0x1000, v6
	v_add_u32_e32 v11, 0x1400, v6
	v_add_u32_e32 v16, 0x1800, v6
	v_add_u32_e32 v17, 0x1c00, v6
	s_mov_b32 s13, s81

.LBB0_71:
	s_cmpk_lt_i32 s82, 0x180
	s_cselect_b64 s[12:13], -1, 0
	s_cmpk_gt_i32 s82, 0x17f
	s_cbranch_scc1 .LBB0_74
	v_and_b32_e32 v2, 0x7c, v15
	v_mov_b32_e32 v3, 0
	s_waitcnt lgkmcnt(0)
	v_lshl_add_u64 v[0:1], s[8:9], 0, v[2:3]
	v_add_u32_e32 v6, s41, v2
	v_mul_u32_u24_e32 v7, 0x84, v12
	v_and_b32_e32 v2, 56, v14
	v_mul_u32_u24_e32 v5, 0x84, v2
	v_lshlrev_b32_e32 v2, 1, v2
	v_lshlrev_b32_e32 v8, 2, v13
	s_lshl_b32 s3, s82, 5
	s_mov_b32 s6, 0
	v_add_u32_e32 v6, v6, v7
	v_lshl_add_u64 v[2:3], s[0:1], 0, v[2:3]
	v_add3_u32 v5, s41, v5, v8
	s_add_i32 s3, s3, s6
	s_lshl_b32 s16, s64, 8
	s_movk_i32 s17, 0x5880
	v_add_u32_e32 v7, 0x400, v6
	v_add_u32_e32 v8, 0x800, v6
	v_add_u32_e32 v9, 0xc00, v6
	v_add_u32_e32 v10, 0x1000, v6
	v_add_u32_e32 v11, 0x1400, v6
	v_add_u32_e32 v16, 0x1800, v6
	v_add_u32_e32 v17, 0x1c00, v6
	s_mov_b32 s18, s82

.LBB0_74:
	v_cndmask_b32_e64 v0, 0, 1, s[10:11]
	v_cmp_ne_u32_e64 s[6:7], 1, v0
	s_andn2_b64 vcc, exec, s[10:11]
	s_cbranch_vccnz .LBB0_77
	v_and_b32_e32 v2, 0x7c, v15
	v_mov_b32_e32 v3, 0
	s_waitcnt lgkmcnt(0)
	v_lshl_add_u64 v[0:1], s[8:9], 0, v[2:3]
	v_add_u32_e32 v7, s41, v2
	v_mul_u32_u24_e32 v8, 0x84, v12
	v_and_b32_e32 v2, 56, v14
	v_mul_u32_u24_e32 v5, 0x84, v2
	v_lshlrev_b32_e32 v2, 1, v2
	v_lshlrev_b32_e32 v6, 2, v13
	s_lshl_b32 s10, s81, 5
	v_add_u32_e32 v7, v7, v8
	v_lshl_add_u64 v[2:3], s[0:1], 0, v[2:3]
	v_add3_u32 v5, s41, v5, v6
	s_mov_b32 s3, 0
	v_or_b32_e32 v6, s10, v13
	s_lshl_b32 s11, s64, 8
	s_add_i32 s14, s10, 0x580
	s_movk_i32 s15, 0x5880
	s_mov_b32 s10, 0x3e13cd3a
	v_add_u32_e32 v8, 0x400, v7
	v_add_u32_e32 v9, 0x800, v7
	v_add_u32_e32 v10, 0xc00, v7
	v_add_u32_e32 v11, 0x1000, v7
	v_add_u32_e32 v16, 0x1400, v7
	v_add_u32_e32 v17, 0x1800, v7
	v_add_u32_e32 v18, 0x1c00, v7
	s_mov_b32 s16, s81

.LBB0_77:
	s_cmpk_lt_i32 s83, 0x1f0
	s_cselect_b64 s[18:19], -1, 0
	s_cmpk_gt_i32 s83, 0x1ef
	s_cbranch_scc1 .LBB0_80
	v_and_b32_e32 v2, 0x7c, v15
	v_mov_b32_e32 v3, 0
	s_waitcnt lgkmcnt(0)
	v_lshl_add_u64 v[0:1], s[8:9], 0, v[2:3]
	v_add_u32_e32 v7, s41, v2
	v_mul_u32_u24_e32 v8, 0x84, v12
	v_and_b32_e32 v2, 56, v14
	v_mul_u32_u24_e32 v5, 0x84, v2
	v_lshlrev_b32_e32 v2, 1, v2
	v_lshlrev_b32_e32 v6, 2, v13
	s_lshl_b32 s10, s83, 5
	v_add_u32_e32 v7, v7, v8
	v_lshl_add_u64 v[2:3], s[0:1], 0, v[2:3]
	v_add3_u32 v5, s41, v5, v6
	s_mov_b32 s3, 0
	v_or_b32_e32 v6, s10, v13
	s_lshl_b32 s16, s64, 8
	s_add_i32 s17, s10, 0x640
	s_movk_i32 s20, 0x5880
	v_add_u32_e32 v8, 0x400, v7
	v_add_u32_e32 v9, 0x800, v7
	v_add_u32_e32 v10, 0xc00, v7
	v_add_u32_e32 v11, 0x1000, v7
	v_add_u32_e32 v16, 0x1400, v7
	v_add_u32_e32 v17, 0x1800, v7
	v_add_u32_e32 v18, 0x1c00, v7
	s_mov_b32 s21, s83

.LBB0_80:
	s_cmpk_lt_i32 s84, 0x600
	s_cselect_b64 s[20:21], -1, 0
	s_cmpk_gt_i32 s84, 0x5ff
	s_cbranch_scc1 .LBB0_83
	v_and_b32_e32 v2, 0x7c, v15
	v_mov_b32_e32 v3, 0
	s_waitcnt lgkmcnt(0)
	v_lshl_add_u64 v[0:1], s[8:9], 0, v[2:3]
	v_add_u32_e32 v6, s41, v2
	v_and_b32_e32 v2, 56, v14
	v_mul_u32_u24_e32 v5, 0x84, v2
	v_lshlrev_b32_e32 v2, 1, v2
	v_mul_u32_u24_e32 v7, 0x84, v12
	v_lshl_add_u64 v[2:3], s[0:1], 0, v[2:3]
	s_mov_b64 s[8:9], 0x580000
	v_lshl_add_u64 v[2:3], v[2:3], 0, s[8:9]
	v_lshlrev_b32_e32 v8, 2, v13
	s_lshl_b32 s3, s84, 5
	s_mov_b32 s8, 0
	v_add_u32_e32 v6, v6, v7
	v_add3_u32 v5, s41, v5, v8
	s_add_i32 s3, s3, s8
	s_lshl_b32 s16, s64, 8
	s_mov_b64 s[8:9], 0x2880
	s_movk_i32 s17, 0x5880
	v_add_u32_e32 v7, 0x400, v6
	v_add_u32_e32 v8, 0x800, v6
	v_add_u32_e32 v9, 0xc00, v6
	v_add_u32_e32 v10, 0x1000, v6
	v_add_u32_e32 v11, 0x1400, v6
	v_add_u32_e32 v16, 0x1800, v6
	v_add_u32_e32 v17, 0x1c00, v6
	s_mov_b32 s22, s84

.LBB0_83:
	s_cmpk_lt_i32 s85, 0x80
	s_waitcnt lgkmcnt(0)
	s_mov_b64 s[8:9], s[78:79]
	s_cselect_b64 s[22:23], -1, 0
	s_cmpk_gt_i32 s85, 0x7f
	s_cbranch_scc1 .LBB0_86
	s_load_dwordx2 s[8:9], s[8:9], 0xc0
	v_and_b32_e32 v2, 0x7c, v15
	v_mov_b32_e32 v3, 0
	v_add_u32_e32 v7, s41, v2
	v_mul_u32_u24_e32 v6, 0x84, v12
	s_waitcnt lgkmcnt(0)
	v_lshl_add_u64 v[0:1], s[8:9], 0, v[2:3]
	v_and_b32_e32 v2, 56, v14
	v_mul_u32_u24_e32 v5, 0x84, v2
	v_lshlrev_b32_e32 v2, 1, v2
	v_lshl_add_u64 v[2:3], s[0:1], 0, v[2:3]
	s_mov_b64 s[8:9], 0xb80000
	v_lshl_add_u64 v[2:3], v[2:3], 0, s[8:9]
	v_lshlrev_b32_e32 v8, 2, v13
	s_lshl_b32 s3, s85, 5
	s_mov_b32 s8, 0
	v_add_u32_e32 v6, v7, v6
	v_add3_u32 v5, s41, v5, v8
	s_add_i32 s3, s3, s8
	s_lshl_b32 s14, s64, 8
	v_add_u32_e32 v7, 0x400, v6
	v_add_u32_e32 v8, 0x800, v6
	v_add_u32_e32 v9, 0xc00, v6
	v_add_u32_e32 v10, 0x1000, v6
	v_add_u32_e32 v11, 0x1400, v6
	v_add_u32_e32 v16, 0x1800, v6
	v_add_u32_e32 v17, 0x1c00, v6
	s_mov_b32 s15, s85

.LBB0_86:
	s_cmpk_lt_i32 s86, 0xc0
	s_mov_b64 s[8:9], s[78:79]
	s_cselect_b64 s[10:11], -1, 0
	s_cmpk_gt_i32 s86, 0xbf
	s_cbranch_scc1 .LBB0_89
	s_load_dwordx2 s[8:9], s[8:9], 0xc8
	v_and_b32_e32 v2, 0x7c, v15
	v_mov_b32_e32 v3, 0
	v_add_u32_e32 v7, s41, v2
	v_mul_u32_u24_e32 v6, 0x84, v12
	s_waitcnt lgkmcnt(0)
	v_lshl_add_u64 v[0:1], s[8:9], 0, v[2:3]
	v_and_b32_e32 v2, 56, v14
	v_mul_u32_u24_e32 v5, 0x84, v2
	v_lshlrev_b32_e32 v2, 1, v2
	v_lshl_add_u64 v[2:3], s[0:1], 0, v[2:3]
	s_mov_b64 s[8:9], 0xb80200
	v_lshl_add_u64 v[2:3], v[2:3], 0, s[8:9]
	v_lshlrev_b32_e32 v8, 2, v13
	s_lshl_b32 s3, s86, 5
	s_mov_b32 s8, 0
	v_add_u32_e32 v6, v7, v6
	v_add3_u32 v5, s41, v5, v8
	s_add_i32 s3, s3, s8
	s_lshl_b32 s16, s64, 8
	v_add_u32_e32 v7, 0x400, v6
	v_add_u32_e32 v8, 0x800, v6
	v_add_u32_e32 v9, 0xc00, v6
	v_add_u32_e32 v10, 0x1000, v6
	v_add_u32_e32 v11, 0x1400, v6
	v_add_u32_e32 v16, 0x1800, v6
	v_add_u32_e32 v17, 0x1c00, v6
	s_mov_b32 s17, s86

.LBB0_89:
	v_cndmask_b32_e64 v0, 0, 1, s[10:11]
	s_mov_b64 s[14:15], s[78:79]
	v_cmp_ne_u32_e64 s[8:9], 1, v0
	s_andn2_b64 vcc, exec, s[10:11]
	s_cbranch_vccnz .LBB0_92
	s_load_dwordx2 s[10:11], s[14:15], 0xd0
	v_and_b32_e32 v2, 0x7c, v15
	v_mov_b32_e32 v3, 0
	v_add_u32_e32 v7, s41, v2
	v_mul_u32_u24_e32 v6, 0x84, v12
	s_waitcnt lgkmcnt(0)
	v_lshl_add_u64 v[0:1], s[10:11], 0, v[2:3]
	v_and_b32_e32 v2, 56, v14
	v_mul_u32_u24_e32 v5, 0x84, v2
	v_lshlrev_b32_e32 v2, 1, v2
	v_lshl_add_u64 v[2:3], s[0:1], 0, v[2:3]
	s_mov_b64 s[10:11], 0xb80500
	v_lshl_add_u64 v[2:3], v[2:3], 0, s[10:11]
	v_lshlrev_b32_e32 v8, 2, v13
	s_lshl_b32 s3, s86, 5
	s_mov_b32 s10, 0
	v_add_u32_e32 v6, v7, v6
	v_add3_u32 v5, s41, v5, v8
	s_add_i32 s3, s3, s10
	s_lshl_b32 s16, s64, 8
	v_add_u32_e32 v7, 0x400, v6
	v_add_u32_e32 v8, 0x800, v6
	v_add_u32_e32 v9, 0xc00, v6
	v_add_u32_e32 v10, 0x1000, v6
	v_add_u32_e32 v11, 0x1400, v6
	v_add_u32_e32 v16, 0x1800, v6
	v_add_u32_e32 v17, 0x1c00, v6
	s_mov_b32 s17, s86

.LBB0_92:
	s_cmpk_lt_i32 s87, 0x200
	s_mov_b64 s[10:11], s[78:79]
	s_cselect_b64 s[26:27], -1, 0
	s_cmpk_gt_i32 s87, 0x1ff
	s_cbranch_scc1 .LBB0_95
	s_load_dwordx2 s[10:11], s[10:11], 0xd8
	v_and_b32_e32 v2, 0x7c, v15
	v_mov_b32_e32 v3, 0
	v_add_u32_e32 v7, s41, v2
	v_mul_u32_u24_e32 v6, 0x84, v12
	s_waitcnt lgkmcnt(0)
	v_lshl_add_u64 v[0:1], s[10:11], 0, v[2:3]
	v_and_b32_e32 v2, 56, v14
	v_mul_u32_u24_e32 v5, 0x84, v2
	v_lshlrev_b32_e32 v2, 1, v2
	v_lshl_add_u64 v[2:3], s[0:1], 0, v[2:3]
	s_mov_b64 s[10:11], 0xd80000
	v_lshl_add_u64 v[2:3], v[2:3], 0, s[10:11]
	v_lshlrev_b32_e32 v8, 2, v13
	s_lshl_b32 s3, s87, 5
	s_mov_b32 s10, 0
	v_add_u32_e32 v6, v7, v6
	v_add3_u32 v5, s41, v5, v8
	s_add_i32 s3, s3, s10
	s_lshl_b32 s16, s64, 8
	v_add_u32_e32 v7, 0x400, v6
	v_add_u32_e32 v8, 0x800, v6
	v_add_u32_e32 v9, 0xc00, v6
	v_add_u32_e32 v10, 0x1000, v6
	v_add_u32_e32 v11, 0x1400, v6
	v_add_u32_e32 v16, 0x1800, v6
	v_add_u32_e32 v17, 0x1c00, v6
	s_mov_b32 s17, s87

.LBB0_95:
	s_cmpk_lt_i32 s88, 0xb00
	s_mov_b64 s[10:11], s[78:79]
	s_cselect_b64 s[24:25], -1, 0
	s_cmpk_gt_i32 s88, 0xaff
	s_cbranch_scc1 .LBB0_98
	s_load_dwordx2 s[10:11], s[10:11], 0xe0
	v_and_b32_e32 v2, 0x7c, v15
	v_mov_b32_e32 v3, 0
	v_add_u32_e32 v7, s41, v2
	v_mul_u32_u24_e32 v6, 0x84, v12
	s_waitcnt lgkmcnt(0)
	v_lshl_add_u64 v[0:1], s[10:11], 0, v[2:3]
	v_and_b32_e32 v2, 56, v14
	v_mul_u32_u24_e32 v5, 0x84, v2
	v_lshlrev_b32_e32 v2, 1, v2
	v_lshl_add_u64 v[2:3], s[0:1], 0, v[2:3]
	s_mov_b64 s[10:11], 0xf80000
	v_lshl_add_u64 v[2:3], v[2:3], 0, s[10:11]
	s_lshl_b32 s3, s88, 4
	s_mov_b32 s10, 0
	v_lshlrev_b32_e32 v8, 2, v13
	s_add_i32 s3, s3, s10
	s_lshl_b32 s10, s88, 5
	s_mov_b32 s11, 0
	v_add_u32_e32 v6, v7, v6
	v_add3_u32 v5, s41, v5, v8
	s_lshl_b32 s14, s64, 7
	s_add_i32 s15, s10, s11
	s_lshl_b32 s16, s64, 8
	s_movk_i32 s17, 0x5800
	v_add_u32_e32 v7, 0x400, v6
	v_add_u32_e32 v8, 0x800, v6
	v_add_u32_e32 v9, 0xc00, v6
	v_add_u32_e32 v10, 0x1000, v6
	v_add_u32_e32 v11, 0x1400, v6
	v_add_u32_e32 v16, 0x1800, v6
	v_add_u32_e32 v17, 0x1c00, v6
	s_mov_b32 s28, s88

.LBB0_98:
	s_cmpk_lt_i32 s89, 0x580
	s_mov_b64 s[10:11], s[78:79]
	s_cselect_b64 s[16:17], -1, 0
	s_cmpk_gt_i32 s89, 0x57f
	s_cbranch_scc1 .LBB0_101
	s_load_dwordx2 s[10:11], s[10:11], 0xe8
	v_and_b32_e32 v2, 0x7c, v15
	v_mov_b32_e32 v3, 0
	v_add_u32_e32 v7, s41, v2
	v_mul_u32_u24_e32 v6, 0x84, v12
	s_waitcnt lgkmcnt(0)
	v_lshl_add_u64 v[0:1], s[10:11], 0, v[2:3]
	v_and_b32_e32 v2, 56, v14
	v_mul_u32_u24_e32 v5, 0x84, v2
	v_lshlrev_b32_e32 v2, 1, v2
	v_lshl_add_u64 v[2:3], s[0:1], 0, v[2:3]
	s_mov_b64 s[10:11], 0x1a80000
	v_lshl_add_u64 v[2:3], v[2:3], 0, s[10:11]
	v_lshlrev_b32_e32 v8, 2, v13
	s_lshl_b32 s3, s89, 5
	s_mov_b32 s10, 0
	v_add_u32_e32 v6, v7, v6
	v_add3_u32 v5, s41, v5, v8
	s_add_i32 s3, s3, s10
	s_lshl_b32 s28, s64, 8
	s_movk_i32 s29, 0x1600
	v_add_u32_e32 v7, 0x400, v6
	v_add_u32_e32 v8, 0x800, v6
	v_add_u32_e32 v9, 0xc00, v6
	v_add_u32_e32 v10, 0x1000, v6
	v_add_u32_e32 v11, 0x1400, v6
	v_add_u32_e32 v16, 0x1800, v6
	v_add_u32_e32 v17, 0x1c00, v6
	s_mov_b32 s30, s89

.LBB0_101:
	s_cmp_lt_i32 s90, 32
	s_mov_b64 s[10:11], s[78:79]
	s_cselect_b64 s[14:15], -1, 0
	s_cmp_gt_i32 s90, 31
	s_cbranch_scc1 .LBB0_104
	s_load_dwordx2 s[10:11], s[10:11], 0x88
	v_and_b32_e32 v2, 0x7c, v15
	v_mov_b32_e32 v3, 0
	v_add_u32_e32 v7, s41, v2
	v_mul_u32_u24_e32 v6, 0x84, v12
	s_waitcnt lgkmcnt(0)
	v_lshl_add_u64 v[0:1], s[10:11], 0, v[2:3]
	v_and_b32_e32 v2, 56, v14
	v_mul_u32_u24_e32 v5, 0x84, v2
	v_lshlrev_b32_e32 v2, 1, v2
	v_lshl_add_u64 v[2:3], s[0:1], 0, v[2:3]
	s_mov_b64 s[10:11], 0x2000000
	v_lshl_add_u64 v[2:3], v[2:3], 0, s[10:11]
	v_lshlrev_b32_e32 v8, 2, v13
	s_lshl_b32 s3, s90, 5
	s_mov_b32 s10, 0
	v_add_u32_e32 v6, v7, v6
	v_add3_u32 v5, s41, v5, v8
	s_add_i32 s3, s3, s10
	s_lshl_b32 s30, s64, 8
	v_add_u32_e32 v7, 0x400, v6
	v_add_u32_e32 v8, 0x800, v6
	v_add_u32_e32 v9, 0xc00, v6
	v_add_u32_e32 v10, 0x1000, v6
	v_add_u32_e32 v11, 0x1400, v6
	v_add_u32_e32 v16, 0x1800, v6
	v_add_u32_e32 v17, 0x1c00, v6
	s_mov_b32 s31, s90

.LBB0_754:
	s_or_b64 exec, exec, s[0:1]
	s_mov_b64 s[4:5], s[78:79]
	s_mov_b64 s[6:7], s[78:79]
	s_mov_b64 s[8:9], s[78:79]
	s_waitcnt vmcnt(11) lgkmcnt(0)
	v_mov_b32_e32 v0, v224
	s_movk_i32 s0, 0x40
	s_barrier
	s_nop 0
	v_cmp_gt_i32_e32 vcc, s0, v0
	s_and_saveexec_b64 s[0:1], vcc
	s_cbranch_execz .LBB0_760
	v_readlane_b32 s10, v252, 29
	s_nop 1
	v_add_u32_e32 v1, s10, v0
	v_cmp_gt_i32_e32 vcc, s89, v1
	s_and_b64 exec, exec, vcc
	s_cbranch_execz .LBB0_760
	s_load_dwordx2 s[4:5], s[78:79], 0x100
	v_and_b32_e32 v188, 15, v224
	v_bfe_u32 v189, v224, 4, 1
	v_bfe_u32 v190, v224, 5, 1
	s_and_b32 s6, s2, 7
	s_lshl_b32 s6, s6, 1
	s_lshr_b32 s7, s2, 3
	s_mul_i32 s7, s7, 72
	v_add_u32_e32 v190, s6, v190
	v_lshl_add_u32 v50, v190, 1, v189
	v_lshlrev_b32_e32 v50, 6, v50
	v_lshl_add_u32 v50, v188, 2, v50
	v_mul_u32_u24_e32 v50, 0x108, v50
	s_mul_i32 s10, s80, 0x1c4000
	s_waitcnt lgkmcnt(0)
	s_add_u32 s10, s4, s10
	s_addc_u32 s11, s5, 0
	s_add_u32 s10, s10, 0x6040100
	s_addc_u32 s11, s11, 0
	global_load_dwordx2 v[164:165], v50, s[10:11]
	global_load_dwordx2 v[166:167], v50, s[10:11] offset:264
	global_load_dwordx2 v[168:169], v50, s[10:11] offset:528
	global_load_dwordx2 v[170:171], v50, s[10:11] offset:792
	v_mul_u32_u24_e32 v190, 0x900, v190
	v_add_u32_e32 v190, s7, v190
	v_mul_u32_u24_e32 v160, 7, v189
	v_add_u32_e32 v190, v190, v160
	v_lshlrev_b32_e32 v50, 10, v190
	v_lshl_add_u32 v50, v189, 9, v50
	v_lshl_add_u32 v50, v188, 4, v50
	v_mul_u32_u24_e32 v51, 0x600, v190
	v_lshl_add_u32 v51, v189, 8, v51
	v_lshl_add_u32 v51, v188, 3, v51
	v_add_u32_e32 v51, 0x400, v51
	v_sub_u32_e32 v116, 0, v189
	v_lshlrev_b32_e32 v116, 1, v116
	v_add_u32_e32 v116, 1, v116
	v_mul_i32_i24_e32 v117, 0x600, v116
	v_lshlrev_b32_e32 v116, 10, v116
	v_mul_u32_u24_e32 v160, 0x12000, v189
	v_mul_u32_u24_e32 v162, 0x1b000, v189
	s_add_u32 s6, s4, 0x38f14000
	s_addc_u32 s7, s5, 0
	s_add_u32 s8, s4, 0x29314000
	s_addc_u32 s9, s5, 0
	global_load_dwordx4 v[0:3], v50, s[6:7]
	global_load_dwordx4 v[4:7], v50, s[6:7] offset:256
	v_add_u32_e32 v50, v50, v116
	global_load_dwordx4 v[8:11], v50, s[6:7]
	global_load_dwordx4 v[12:15], v50, s[6:7] offset:256
	v_add_u32_e32 v50, v50, v116
	global_load_dwordx4 v[16:19], v50, s[6:7]
	global_load_dwordx4 v[20:23], v50, s[6:7] offset:256
	v_add_u32_e32 v50, v50, v116
	global_load_dwordx4 v[24:27], v50, s[6:7]
	global_load_dwordx4 v[28:31], v50, s[6:7] offset:256
	v_add_u32_e32 v50, v50, v116
	global_load_dwordx4 v[32:35], v50, s[6:7]
	global_load_dwordx4 v[36:39], v50, s[6:7] offset:256
	v_add_u32_e32 v50, v50, v116
	global_load_dwordx4 v[40:43], v50, s[6:7]
	global_load_dwordx4 v[44:47], v50, s[6:7] offset:256
	v_add_u32_e32 v50, v50, v116
	global_load_dwordx4 v[52:55], v50, s[6:7]
	global_load_dwordx4 v[56:59], v50, s[6:7] offset:256
	v_add_u32_e32 v50, v50, v116
	global_load_dwordx4 v[60:63], v50, s[6:7]
	global_load_dwordx4 v[64:67], v50, s[6:7] offset:256
	v_add_u32_e32 v50, v50, v116
	v_add_u32_e32 v50, v50, v160
	global_load_dwordx4 v[68:71], v50, s[6:7]
	global_load_dwordx4 v[72:75], v50, s[6:7] offset:256
	v_add_u32_e32 v50, v50, v116
	global_load_dwordx4 v[76:79], v50, s[6:7]
	global_load_dwordx4 v[80:83], v50, s[6:7] offset:256
	v_add_u32_e32 v50, v50, v116
	s_waitcnt vmcnt(20)
	v_mov_b32_e32 v108, v164
	v_mov_b32_e32 v112, v165
	v_mov_b32_e32 v109, v166
	v_mov_b32_e32 v113, v167
	v_mov_b32_e32 v110, v168
	v_mov_b32_e32 v114, v169
	v_mov_b32_e32 v111, v170
	v_mov_b32_e32 v115, v171
	v_mov_b32_e32 v92, 0
	v_mov_b32_e32 v93, 0
	v_mov_b32_e32 v94, 0
	v_mov_b32_e32 v95, 0
	v_mov_b32_e32 v96, 0
	v_mov_b32_e32 v97, 0
	v_mov_b32_e32 v98, 0
	v_mov_b32_e32 v99, 0
	global_load_dwordx4 v[84:87], v50, s[6:7]
	global_load_dwordx4 v[88:91], v50, s[6:7] offset:256
	v_add_u32_e32 v50, v50, v116
	v_cvt_pk_bf16_f32 v180, v92, v93
	v_cvt_pk_bf16_f32 v181, v94, v95
	v_cvt_pk_bf16_f32 v182, v96, v97
	v_cvt_pk_bf16_f32 v183, v98, v99
	global_store_dwordx2 v51, v[180:181], s[8:9]
	global_store_dwordx2 v51, v[182:183], s[8:9] offset:128
	v_add_u32_e32 v51, v51, v117
	s_waitcnt vmcnt(22)
	v_pk_fma_f32 v[172:173], v[108:109], v[92:93], v[0:1]
	v_pk_fma_f32 v[176:177], v[108:109], v[96:97], v[4:5]
	v_pk_fma_f32 v[174:175], v[110:111], v[94:95], v[2:3]
	v_pk_fma_f32 v[178:179], v[110:111], v[98:99], v[6:7]
	v_pk_fma_f32 v[100:101], v[112:113], v[96:97], v[172:173] neg_lo:[1,0,0] neg_hi:[1,0,0]
	v_pk_fma_f32 v[104:105], v[112:113], v[92:93], v[176:177]
	v_pk_fma_f32 v[102:103], v[114:115], v[98:99], v[174:175] neg_lo:[1,0,0] neg_hi:[1,0,0]
	v_pk_fma_f32 v[106:107], v[114:115], v[94:95], v[178:179]
	global_load_dwordx4 v[0:3], v50, s[6:7]
	global_load_dwordx4 v[4:7], v50, s[6:7] offset:256
	v_add_u32_e32 v50, v50, v116
	v_cvt_pk_bf16_f32 v184, v100, v101
	v_cvt_pk_bf16_f32 v185, v102, v103
	v_cvt_pk_bf16_f32 v186, v104, v105
	v_cvt_pk_bf16_f32 v187, v106, v107
	global_store_dwordx2 v51, v[184:185], s[8:9]
	global_store_dwordx2 v51, v[186:187], s[8:9] offset:128
	v_add_u32_e32 v51, v51, v117
	s_waitcnt vmcnt(24)
	v_pk_fma_f32 v[172:173], v[108:109], v[100:101], v[8:9]
	v_pk_fma_f32 v[176:177], v[108:109], v[104:105], v[12:13]
	v_pk_fma_f32 v[174:175], v[110:111], v[102:103], v[10:11]
	v_pk_fma_f32 v[178:179], v[110:111], v[106:107], v[14:15]
	v_pk_fma_f32 v[92:93], v[112:113], v[104:105], v[172:173] neg_lo:[1,0,0] neg_hi:[1,0,0]
	v_pk_fma_f32 v[96:97], v[112:113], v[100:101], v[176:177]
	v_pk_fma_f32 v[94:95], v[114:115], v[106:107], v[174:175] neg_lo:[1,0,0] neg_hi:[1,0,0]
	v_pk_fma_f32 v[98:99], v[114:115], v[102:103], v[178:179]
	global_load_dwordx4 v[8:11], v50, s[6:7]
	global_load_dwordx4 v[12:15], v50, s[6:7] offset:256
	v_add_u32_e32 v50, v50, v116
	v_cvt_pk_bf16_f32 v180, v92, v93
	v_cvt_pk_bf16_f32 v181, v94, v95
	v_cvt_pk_bf16_f32 v182, v96, v97
	v_cvt_pk_bf16_f32 v183, v98, v99
	global_store_dwordx2 v51, v[180:181], s[8:9]
	global_store_dwordx2 v51, v[182:183], s[8:9] offset:128
	v_add_u32_e32 v51, v51, v117
	s_waitcnt vmcnt(26)
	v_pk_fma_f32 v[172:173], v[108:109], v[92:93], v[16:17]
	v_pk_fma_f32 v[176:177], v[108:109], v[96:97], v[20:21]
	v_pk_fma_f32 v[174:175], v[110:111], v[94:95], v[18:19]
	v_pk_fma_f32 v[178:179], v[110:111], v[98:99], v[22:23]
	v_pk_fma_f32 v[100:101], v[112:113], v[96:97], v[172:173] neg_lo:[1,0,0] neg_hi:[1,0,0]
	v_pk_fma_f32 v[104:105], v[112:113], v[92:93], v[176:177]
	v_pk_fma_f32 v[102:103], v[114:115], v[98:99], v[174:175] neg_lo:[1,0,0] neg_hi:[1,0,0]
	v_pk_fma_f32 v[106:107], v[114:115], v[94:95], v[178:179]
	global_load_dwordx4 v[16:19], v50, s[6:7]
	global_load_dwordx4 v[20:23], v50, s[6:7] offset:256
	v_add_u32_e32 v50, v50, v116
	v_cvt_pk_bf16_f32 v184, v100, v101
	v_cvt_pk_bf16_f32 v185, v102, v103
	v_cvt_pk_bf16_f32 v186, v104, v105
	v_cvt_pk_bf16_f32 v187, v106, v107
	global_store_dwordx2 v51, v[184:185], s[8:9]
	global_store_dwordx2 v51, v[186:187], s[8:9] offset:128
	v_add_u32_e32 v51, v51, v117
	s_waitcnt vmcnt(28)
	v_pk_fma_f32 v[172:173], v[108:109], v[100:101], v[24:25]
	v_pk_fma_f32 v[176:177], v[108:109], v[104:105], v[28:29]
	v_pk_fma_f32 v[174:175], v[110:111], v[102:103], v[26:27]
	v_pk_fma_f32 v[178:179], v[110:111], v[106:107], v[30:31]
	v_pk_fma_f32 v[92:93], v[112:113], v[104:105], v[172:173] neg_lo:[1,0,0] neg_hi:[1,0,0]
	v_pk_fma_f32 v[96:97], v[112:113], v[100:101], v[176:177]
	v_pk_fma_f32 v[94:95], v[114:115], v[106:107], v[174:175] neg_lo:[1,0,0] neg_hi:[1,0,0]
	v_pk_fma_f32 v[98:99], v[114:115], v[102:103], v[178:179]
	global_load_dwordx4 v[24:27], v50, s[6:7]
	global_load_dwordx4 v[28:31], v50, s[6:7] offset:256
	v_add_u32_e32 v50, v50, v116
	v_cvt_pk_bf16_f32 v180, v92, v93
	v_cvt_pk_bf16_f32 v181, v94, v95
	v_cvt_pk_bf16_f32 v182, v96, v97
	v_cvt_pk_bf16_f32 v183, v98, v99
	global_store_dwordx2 v51, v[180:181], s[8:9]
	global_store_dwordx2 v51, v[182:183], s[8:9] offset:128
	v_add_u32_e32 v51, v51, v117
	s_waitcnt vmcnt(30)
	v_pk_fma_f32 v[172:173], v[108:109], v[92:93], v[32:33]
	v_pk_fma_f32 v[176:177], v[108:109], v[96:97], v[36:37]
	v_pk_fma_f32 v[174:175], v[110:111], v[94:95], v[34:35]
	v_pk_fma_f32 v[178:179], v[110:111], v[98:99], v[38:39]
	v_pk_fma_f32 v[100:101], v[112:113], v[96:97], v[172:173] neg_lo:[1,0,0] neg_hi:[1,0,0]
	v_pk_fma_f32 v[104:105], v[112:113], v[92:93], v[176:177]
	v_pk_fma_f32 v[102:103], v[114:115], v[98:99], v[174:175] neg_lo:[1,0,0] neg_hi:[1,0,0]
	v_pk_fma_f32 v[106:107], v[114:115], v[94:95], v[178:179]
	global_load_dwordx4 v[32:35], v50, s[6:7]
	global_load_dwordx4 v[36:39], v50, s[6:7] offset:256
	v_add_u32_e32 v50, v50, v116
	v_cvt_pk_bf16_f32 v184, v100, v101
	v_cvt_pk_bf16_f32 v185, v102, v103
	v_cvt_pk_bf16_f32 v186, v104, v105
	v_cvt_pk_bf16_f32 v187, v106, v107
	global_store_dwordx2 v51, v[184:185], s[8:9]
	global_store_dwordx2 v51, v[186:187], s[8:9] offset:128
	v_add_u32_e32 v51, v51, v117
	s_waitcnt vmcnt(32)
	v_pk_fma_f32 v[172:173], v[108:109], v[100:101], v[40:41]
	v_pk_fma_f32 v[176:177], v[108:109], v[104:105], v[44:45]
	v_pk_fma_f32 v[174:175], v[110:111], v[102:103], v[42:43]
	v_pk_fma_f32 v[178:179], v[110:111], v[106:107], v[46:47]
	v_pk_fma_f32 v[92:93], v[112:113], v[104:105], v[172:173] neg_lo:[1,0,0] neg_hi:[1,0,0]
	v_pk_fma_f32 v[96:97], v[112:113], v[100:101], v[176:177]
	v_pk_fma_f32 v[94:95], v[114:115], v[106:107], v[174:175] neg_lo:[1,0,0] neg_hi:[1,0,0]
	v_pk_fma_f32 v[98:99], v[114:115], v[102:103], v[178:179]
	global_load_dwordx4 v[40:43], v50, s[6:7]
	global_load_dwordx4 v[44:47], v50, s[6:7] offset:256
	v_add_u32_e32 v50, v50, v116
	v_cvt_pk_bf16_f32 v180, v92, v93
	v_cvt_pk_bf16_f32 v181, v94, v95
	v_cvt_pk_bf16_f32 v182, v96, v97
	v_cvt_pk_bf16_f32 v183, v98, v99
	global_store_dwordx2 v51, v[180:181], s[8:9]
	global_store_dwordx2 v51, v[182:183], s[8:9] offset:128
	v_add_u32_e32 v51, v51, v117
	s_waitcnt vmcnt(34)
	v_pk_fma_f32 v[172:173], v[108:109], v[92:93], v[52:53]
	v_pk_fma_f32 v[176:177], v[108:109], v[96:97], v[56:57]
	v_pk_fma_f32 v[174:175], v[110:111], v[94:95], v[54:55]
	v_pk_fma_f32 v[178:179], v[110:111], v[98:99], v[58:59]
	v_pk_fma_f32 v[100:101], v[112:113], v[96:97], v[172:173] neg_lo:[1,0,0] neg_hi:[1,0,0]
	v_pk_fma_f32 v[104:105], v[112:113], v[92:93], v[176:177]
	v_pk_fma_f32 v[102:103], v[114:115], v[98:99], v[174:175] neg_lo:[1,0,0] neg_hi:[1,0,0]
	v_pk_fma_f32 v[106:107], v[114:115], v[94:95], v[178:179]
	global_load_dwordx4 v[52:55], v50, s[6:7]
	global_load_dwordx4 v[56:59], v50, s[6:7] offset:256
	v_add_u32_e32 v50, v50, v116
	v_cvt_pk_bf16_f32 v184, v100, v101
	v_cvt_pk_bf16_f32 v185, v102, v103
	v_cvt_pk_bf16_f32 v186, v104, v105
	v_cvt_pk_bf16_f32 v187, v106, v107
	global_store_dwordx2 v51, v[184:185], s[8:9]
	global_store_dwordx2 v51, v[186:187], s[8:9] offset:128
	v_add_u32_e32 v51, v51, v117
	s_waitcnt vmcnt(36)
	v_pk_fma_f32 v[172:173], v[108:109], v[100:101], v[60:61]
	v_pk_fma_f32 v[176:177], v[108:109], v[104:105], v[64:65]
	v_pk_fma_f32 v[174:175], v[110:111], v[102:103], v[62:63]
	v_pk_fma_f32 v[178:179], v[110:111], v[106:107], v[66:67]
	v_pk_fma_f32 v[92:93], v[112:113], v[104:105], v[172:173] neg_lo:[1,0,0] neg_hi:[1,0,0]
	v_pk_fma_f32 v[96:97], v[112:113], v[100:101], v[176:177]
	v_pk_fma_f32 v[94:95], v[114:115], v[106:107], v[174:175] neg_lo:[1,0,0] neg_hi:[1,0,0]
	v_pk_fma_f32 v[98:99], v[114:115], v[102:103], v[178:179]
	global_load_dwordx4 v[60:63], v50, s[6:7]
	global_load_dwordx4 v[64:67], v50, s[6:7] offset:256
	v_add_u32_e32 v50, v50, v116
	v_cvt_pk_bf16_f32 v180, v92, v93
	v_cvt_pk_bf16_f32 v181, v94, v95
	v_cvt_pk_bf16_f32 v182, v96, v97
	v_cvt_pk_bf16_f32 v183, v98, v99
	v_add_u32_e32 v51, v51, v162
	global_store_dwordx2 v51, v[180:181], s[8:9]
	global_store_dwordx2 v51, v[182:183], s[8:9] offset:128
	v_add_u32_e32 v51, v51, v117
	s_waitcnt vmcnt(38)
	v_pk_fma_f32 v[172:173], v[108:109], v[92:93], v[68:69]
	v_pk_fma_f32 v[176:177], v[108:109], v[96:97], v[72:73]
	v_pk_fma_f32 v[174:175], v[110:111], v[94:95], v[70:71]
	v_pk_fma_f32 v[178:179], v[110:111], v[98:99], v[74:75]
	v_pk_fma_f32 v[100:101], v[112:113], v[96:97], v[172:173] neg_lo:[1,0,0] neg_hi:[1,0,0]
	v_pk_fma_f32 v[104:105], v[112:113], v[92:93], v[176:177]
	v_pk_fma_f32 v[102:103], v[114:115], v[98:99], v[174:175] neg_lo:[1,0,0] neg_hi:[1,0,0]
	v_pk_fma_f32 v[106:107], v[114:115], v[94:95], v[178:179]
	global_load_dwordx4 v[68:71], v50, s[6:7]
	global_load_dwordx4 v[72:75], v50, s[6:7] offset:256
	v_add_u32_e32 v50, v50, v116
	v_cvt_pk_bf16_f32 v184, v100, v101
	v_cvt_pk_bf16_f32 v185, v102, v103
	v_cvt_pk_bf16_f32 v186, v104, v105
	v_cvt_pk_bf16_f32 v187, v106, v107
	global_store_dwordx2 v51, v[184:185], s[8:9]
	global_store_dwordx2 v51, v[186:187], s[8:9] offset:128
	v_add_u32_e32 v51, v51, v117
	s_waitcnt vmcnt(40)
	v_pk_fma_f32 v[172:173], v[108:109], v[100:101], v[76:77]
	v_pk_fma_f32 v[176:177], v[108:109], v[104:105], v[80:81]
	v_pk_fma_f32 v[174:175], v[110:111], v[102:103], v[78:79]
	v_pk_fma_f32 v[178:179], v[110:111], v[106:107], v[82:83]
	v_pk_fma_f32 v[92:93], v[112:113], v[104:105], v[172:173] neg_lo:[1,0,0] neg_hi:[1,0,0]
	v_pk_fma_f32 v[96:97], v[112:113], v[100:101], v[176:177]
	v_pk_fma_f32 v[94:95], v[114:115], v[106:107], v[174:175] neg_lo:[1,0,0] neg_hi:[1,0,0]
	v_pk_fma_f32 v[98:99], v[114:115], v[102:103], v[178:179]
	global_load_dwordx4 v[76:79], v50, s[6:7]
	global_load_dwordx4 v[80:83], v50, s[6:7] offset:256
	v_add_u32_e32 v50, v50, v116
	v_cvt_pk_bf16_f32 v180, v92, v93
	v_cvt_pk_bf16_f32 v181, v94, v95
	v_cvt_pk_bf16_f32 v182, v96, v97
	v_cvt_pk_bf16_f32 v183, v98, v99
	global_store_dwordx2 v51, v[180:181], s[8:9]
	global_store_dwordx2 v51, v[182:183], s[8:9] offset:128
	v_add_u32_e32 v51, v51, v117
	s_waitcnt vmcnt(42)
	v_pk_fma_f32 v[172:173], v[108:109], v[92:93], v[84:85]
	v_pk_fma_f32 v[176:177], v[108:109], v[96:97], v[88:89]
	v_pk_fma_f32 v[174:175], v[110:111], v[94:95], v[86:87]
	v_pk_fma_f32 v[178:179], v[110:111], v[98:99], v[90:91]
	v_pk_fma_f32 v[100:101], v[112:113], v[96:97], v[172:173] neg_lo:[1,0,0] neg_hi:[1,0,0]
	v_pk_fma_f32 v[104:105], v[112:113], v[92:93], v[176:177]
	v_pk_fma_f32 v[102:103], v[114:115], v[98:99], v[174:175] neg_lo:[1,0,0] neg_hi:[1,0,0]
	v_pk_fma_f32 v[106:107], v[114:115], v[94:95], v[178:179]
	global_load_dwordx4 v[84:87], v50, s[6:7]
	global_load_dwordx4 v[88:91], v50, s[6:7] offset:256
	v_add_u32_e32 v50, v50, v116
	v_cvt_pk_bf16_f32 v184, v100, v101
	v_cvt_pk_bf16_f32 v185, v102, v103
	v_cvt_pk_bf16_f32 v186, v104, v105
	v_cvt_pk_bf16_f32 v187, v106, v107
	global_store_dwordx2 v51, v[184:185], s[8:9]
	global_store_dwordx2 v51, v[186:187], s[8:9] offset:128
	v_add_u32_e32 v51, v51, v117
	s_waitcnt vmcnt(42)
	v_pk_fma_f32 v[172:173], v[108:109], v[100:101], v[0:1]
	v_pk_fma_f32 v[176:177], v[108:109], v[104:105], v[4:5]
	v_pk_fma_f32 v[174:175], v[110:111], v[102:103], v[2:3]
	v_pk_fma_f32 v[178:179], v[110:111], v[106:107], v[6:7]
	v_pk_fma_f32 v[92:93], v[112:113], v[104:105], v[172:173] neg_lo:[1,0,0] neg_hi:[1,0,0]
	v_pk_fma_f32 v[96:97], v[112:113], v[100:101], v[176:177]
	v_pk_fma_f32 v[94:95], v[114:115], v[106:107], v[174:175] neg_lo:[1,0,0] neg_hi:[1,0,0]
	v_pk_fma_f32 v[98:99], v[114:115], v[102:103], v[178:179]
	global_load_dwordx4 v[0:3], v50, s[6:7]
	global_load_dwordx4 v[4:7], v50, s[6:7] offset:256
	v_add_u32_e32 v50, v50, v116
	v_cvt_pk_bf16_f32 v180, v92, v93
	v_cvt_pk_bf16_f32 v181, v94, v95
	v_cvt_pk_bf16_f32 v182, v96, v97
	v_cvt_pk_bf16_f32 v183, v98, v99
	global_store_dwordx2 v51, v[180:181], s[8:9]
	global_store_dwordx2 v51, v[182:183], s[8:9] offset:128
	v_add_u32_e32 v51, v51, v117
	s_waitcnt vmcnt(42)
	v_pk_fma_f32 v[172:173], v[108:109], v[92:93], v[8:9]
	v_pk_fma_f32 v[176:177], v[108:109], v[96:97], v[12:13]
	v_pk_fma_f32 v[174:175], v[110:111], v[94:95], v[10:11]
	v_pk_fma_f32 v[178:179], v[110:111], v[98:99], v[14:15]
	v_pk_fma_f32 v[100:101], v[112:113], v[96:97], v[172:173] neg_lo:[1,0,0] neg_hi:[1,0,0]
	v_pk_fma_f32 v[104:105], v[112:113], v[92:93], v[176:177]
	v_pk_fma_f32 v[102:103], v[114:115], v[98:99], v[174:175] neg_lo:[1,0,0] neg_hi:[1,0,0]
	v_pk_fma_f32 v[106:107], v[114:115], v[94:95], v[178:179]
	global_load_dwordx4 v[8:11], v50, s[6:7]
	global_load_dwordx4 v[12:15], v50, s[6:7] offset:256
	v_add_u32_e32 v50, v50, v116
	v_cvt_pk_bf16_f32 v184, v100, v101
	v_cvt_pk_bf16_f32 v185, v102, v103
	v_cvt_pk_bf16_f32 v186, v104, v105
	v_cvt_pk_bf16_f32 v187, v106, v107
	global_store_dwordx2 v51, v[184:185], s[8:9]
	global_store_dwordx2 v51, v[186:187], s[8:9] offset:128
	v_add_u32_e32 v51, v51, v117
	s_waitcnt vmcnt(42)
	v_pk_fma_f32 v[172:173], v[108:109], v[100:101], v[16:17]
	v_pk_fma_f32 v[176:177], v[108:109], v[104:105], v[20:21]
	v_pk_fma_f32 v[174:175], v[110:111], v[102:103], v[18:19]
	v_pk_fma_f32 v[178:179], v[110:111], v[106:107], v[22:23]
	v_pk_fma_f32 v[92:93], v[112:113], v[104:105], v[172:173] neg_lo:[1,0,0] neg_hi:[1,0,0]
	v_pk_fma_f32 v[96:97], v[112:113], v[100:101], v[176:177]
	v_pk_fma_f32 v[94:95], v[114:115], v[106:107], v[174:175] neg_lo:[1,0,0] neg_hi:[1,0,0]
	v_pk_fma_f32 v[98:99], v[114:115], v[102:103], v[178:179]
	global_load_dwordx4 v[16:19], v50, s[6:7]
	global_load_dwordx4 v[20:23], v50, s[6:7] offset:256
	v_add_u32_e32 v50, v50, v116
	v_cvt_pk_bf16_f32 v180, v92, v93
	v_cvt_pk_bf16_f32 v181, v94, v95
	v_cvt_pk_bf16_f32 v182, v96, v97
	v_cvt_pk_bf16_f32 v183, v98, v99
	global_store_dwordx2 v51, v[180:181], s[8:9]
	global_store_dwordx2 v51, v[182:183], s[8:9] offset:128
	v_add_u32_e32 v51, v51, v117
	s_waitcnt vmcnt(42)
	v_pk_fma_f32 v[172:173], v[108:109], v[92:93], v[24:25]
	v_pk_fma_f32 v[176:177], v[108:109], v[96:97], v[28:29]
	v_pk_fma_f32 v[174:175], v[110:111], v[94:95], v[26:27]
	v_pk_fma_f32 v[178:179], v[110:111], v[98:99], v[30:31]
	v_pk_fma_f32 v[100:101], v[112:113], v[96:97], v[172:173] neg_lo:[1,0,0] neg_hi:[1,0,0]
	v_pk_fma_f32 v[104:105], v[112:113], v[92:93], v[176:177]
	v_pk_fma_f32 v[102:103], v[114:115], v[98:99], v[174:175] neg_lo:[1,0,0] neg_hi:[1,0,0]
	v_pk_fma_f32 v[106:107], v[114:115], v[94:95], v[178:179]
	global_load_dwordx4 v[24:27], v50, s[6:7]
	global_load_dwordx4 v[28:31], v50, s[6:7] offset:256
	v_add_u32_e32 v50, v50, v116
	v_cvt_pk_bf16_f32 v184, v100, v101
	v_cvt_pk_bf16_f32 v185, v102, v103
	v_cvt_pk_bf16_f32 v186, v104, v105
	v_cvt_pk_bf16_f32 v187, v106, v107
	global_store_dwordx2 v51, v[184:185], s[8:9]
	global_store_dwordx2 v51, v[186:187], s[8:9] offset:128
	v_add_u32_e32 v51, v51, v117
	s_waitcnt vmcnt(42)
	v_pk_fma_f32 v[172:173], v[108:109], v[100:101], v[32:33]
	v_pk_fma_f32 v[176:177], v[108:109], v[104:105], v[36:37]
	v_pk_fma_f32 v[174:175], v[110:111], v[102:103], v[34:35]
	v_pk_fma_f32 v[178:179], v[110:111], v[106:107], v[38:39]
	v_pk_fma_f32 v[92:93], v[112:113], v[104:105], v[172:173] neg_lo:[1,0,0] neg_hi:[1,0,0]
	v_pk_fma_f32 v[96:97], v[112:113], v[100:101], v[176:177]
	v_pk_fma_f32 v[94:95], v[114:115], v[106:107], v[174:175] neg_lo:[1,0,0] neg_hi:[1,0,0]
	v_pk_fma_f32 v[98:99], v[114:115], v[102:103], v[178:179]
	global_load_dwordx4 v[32:35], v50, s[6:7]
	global_load_dwordx4 v[36:39], v50, s[6:7] offset:256
	v_add_u32_e32 v50, v50, v116
	v_cvt_pk_bf16_f32 v180, v92, v93
	v_cvt_pk_bf16_f32 v181, v94, v95
	v_cvt_pk_bf16_f32 v182, v96, v97
	v_cvt_pk_bf16_f32 v183, v98, v99
	global_store_dwordx2 v51, v[180:181], s[8:9]
	global_store_dwordx2 v51, v[182:183], s[8:9] offset:128
	v_add_u32_e32 v51, v51, v117
	s_waitcnt vmcnt(42)
	v_pk_fma_f32 v[172:173], v[108:109], v[92:93], v[40:41]
	v_pk_fma_f32 v[176:177], v[108:109], v[96:97], v[44:45]
	v_pk_fma_f32 v[174:175], v[110:111], v[94:95], v[42:43]
	v_pk_fma_f32 v[178:179], v[110:111], v[98:99], v[46:47]
	v_pk_fma_f32 v[100:101], v[112:113], v[96:97], v[172:173] neg_lo:[1,0,0] neg_hi:[1,0,0]
	v_pk_fma_f32 v[104:105], v[112:113], v[92:93], v[176:177]
	v_pk_fma_f32 v[102:103], v[114:115], v[98:99], v[174:175] neg_lo:[1,0,0] neg_hi:[1,0,0]
	v_pk_fma_f32 v[106:107], v[114:115], v[94:95], v[178:179]
	global_load_dwordx4 v[40:43], v50, s[6:7]
	global_load_dwordx4 v[44:47], v50, s[6:7] offset:256
	v_add_u32_e32 v50, v50, v116
	v_cvt_pk_bf16_f32 v184, v100, v101
	v_cvt_pk_bf16_f32 v185, v102, v103
	v_cvt_pk_bf16_f32 v186, v104, v105
	v_cvt_pk_bf16_f32 v187, v106, v107
	global_store_dwordx2 v51, v[184:185], s[8:9]
	global_store_dwordx2 v51, v[186:187], s[8:9] offset:128
	v_add_u32_e32 v51, v51, v117
	s_waitcnt vmcnt(42)
	v_pk_fma_f32 v[172:173], v[108:109], v[100:101], v[52:53]
	v_pk_fma_f32 v[176:177], v[108:109], v[104:105], v[56:57]
	v_pk_fma_f32 v[174:175], v[110:111], v[102:103], v[54:55]
	v_pk_fma_f32 v[178:179], v[110:111], v[106:107], v[58:59]
	v_pk_fma_f32 v[92:93], v[112:113], v[104:105], v[172:173] neg_lo:[1,0,0] neg_hi:[1,0,0]
	v_pk_fma_f32 v[96:97], v[112:113], v[100:101], v[176:177]
	v_pk_fma_f32 v[94:95], v[114:115], v[106:107], v[174:175] neg_lo:[1,0,0] neg_hi:[1,0,0]
	v_pk_fma_f32 v[98:99], v[114:115], v[102:103], v[178:179]
	global_load_dwordx4 v[52:55], v50, s[6:7]
	global_load_dwordx4 v[56:59], v50, s[6:7] offset:256
	v_add_u32_e32 v50, v50, v116
	v_cvt_pk_bf16_f32 v180, v92, v93
	v_cvt_pk_bf16_f32 v181, v94, v95
	v_cvt_pk_bf16_f32 v182, v96, v97
	v_cvt_pk_bf16_f32 v183, v98, v99
	global_store_dwordx2 v51, v[180:181], s[8:9]
	global_store_dwordx2 v51, v[182:183], s[8:9] offset:128
	v_add_u32_e32 v51, v51, v117
	s_waitcnt vmcnt(42)
	v_pk_fma_f32 v[172:173], v[108:109], v[92:93], v[60:61]
	v_pk_fma_f32 v[176:177], v[108:109], v[96:97], v[64:65]
	v_pk_fma_f32 v[174:175], v[110:111], v[94:95], v[62:63]
	v_pk_fma_f32 v[178:179], v[110:111], v[98:99], v[66:67]
	v_pk_fma_f32 v[100:101], v[112:113], v[96:97], v[172:173] neg_lo:[1,0,0] neg_hi:[1,0,0]
	v_pk_fma_f32 v[104:105], v[112:113], v[92:93], v[176:177]
	v_pk_fma_f32 v[102:103], v[114:115], v[98:99], v[174:175] neg_lo:[1,0,0] neg_hi:[1,0,0]
	v_pk_fma_f32 v[106:107], v[114:115], v[94:95], v[178:179]
	global_load_dwordx4 v[60:63], v50, s[6:7]
	global_load_dwordx4 v[64:67], v50, s[6:7] offset:256
	v_add_u32_e32 v50, v50, v116
	v_cvt_pk_bf16_f32 v184, v100, v101
	v_cvt_pk_bf16_f32 v185, v102, v103
	v_cvt_pk_bf16_f32 v186, v104, v105
	v_cvt_pk_bf16_f32 v187, v106, v107
	global_store_dwordx2 v51, v[184:185], s[8:9]
	global_store_dwordx2 v51, v[186:187], s[8:9] offset:128
	v_add_u32_e32 v51, v51, v117
	s_waitcnt vmcnt(42)
	v_pk_fma_f32 v[172:173], v[108:109], v[100:101], v[68:69]
	v_pk_fma_f32 v[176:177], v[108:109], v[104:105], v[72:73]
	v_pk_fma_f32 v[174:175], v[110:111], v[102:103], v[70:71]
	v_pk_fma_f32 v[178:179], v[110:111], v[106:107], v[74:75]
	v_pk_fma_f32 v[92:93], v[112:113], v[104:105], v[172:173] neg_lo:[1,0,0] neg_hi:[1,0,0]
	v_pk_fma_f32 v[96:97], v[112:113], v[100:101], v[176:177]
	v_pk_fma_f32 v[94:95], v[114:115], v[106:107], v[174:175] neg_lo:[1,0,0] neg_hi:[1,0,0]
	v_pk_fma_f32 v[98:99], v[114:115], v[102:103], v[178:179]
	global_load_dwordx4 v[68:71], v50, s[6:7]
	global_load_dwordx4 v[72:75], v50, s[6:7] offset:256
	v_add_u32_e32 v50, v50, v116
	v_cvt_pk_bf16_f32 v180, v92, v93
	v_cvt_pk_bf16_f32 v181, v94, v95
	v_cvt_pk_bf16_f32 v182, v96, v97
	v_cvt_pk_bf16_f32 v183, v98, v99
	global_store_dwordx2 v51, v[180:181], s[8:9]
	global_store_dwordx2 v51, v[182:183], s[8:9] offset:128
	v_add_u32_e32 v51, v51, v117
	s_waitcnt vmcnt(42)
	v_pk_fma_f32 v[172:173], v[108:109], v[92:93], v[76:77]
	v_pk_fma_f32 v[176:177], v[108:109], v[96:97], v[80:81]
	v_pk_fma_f32 v[174:175], v[110:111], v[94:95], v[78:79]
	v_pk_fma_f32 v[178:179], v[110:111], v[98:99], v[82:83]
	v_pk_fma_f32 v[100:101], v[112:113], v[96:97], v[172:173] neg_lo:[1,0,0] neg_hi:[1,0,0]
	v_pk_fma_f32 v[104:105], v[112:113], v[92:93], v[176:177]
	v_pk_fma_f32 v[102:103], v[114:115], v[98:99], v[174:175] neg_lo:[1,0,0] neg_hi:[1,0,0]
	v_pk_fma_f32 v[106:107], v[114:115], v[94:95], v[178:179]
	global_load_dwordx4 v[76:79], v50, s[6:7]
	global_load_dwordx4 v[80:83], v50, s[6:7] offset:256
	v_add_u32_e32 v50, v50, v116
	v_cvt_pk_bf16_f32 v184, v100, v101
	v_cvt_pk_bf16_f32 v185, v102, v103
	v_cvt_pk_bf16_f32 v186, v104, v105
	v_cvt_pk_bf16_f32 v187, v106, v107
	global_store_dwordx2 v51, v[184:185], s[8:9]
	global_store_dwordx2 v51, v[186:187], s[8:9] offset:128
	v_add_u32_e32 v51, v51, v117
	s_waitcnt vmcnt(42)
	v_pk_fma_f32 v[172:173], v[108:109], v[100:101], v[84:85]
	v_pk_fma_f32 v[176:177], v[108:109], v[104:105], v[88:89]
	v_pk_fma_f32 v[174:175], v[110:111], v[102:103], v[86:87]
	v_pk_fma_f32 v[178:179], v[110:111], v[106:107], v[90:91]
	v_pk_fma_f32 v[92:93], v[112:113], v[104:105], v[172:173] neg_lo:[1,0,0] neg_hi:[1,0,0]
	v_pk_fma_f32 v[96:97], v[112:113], v[100:101], v[176:177]
	v_pk_fma_f32 v[94:95], v[114:115], v[106:107], v[174:175] neg_lo:[1,0,0] neg_hi:[1,0,0]
	v_pk_fma_f32 v[98:99], v[114:115], v[102:103], v[178:179]
	global_load_dwordx4 v[84:87], v50, s[6:7]
	global_load_dwordx4 v[88:91], v50, s[6:7] offset:256
	v_add_u32_e32 v50, v50, v116
	v_cvt_pk_bf16_f32 v180, v92, v93
	v_cvt_pk_bf16_f32 v181, v94, v95
	v_cvt_pk_bf16_f32 v182, v96, v97
	v_cvt_pk_bf16_f32 v183, v98, v99
	global_store_dwordx2 v51, v[180:181], s[8:9]
	global_store_dwordx2 v51, v[182:183], s[8:9] offset:128
	v_add_u32_e32 v51, v51, v117
	s_waitcnt vmcnt(42)
	v_pk_fma_f32 v[172:173], v[108:109], v[92:93], v[0:1]
	v_pk_fma_f32 v[176:177], v[108:109], v[96:97], v[4:5]
	v_pk_fma_f32 v[174:175], v[110:111], v[94:95], v[2:3]
	v_pk_fma_f32 v[178:179], v[110:111], v[98:99], v[6:7]
	v_pk_fma_f32 v[100:101], v[112:113], v[96:97], v[172:173] neg_lo:[1,0,0] neg_hi:[1,0,0]
	v_pk_fma_f32 v[104:105], v[112:113], v[92:93], v[176:177]
	v_pk_fma_f32 v[102:103], v[114:115], v[98:99], v[174:175] neg_lo:[1,0,0] neg_hi:[1,0,0]
	v_pk_fma_f32 v[106:107], v[114:115], v[94:95], v[178:179]
	global_load_dwordx4 v[0:3], v50, s[6:7]
	global_load_dwordx4 v[4:7], v50, s[6:7] offset:256
	v_add_u32_e32 v50, v50, v116
	v_cvt_pk_bf16_f32 v184, v100, v101
	v_cvt_pk_bf16_f32 v185, v102, v103
	v_cvt_pk_bf16_f32 v186, v104, v105
	v_cvt_pk_bf16_f32 v187, v106, v107
	global_store_dwordx2 v51, v[184:185], s[8:9]
	global_store_dwordx2 v51, v[186:187], s[8:9] offset:128
	v_add_u32_e32 v51, v51, v117
	s_waitcnt vmcnt(42)
	v_pk_fma_f32 v[172:173], v[108:109], v[100:101], v[8:9]
	v_pk_fma_f32 v[176:177], v[108:109], v[104:105], v[12:13]
	v_pk_fma_f32 v[174:175], v[110:111], v[102:103], v[10:11]
	v_pk_fma_f32 v[178:179], v[110:111], v[106:107], v[14:15]
	v_pk_fma_f32 v[92:93], v[112:113], v[104:105], v[172:173] neg_lo:[1,0,0] neg_hi:[1,0,0]
	v_pk_fma_f32 v[96:97], v[112:113], v[100:101], v[176:177]
	v_pk_fma_f32 v[94:95], v[114:115], v[106:107], v[174:175] neg_lo:[1,0,0] neg_hi:[1,0,0]
	v_pk_fma_f32 v[98:99], v[114:115], v[102:103], v[178:179]
	global_load_dwordx4 v[8:11], v50, s[6:7]
	global_load_dwordx4 v[12:15], v50, s[6:7] offset:256
	v_add_u32_e32 v50, v50, v116
	v_cvt_pk_bf16_f32 v180, v92, v93
	v_cvt_pk_bf16_f32 v181, v94, v95
	v_cvt_pk_bf16_f32 v182, v96, v97
	v_cvt_pk_bf16_f32 v183, v98, v99
	global_store_dwordx2 v51, v[180:181], s[8:9]
	global_store_dwordx2 v51, v[182:183], s[8:9] offset:128
	v_add_u32_e32 v51, v51, v117
	s_waitcnt vmcnt(42)
	v_pk_fma_f32 v[172:173], v[108:109], v[92:93], v[16:17]
	v_pk_fma_f32 v[176:177], v[108:109], v[96:97], v[20:21]
	v_pk_fma_f32 v[174:175], v[110:111], v[94:95], v[18:19]
	v_pk_fma_f32 v[178:179], v[110:111], v[98:99], v[22:23]
	v_pk_fma_f32 v[100:101], v[112:113], v[96:97], v[172:173] neg_lo:[1,0,0] neg_hi:[1,0,0]
	v_pk_fma_f32 v[104:105], v[112:113], v[92:93], v[176:177]
	v_pk_fma_f32 v[102:103], v[114:115], v[98:99], v[174:175] neg_lo:[1,0,0] neg_hi:[1,0,0]
	v_pk_fma_f32 v[106:107], v[114:115], v[94:95], v[178:179]
	global_load_dwordx4 v[16:19], v50, s[6:7]
	global_load_dwordx4 v[20:23], v50, s[6:7] offset:256
	v_add_u32_e32 v50, v50, v116
	v_cvt_pk_bf16_f32 v184, v100, v101
	v_cvt_pk_bf16_f32 v185, v102, v103
	v_cvt_pk_bf16_f32 v186, v104, v105
	v_cvt_pk_bf16_f32 v187, v106, v107
	global_store_dwordx2 v51, v[184:185], s[8:9]
	global_store_dwordx2 v51, v[186:187], s[8:9] offset:128
	v_add_u32_e32 v51, v51, v117
	s_waitcnt vmcnt(42)
	v_pk_fma_f32 v[172:173], v[108:109], v[100:101], v[24:25]
	v_pk_fma_f32 v[176:177], v[108:109], v[104:105], v[28:29]
	v_pk_fma_f32 v[174:175], v[110:111], v[102:103], v[26:27]
	v_pk_fma_f32 v[178:179], v[110:111], v[106:107], v[30:31]
	v_pk_fma_f32 v[92:93], v[112:113], v[104:105], v[172:173] neg_lo:[1,0,0] neg_hi:[1,0,0]
	v_pk_fma_f32 v[96:97], v[112:113], v[100:101], v[176:177]
	v_pk_fma_f32 v[94:95], v[114:115], v[106:107], v[174:175] neg_lo:[1,0,0] neg_hi:[1,0,0]
	v_pk_fma_f32 v[98:99], v[114:115], v[102:103], v[178:179]
	global_load_dwordx4 v[24:27], v50, s[6:7]
	global_load_dwordx4 v[28:31], v50, s[6:7] offset:256
	v_add_u32_e32 v50, v50, v116
	v_cvt_pk_bf16_f32 v180, v92, v93
	v_cvt_pk_bf16_f32 v181, v94, v95
	v_cvt_pk_bf16_f32 v182, v96, v97
	v_cvt_pk_bf16_f32 v183, v98, v99
	global_store_dwordx2 v51, v[180:181], s[8:9]
	global_store_dwordx2 v51, v[182:183], s[8:9] offset:128
	v_add_u32_e32 v51, v51, v117
	s_waitcnt vmcnt(42)
	v_pk_fma_f32 v[172:173], v[108:109], v[92:93], v[32:33]
	v_pk_fma_f32 v[176:177], v[108:109], v[96:97], v[36:37]
	v_pk_fma_f32 v[174:175], v[110:111], v[94:95], v[34:35]
	v_pk_fma_f32 v[178:179], v[110:111], v[98:99], v[38:39]
	v_pk_fma_f32 v[100:101], v[112:113], v[96:97], v[172:173] neg_lo:[1,0,0] neg_hi:[1,0,0]
	v_pk_fma_f32 v[104:105], v[112:113], v[92:93], v[176:177]
	v_pk_fma_f32 v[102:103], v[114:115], v[98:99], v[174:175] neg_lo:[1,0,0] neg_hi:[1,0,0]
	v_pk_fma_f32 v[106:107], v[114:115], v[94:95], v[178:179]
	global_load_dwordx4 v[32:35], v50, s[6:7]
	global_load_dwordx4 v[36:39], v50, s[6:7] offset:256
	v_add_u32_e32 v50, v50, v116
	v_cvt_pk_bf16_f32 v184, v100, v101
	v_cvt_pk_bf16_f32 v185, v102, v103
	v_cvt_pk_bf16_f32 v186, v104, v105
	v_cvt_pk_bf16_f32 v187, v106, v107
	global_store_dwordx2 v51, v[184:185], s[8:9]
	global_store_dwordx2 v51, v[186:187], s[8:9] offset:128
	v_add_u32_e32 v51, v51, v117
	s_waitcnt vmcnt(42)
	v_pk_fma_f32 v[172:173], v[108:109], v[100:101], v[40:41]
	v_pk_fma_f32 v[176:177], v[108:109], v[104:105], v[44:45]
	v_pk_fma_f32 v[174:175], v[110:111], v[102:103], v[42:43]
	v_pk_fma_f32 v[178:179], v[110:111], v[106:107], v[46:47]
	v_pk_fma_f32 v[92:93], v[112:113], v[104:105], v[172:173] neg_lo:[1,0,0] neg_hi:[1,0,0]
	v_pk_fma_f32 v[96:97], v[112:113], v[100:101], v[176:177]
	v_pk_fma_f32 v[94:95], v[114:115], v[106:107], v[174:175] neg_lo:[1,0,0] neg_hi:[1,0,0]
	v_pk_fma_f32 v[98:99], v[114:115], v[102:103], v[178:179]
	global_load_dwordx4 v[40:43], v50, s[6:7]
	global_load_dwordx4 v[44:47], v50, s[6:7] offset:256
	v_add_u32_e32 v50, v50, v116
	v_cvt_pk_bf16_f32 v180, v92, v93
	v_cvt_pk_bf16_f32 v181, v94, v95
	v_cvt_pk_bf16_f32 v182, v96, v97
	v_cvt_pk_bf16_f32 v183, v98, v99
	global_store_dwordx2 v51, v[180:181], s[8:9]
	global_store_dwordx2 v51, v[182:183], s[8:9] offset:128
	v_add_u32_e32 v51, v51, v117
	s_waitcnt vmcnt(42)
	v_pk_fma_f32 v[172:173], v[108:109], v[92:93], v[52:53]
	v_pk_fma_f32 v[176:177], v[108:109], v[96:97], v[56:57]
	v_pk_fma_f32 v[174:175], v[110:111], v[94:95], v[54:55]
	v_pk_fma_f32 v[178:179], v[110:111], v[98:99], v[58:59]
	v_pk_fma_f32 v[100:101], v[112:113], v[96:97], v[172:173] neg_lo:[1,0,0] neg_hi:[1,0,0]
	v_pk_fma_f32 v[104:105], v[112:113], v[92:93], v[176:177]
	v_pk_fma_f32 v[102:103], v[114:115], v[98:99], v[174:175] neg_lo:[1,0,0] neg_hi:[1,0,0]
	v_pk_fma_f32 v[106:107], v[114:115], v[94:95], v[178:179]
	global_load_dwordx4 v[52:55], v50, s[6:7]
	global_load_dwordx4 v[56:59], v50, s[6:7] offset:256
	v_add_u32_e32 v50, v50, v116
	v_cvt_pk_bf16_f32 v184, v100, v101
	v_cvt_pk_bf16_f32 v185, v102, v103
	v_cvt_pk_bf16_f32 v186, v104, v105
	v_cvt_pk_bf16_f32 v187, v106, v107
	global_store_dwordx2 v51, v[184:185], s[8:9]
	global_store_dwordx2 v51, v[186:187], s[8:9] offset:128
	v_add_u32_e32 v51, v51, v117
	s_waitcnt vmcnt(42)
	v_pk_fma_f32 v[172:173], v[108:109], v[100:101], v[60:61]
	v_pk_fma_f32 v[176:177], v[108:109], v[104:105], v[64:65]
	v_pk_fma_f32 v[174:175], v[110:111], v[102:103], v[62:63]
	v_pk_fma_f32 v[178:179], v[110:111], v[106:107], v[66:67]
	v_pk_fma_f32 v[92:93], v[112:113], v[104:105], v[172:173] neg_lo:[1,0,0] neg_hi:[1,0,0]
	v_pk_fma_f32 v[96:97], v[112:113], v[100:101], v[176:177]
	v_pk_fma_f32 v[94:95], v[114:115], v[106:107], v[174:175] neg_lo:[1,0,0] neg_hi:[1,0,0]
	v_pk_fma_f32 v[98:99], v[114:115], v[102:103], v[178:179]
	global_load_dwordx4 v[60:63], v50, s[6:7]
	global_load_dwordx4 v[64:67], v50, s[6:7] offset:256
	v_add_u32_e32 v50, v50, v116
	v_cvt_pk_bf16_f32 v180, v92, v93
	v_cvt_pk_bf16_f32 v181, v94, v95
	v_cvt_pk_bf16_f32 v182, v96, v97
	v_cvt_pk_bf16_f32 v183, v98, v99
	global_store_dwordx2 v51, v[180:181], s[8:9]
	global_store_dwordx2 v51, v[182:183], s[8:9] offset:128
	v_add_u32_e32 v51, v51, v117
	s_waitcnt vmcnt(42)
	v_pk_fma_f32 v[172:173], v[108:109], v[92:93], v[68:69]
	v_pk_fma_f32 v[176:177], v[108:109], v[96:97], v[72:73]
	v_pk_fma_f32 v[174:175], v[110:111], v[94:95], v[70:71]
	v_pk_fma_f32 v[178:179], v[110:111], v[98:99], v[74:75]
	v_pk_fma_f32 v[100:101], v[112:113], v[96:97], v[172:173] neg_lo:[1,0,0] neg_hi:[1,0,0]
	v_pk_fma_f32 v[104:105], v[112:113], v[92:93], v[176:177]
	v_pk_fma_f32 v[102:103], v[114:115], v[98:99], v[174:175] neg_lo:[1,0,0] neg_hi:[1,0,0]
	v_pk_fma_f32 v[106:107], v[114:115], v[94:95], v[178:179]
	global_load_dwordx4 v[68:71], v50, s[6:7]
	global_load_dwordx4 v[72:75], v50, s[6:7] offset:256
	v_add_u32_e32 v50, v50, v116
	v_cvt_pk_bf16_f32 v184, v100, v101
	v_cvt_pk_bf16_f32 v185, v102, v103
	v_cvt_pk_bf16_f32 v186, v104, v105
	v_cvt_pk_bf16_f32 v187, v106, v107
	global_store_dwordx2 v51, v[184:185], s[8:9]
	global_store_dwordx2 v51, v[186:187], s[8:9] offset:128
	v_add_u32_e32 v51, v51, v117
	s_waitcnt vmcnt(42)
	v_pk_fma_f32 v[172:173], v[108:109], v[100:101], v[76:77]
	v_pk_fma_f32 v[176:177], v[108:109], v[104:105], v[80:81]
	v_pk_fma_f32 v[174:175], v[110:111], v[102:103], v[78:79]
	v_pk_fma_f32 v[178:179], v[110:111], v[106:107], v[82:83]
	v_pk_fma_f32 v[92:93], v[112:113], v[104:105], v[172:173] neg_lo:[1,0,0] neg_hi:[1,0,0]
	v_pk_fma_f32 v[96:97], v[112:113], v[100:101], v[176:177]
	v_pk_fma_f32 v[94:95], v[114:115], v[106:107], v[174:175] neg_lo:[1,0,0] neg_hi:[1,0,0]
	v_pk_fma_f32 v[98:99], v[114:115], v[102:103], v[178:179]
	global_load_dwordx4 v[76:79], v50, s[6:7]
	global_load_dwordx4 v[80:83], v50, s[6:7] offset:256
	v_add_u32_e32 v50, v50, v116
	v_cvt_pk_bf16_f32 v180, v92, v93
	v_cvt_pk_bf16_f32 v181, v94, v95
	v_cvt_pk_bf16_f32 v182, v96, v97
	v_cvt_pk_bf16_f32 v183, v98, v99
	global_store_dwordx2 v51, v[180:181], s[8:9]
	global_store_dwordx2 v51, v[182:183], s[8:9] offset:128
	v_add_u32_e32 v51, v51, v117
	s_waitcnt vmcnt(42)
	v_pk_fma_f32 v[172:173], v[108:109], v[92:93], v[84:85]
	v_pk_fma_f32 v[176:177], v[108:109], v[96:97], v[88:89]
	v_pk_fma_f32 v[174:175], v[110:111], v[94:95], v[86:87]
	v_pk_fma_f32 v[178:179], v[110:111], v[98:99], v[90:91]
	v_pk_fma_f32 v[100:101], v[112:113], v[96:97], v[172:173] neg_lo:[1,0,0] neg_hi:[1,0,0]
	v_pk_fma_f32 v[104:105], v[112:113], v[92:93], v[176:177]
	v_pk_fma_f32 v[102:103], v[114:115], v[98:99], v[174:175] neg_lo:[1,0,0] neg_hi:[1,0,0]
	v_pk_fma_f32 v[106:107], v[114:115], v[94:95], v[178:179]
	global_load_dwordx4 v[84:87], v50, s[6:7]
	global_load_dwordx4 v[88:91], v50, s[6:7] offset:256
	v_add_u32_e32 v50, v50, v116
	v_cvt_pk_bf16_f32 v184, v100, v101
	v_cvt_pk_bf16_f32 v185, v102, v103
	v_cvt_pk_bf16_f32 v186, v104, v105
	v_cvt_pk_bf16_f32 v187, v106, v107
	global_store_dwordx2 v51, v[184:185], s[8:9]
	global_store_dwordx2 v51, v[186:187], s[8:9] offset:128
	v_add_u32_e32 v51, v51, v117
	s_waitcnt vmcnt(42)
	v_pk_fma_f32 v[172:173], v[108:109], v[100:101], v[0:1]
	v_pk_fma_f32 v[176:177], v[108:109], v[104:105], v[4:5]
	v_pk_fma_f32 v[174:175], v[110:111], v[102:103], v[2:3]
	v_pk_fma_f32 v[178:179], v[110:111], v[106:107], v[6:7]
	v_pk_fma_f32 v[92:93], v[112:113], v[104:105], v[172:173] neg_lo:[1,0,0] neg_hi:[1,0,0]
	v_pk_fma_f32 v[96:97], v[112:113], v[100:101], v[176:177]
	v_pk_fma_f32 v[94:95], v[114:115], v[106:107], v[174:175] neg_lo:[1,0,0] neg_hi:[1,0,0]
	v_pk_fma_f32 v[98:99], v[114:115], v[102:103], v[178:179]
	global_load_dwordx4 v[0:3], v50, s[6:7]
	global_load_dwordx4 v[4:7], v50, s[6:7] offset:256
	v_add_u32_e32 v50, v50, v116
	v_cvt_pk_bf16_f32 v180, v92, v93
	v_cvt_pk_bf16_f32 v181, v94, v95
	v_cvt_pk_bf16_f32 v182, v96, v97
	v_cvt_pk_bf16_f32 v183, v98, v99
	global_store_dwordx2 v51, v[180:181], s[8:9]
	global_store_dwordx2 v51, v[182:183], s[8:9] offset:128
	v_add_u32_e32 v51, v51, v117
	s_waitcnt vmcnt(42)
	v_pk_fma_f32 v[172:173], v[108:109], v[92:93], v[8:9]
	v_pk_fma_f32 v[176:177], v[108:109], v[96:97], v[12:13]
	v_pk_fma_f32 v[174:175], v[110:111], v[94:95], v[10:11]
	v_pk_fma_f32 v[178:179], v[110:111], v[98:99], v[14:15]
	v_pk_fma_f32 v[100:101], v[112:113], v[96:97], v[172:173] neg_lo:[1,0,0] neg_hi:[1,0,0]
	v_pk_fma_f32 v[104:105], v[112:113], v[92:93], v[176:177]
	v_pk_fma_f32 v[102:103], v[114:115], v[98:99], v[174:175] neg_lo:[1,0,0] neg_hi:[1,0,0]
	v_pk_fma_f32 v[106:107], v[114:115], v[94:95], v[178:179]
	global_load_dwordx4 v[8:11], v50, s[6:7]
	global_load_dwordx4 v[12:15], v50, s[6:7] offset:256
	v_add_u32_e32 v50, v50, v116
	v_cvt_pk_bf16_f32 v184, v100, v101
	v_cvt_pk_bf16_f32 v185, v102, v103
	v_cvt_pk_bf16_f32 v186, v104, v105
	v_cvt_pk_bf16_f32 v187, v106, v107
	global_store_dwordx2 v51, v[184:185], s[8:9]
	global_store_dwordx2 v51, v[186:187], s[8:9] offset:128
	v_add_u32_e32 v51, v51, v117
	s_waitcnt vmcnt(42)
	v_pk_fma_f32 v[172:173], v[108:109], v[100:101], v[16:17]
	v_pk_fma_f32 v[176:177], v[108:109], v[104:105], v[20:21]
	v_pk_fma_f32 v[174:175], v[110:111], v[102:103], v[18:19]
	v_pk_fma_f32 v[178:179], v[110:111], v[106:107], v[22:23]
	v_pk_fma_f32 v[92:93], v[112:113], v[104:105], v[172:173] neg_lo:[1,0,0] neg_hi:[1,0,0]
	v_pk_fma_f32 v[96:97], v[112:113], v[100:101], v[176:177]
	v_pk_fma_f32 v[94:95], v[114:115], v[106:107], v[174:175] neg_lo:[1,0,0] neg_hi:[1,0,0]
	v_pk_fma_f32 v[98:99], v[114:115], v[102:103], v[178:179]
	global_load_dwordx4 v[16:19], v50, s[6:7]
	global_load_dwordx4 v[20:23], v50, s[6:7] offset:256
	v_add_u32_e32 v50, v50, v116
	v_cvt_pk_bf16_f32 v180, v92, v93
	v_cvt_pk_bf16_f32 v181, v94, v95
	v_cvt_pk_bf16_f32 v182, v96, v97
	v_cvt_pk_bf16_f32 v183, v98, v99
	global_store_dwordx2 v51, v[180:181], s[8:9]
	global_store_dwordx2 v51, v[182:183], s[8:9] offset:128
	v_add_u32_e32 v51, v51, v117
	s_waitcnt vmcnt(42)
	v_pk_fma_f32 v[172:173], v[108:109], v[92:93], v[24:25]
	v_pk_fma_f32 v[176:177], v[108:109], v[96:97], v[28:29]
	v_pk_fma_f32 v[174:175], v[110:111], v[94:95], v[26:27]
	v_pk_fma_f32 v[178:179], v[110:111], v[98:99], v[30:31]
	v_pk_fma_f32 v[100:101], v[112:113], v[96:97], v[172:173] neg_lo:[1,0,0] neg_hi:[1,0,0]
	v_pk_fma_f32 v[104:105], v[112:113], v[92:93], v[176:177]
	v_pk_fma_f32 v[102:103], v[114:115], v[98:99], v[174:175] neg_lo:[1,0,0] neg_hi:[1,0,0]
	v_pk_fma_f32 v[106:107], v[114:115], v[94:95], v[178:179]
	global_load_dwordx4 v[24:27], v50, s[6:7]
	global_load_dwordx4 v[28:31], v50, s[6:7] offset:256
	v_add_u32_e32 v50, v50, v116
	v_cvt_pk_bf16_f32 v184, v100, v101
	v_cvt_pk_bf16_f32 v185, v102, v103
	v_cvt_pk_bf16_f32 v186, v104, v105
	v_cvt_pk_bf16_f32 v187, v106, v107
	global_store_dwordx2 v51, v[184:185], s[8:9]
	global_store_dwordx2 v51, v[186:187], s[8:9] offset:128
	v_add_u32_e32 v51, v51, v117
	s_waitcnt vmcnt(42)
	v_pk_fma_f32 v[172:173], v[108:109], v[100:101], v[32:33]
	v_pk_fma_f32 v[176:177], v[108:109], v[104:105], v[36:37]
	v_pk_fma_f32 v[174:175], v[110:111], v[102:103], v[34:35]
	v_pk_fma_f32 v[178:179], v[110:111], v[106:107], v[38:39]
	v_pk_fma_f32 v[92:93], v[112:113], v[104:105], v[172:173] neg_lo:[1,0,0] neg_hi:[1,0,0]
	v_pk_fma_f32 v[96:97], v[112:113], v[100:101], v[176:177]
	v_pk_fma_f32 v[94:95], v[114:115], v[106:107], v[174:175] neg_lo:[1,0,0] neg_hi:[1,0,0]
	v_pk_fma_f32 v[98:99], v[114:115], v[102:103], v[178:179]
	global_load_dwordx4 v[32:35], v50, s[6:7]
	global_load_dwordx4 v[36:39], v50, s[6:7] offset:256
	v_add_u32_e32 v50, v50, v116
	v_cvt_pk_bf16_f32 v180, v92, v93
	v_cvt_pk_bf16_f32 v181, v94, v95
	v_cvt_pk_bf16_f32 v182, v96, v97
	v_cvt_pk_bf16_f32 v183, v98, v99
	global_store_dwordx2 v51, v[180:181], s[8:9]
	global_store_dwordx2 v51, v[182:183], s[8:9] offset:128
	v_add_u32_e32 v51, v51, v117
	s_waitcnt vmcnt(42)
	v_pk_fma_f32 v[172:173], v[108:109], v[92:93], v[40:41]
	v_pk_fma_f32 v[176:177], v[108:109], v[96:97], v[44:45]
	v_pk_fma_f32 v[174:175], v[110:111], v[94:95], v[42:43]
	v_pk_fma_f32 v[178:179], v[110:111], v[98:99], v[46:47]
	v_pk_fma_f32 v[100:101], v[112:113], v[96:97], v[172:173] neg_lo:[1,0,0] neg_hi:[1,0,0]
	v_pk_fma_f32 v[104:105], v[112:113], v[92:93], v[176:177]
	v_pk_fma_f32 v[102:103], v[114:115], v[98:99], v[174:175] neg_lo:[1,0,0] neg_hi:[1,0,0]
	v_pk_fma_f32 v[106:107], v[114:115], v[94:95], v[178:179]
	global_load_dwordx4 v[40:43], v50, s[6:7]
	global_load_dwordx4 v[44:47], v50, s[6:7] offset:256
	v_add_u32_e32 v50, v50, v116
	v_cvt_pk_bf16_f32 v184, v100, v101
	v_cvt_pk_bf16_f32 v185, v102, v103
	v_cvt_pk_bf16_f32 v186, v104, v105
	v_cvt_pk_bf16_f32 v187, v106, v107
	global_store_dwordx2 v51, v[184:185], s[8:9]
	global_store_dwordx2 v51, v[186:187], s[8:9] offset:128
	v_add_u32_e32 v51, v51, v117
	s_waitcnt vmcnt(42)
	v_pk_fma_f32 v[172:173], v[108:109], v[100:101], v[52:53]
	v_pk_fma_f32 v[176:177], v[108:109], v[104:105], v[56:57]
	v_pk_fma_f32 v[174:175], v[110:111], v[102:103], v[54:55]
	v_pk_fma_f32 v[178:179], v[110:111], v[106:107], v[58:59]
	v_pk_fma_f32 v[92:93], v[112:113], v[104:105], v[172:173] neg_lo:[1,0,0] neg_hi:[1,0,0]
	v_pk_fma_f32 v[96:97], v[112:113], v[100:101], v[176:177]
	v_pk_fma_f32 v[94:95], v[114:115], v[106:107], v[174:175] neg_lo:[1,0,0] neg_hi:[1,0,0]
	v_pk_fma_f32 v[98:99], v[114:115], v[102:103], v[178:179]
	global_load_dwordx4 v[52:55], v50, s[6:7]
	global_load_dwordx4 v[56:59], v50, s[6:7] offset:256
	v_add_u32_e32 v50, v50, v116
	v_cvt_pk_bf16_f32 v180, v92, v93
	v_cvt_pk_bf16_f32 v181, v94, v95
	v_cvt_pk_bf16_f32 v182, v96, v97
	v_cvt_pk_bf16_f32 v183, v98, v99
	global_store_dwordx2 v51, v[180:181], s[8:9]
	global_store_dwordx2 v51, v[182:183], s[8:9] offset:128
	v_add_u32_e32 v51, v51, v117
	s_waitcnt vmcnt(42)
	v_pk_fma_f32 v[172:173], v[108:109], v[92:93], v[60:61]
	v_pk_fma_f32 v[176:177], v[108:109], v[96:97], v[64:65]
	v_pk_fma_f32 v[174:175], v[110:111], v[94:95], v[62:63]
	v_pk_fma_f32 v[178:179], v[110:111], v[98:99], v[66:67]
	v_pk_fma_f32 v[100:101], v[112:113], v[96:97], v[172:173] neg_lo:[1,0,0] neg_hi:[1,0,0]
	v_pk_fma_f32 v[104:105], v[112:113], v[92:93], v[176:177]
	v_pk_fma_f32 v[102:103], v[114:115], v[98:99], v[174:175] neg_lo:[1,0,0] neg_hi:[1,0,0]
	v_pk_fma_f32 v[106:107], v[114:115], v[94:95], v[178:179]
	global_load_dwordx4 v[60:63], v50, s[6:7]
	global_load_dwordx4 v[64:67], v50, s[6:7] offset:256
	v_add_u32_e32 v50, v50, v116
	v_cvt_pk_bf16_f32 v184, v100, v101
	v_cvt_pk_bf16_f32 v185, v102, v103
	v_cvt_pk_bf16_f32 v186, v104, v105
	v_cvt_pk_bf16_f32 v187, v106, v107
	global_store_dwordx2 v51, v[184:185], s[8:9]
	global_store_dwordx2 v51, v[186:187], s[8:9] offset:128
	v_add_u32_e32 v51, v51, v117
	s_waitcnt vmcnt(42)
	v_pk_fma_f32 v[172:173], v[108:109], v[100:101], v[68:69]
	v_pk_fma_f32 v[176:177], v[108:109], v[104:105], v[72:73]
	v_pk_fma_f32 v[174:175], v[110:111], v[102:103], v[70:71]
	v_pk_fma_f32 v[178:179], v[110:111], v[106:107], v[74:75]
	v_pk_fma_f32 v[92:93], v[112:113], v[104:105], v[172:173] neg_lo:[1,0,0] neg_hi:[1,0,0]
	v_pk_fma_f32 v[96:97], v[112:113], v[100:101], v[176:177]
	v_pk_fma_f32 v[94:95], v[114:115], v[106:107], v[174:175] neg_lo:[1,0,0] neg_hi:[1,0,0]
	v_pk_fma_f32 v[98:99], v[114:115], v[102:103], v[178:179]
	global_load_dwordx4 v[68:71], v50, s[6:7]
	global_load_dwordx4 v[72:75], v50, s[6:7] offset:256
	v_add_u32_e32 v50, v50, v116
	v_cvt_pk_bf16_f32 v180, v92, v93
	v_cvt_pk_bf16_f32 v181, v94, v95
	v_cvt_pk_bf16_f32 v182, v96, v97
	v_cvt_pk_bf16_f32 v183, v98, v99
	global_store_dwordx2 v51, v[180:181], s[8:9]
	global_store_dwordx2 v51, v[182:183], s[8:9] offset:128
	v_add_u32_e32 v51, v51, v117
	s_waitcnt vmcnt(42)
	v_pk_fma_f32 v[172:173], v[108:109], v[92:93], v[76:77]
	v_pk_fma_f32 v[176:177], v[108:109], v[96:97], v[80:81]
	v_pk_fma_f32 v[174:175], v[110:111], v[94:95], v[78:79]
	v_pk_fma_f32 v[178:179], v[110:111], v[98:99], v[82:83]
	v_pk_fma_f32 v[100:101], v[112:113], v[96:97], v[172:173] neg_lo:[1,0,0] neg_hi:[1,0,0]
	v_pk_fma_f32 v[104:105], v[112:113], v[92:93], v[176:177]
	v_pk_fma_f32 v[102:103], v[114:115], v[98:99], v[174:175] neg_lo:[1,0,0] neg_hi:[1,0,0]
	v_pk_fma_f32 v[106:107], v[114:115], v[94:95], v[178:179]
	global_load_dwordx4 v[76:79], v50, s[6:7]
	global_load_dwordx4 v[80:83], v50, s[6:7] offset:256
	v_add_u32_e32 v50, v50, v116
	v_cvt_pk_bf16_f32 v184, v100, v101
	v_cvt_pk_bf16_f32 v185, v102, v103
	v_cvt_pk_bf16_f32 v186, v104, v105
	v_cvt_pk_bf16_f32 v187, v106, v107
	global_store_dwordx2 v51, v[184:185], s[8:9]
	global_store_dwordx2 v51, v[186:187], s[8:9] offset:128
	v_add_u32_e32 v51, v51, v117
	s_waitcnt vmcnt(42)
	v_pk_fma_f32 v[172:173], v[108:109], v[100:101], v[84:85]
	v_pk_fma_f32 v[176:177], v[108:109], v[104:105], v[88:89]
	v_pk_fma_f32 v[174:175], v[110:111], v[102:103], v[86:87]
	v_pk_fma_f32 v[178:179], v[110:111], v[106:107], v[90:91]
	v_pk_fma_f32 v[92:93], v[112:113], v[104:105], v[172:173] neg_lo:[1,0,0] neg_hi:[1,0,0]
	v_pk_fma_f32 v[96:97], v[112:113], v[100:101], v[176:177]
	v_pk_fma_f32 v[94:95], v[114:115], v[106:107], v[174:175] neg_lo:[1,0,0] neg_hi:[1,0,0]
	v_pk_fma_f32 v[98:99], v[114:115], v[102:103], v[178:179]
	global_load_dwordx4 v[84:87], v50, s[6:7]
	global_load_dwordx4 v[88:91], v50, s[6:7] offset:256
	v_add_u32_e32 v50, v50, v116
	v_cvt_pk_bf16_f32 v180, v92, v93
	v_cvt_pk_bf16_f32 v181, v94, v95
	v_cvt_pk_bf16_f32 v182, v96, v97
	v_cvt_pk_bf16_f32 v183, v98, v99
	global_store_dwordx2 v51, v[180:181], s[8:9]
	global_store_dwordx2 v51, v[182:183], s[8:9] offset:128
	v_add_u32_e32 v51, v51, v117
	s_waitcnt vmcnt(42)
	v_pk_fma_f32 v[172:173], v[108:109], v[92:93], v[0:1]
	v_pk_fma_f32 v[176:177], v[108:109], v[96:97], v[4:5]
	v_pk_fma_f32 v[174:175], v[110:111], v[94:95], v[2:3]
	v_pk_fma_f32 v[178:179], v[110:111], v[98:99], v[6:7]
	v_pk_fma_f32 v[100:101], v[112:113], v[96:97], v[172:173] neg_lo:[1,0,0] neg_hi:[1,0,0]
	v_pk_fma_f32 v[104:105], v[112:113], v[92:93], v[176:177]
	v_pk_fma_f32 v[102:103], v[114:115], v[98:99], v[174:175] neg_lo:[1,0,0] neg_hi:[1,0,0]
	v_pk_fma_f32 v[106:107], v[114:115], v[94:95], v[178:179]
	global_load_dwordx4 v[0:3], v50, s[6:7]
	global_load_dwordx4 v[4:7], v50, s[6:7] offset:256
	v_add_u32_e32 v50, v50, v116
	v_cvt_pk_bf16_f32 v184, v100, v101
	v_cvt_pk_bf16_f32 v185, v102, v103
	v_cvt_pk_bf16_f32 v186, v104, v105
	v_cvt_pk_bf16_f32 v187, v106, v107
	global_store_dwordx2 v51, v[184:185], s[8:9]
	global_store_dwordx2 v51, v[186:187], s[8:9] offset:128
	v_add_u32_e32 v51, v51, v117
	s_waitcnt vmcnt(42)
	v_pk_fma_f32 v[172:173], v[108:109], v[100:101], v[8:9]
	v_pk_fma_f32 v[176:177], v[108:109], v[104:105], v[12:13]
	v_pk_fma_f32 v[174:175], v[110:111], v[102:103], v[10:11]
	v_pk_fma_f32 v[178:179], v[110:111], v[106:107], v[14:15]
	v_pk_fma_f32 v[92:93], v[112:113], v[104:105], v[172:173] neg_lo:[1,0,0] neg_hi:[1,0,0]
	v_pk_fma_f32 v[96:97], v[112:113], v[100:101], v[176:177]
	v_pk_fma_f32 v[94:95], v[114:115], v[106:107], v[174:175] neg_lo:[1,0,0] neg_hi:[1,0,0]
	v_pk_fma_f32 v[98:99], v[114:115], v[102:103], v[178:179]
	global_load_dwordx4 v[8:11], v50, s[6:7]
	global_load_dwordx4 v[12:15], v50, s[6:7] offset:256
	v_add_u32_e32 v50, v50, v116
	v_cvt_pk_bf16_f32 v180, v92, v93
	v_cvt_pk_bf16_f32 v181, v94, v95
	v_cvt_pk_bf16_f32 v182, v96, v97
	v_cvt_pk_bf16_f32 v183, v98, v99
	global_store_dwordx2 v51, v[180:181], s[8:9]
	global_store_dwordx2 v51, v[182:183], s[8:9] offset:128
	v_add_u32_e32 v51, v51, v117
	s_waitcnt vmcnt(42)
	v_pk_fma_f32 v[172:173], v[108:109], v[92:93], v[16:17]
	v_pk_fma_f32 v[176:177], v[108:109], v[96:97], v[20:21]
	v_pk_fma_f32 v[174:175], v[110:111], v[94:95], v[18:19]
	v_pk_fma_f32 v[178:179], v[110:111], v[98:99], v[22:23]
	v_pk_fma_f32 v[100:101], v[112:113], v[96:97], v[172:173] neg_lo:[1,0,0] neg_hi:[1,0,0]
	v_pk_fma_f32 v[104:105], v[112:113], v[92:93], v[176:177]
	v_pk_fma_f32 v[102:103], v[114:115], v[98:99], v[174:175] neg_lo:[1,0,0] neg_hi:[1,0,0]
	v_pk_fma_f32 v[106:107], v[114:115], v[94:95], v[178:179]
	global_load_dwordx4 v[16:19], v50, s[6:7]
	global_load_dwordx4 v[20:23], v50, s[6:7] offset:256
	v_add_u32_e32 v50, v50, v116
	v_cvt_pk_bf16_f32 v184, v100, v101
	v_cvt_pk_bf16_f32 v185, v102, v103
	v_cvt_pk_bf16_f32 v186, v104, v105
	v_cvt_pk_bf16_f32 v187, v106, v107
	global_store_dwordx2 v51, v[184:185], s[8:9]
	global_store_dwordx2 v51, v[186:187], s[8:9] offset:128
	v_add_u32_e32 v51, v51, v117
	s_waitcnt vmcnt(42)
	v_pk_fma_f32 v[172:173], v[108:109], v[100:101], v[24:25]
	v_pk_fma_f32 v[176:177], v[108:109], v[104:105], v[28:29]
	v_pk_fma_f32 v[174:175], v[110:111], v[102:103], v[26:27]
	v_pk_fma_f32 v[178:179], v[110:111], v[106:107], v[30:31]
	v_pk_fma_f32 v[92:93], v[112:113], v[104:105], v[172:173] neg_lo:[1,0,0] neg_hi:[1,0,0]
	v_pk_fma_f32 v[96:97], v[112:113], v[100:101], v[176:177]
	v_pk_fma_f32 v[94:95], v[114:115], v[106:107], v[174:175] neg_lo:[1,0,0] neg_hi:[1,0,0]
	v_pk_fma_f32 v[98:99], v[114:115], v[102:103], v[178:179]
	global_load_dwordx4 v[24:27], v50, s[6:7]
	global_load_dwordx4 v[28:31], v50, s[6:7] offset:256
	v_add_u32_e32 v50, v50, v116
	v_cvt_pk_bf16_f32 v180, v92, v93
	v_cvt_pk_bf16_f32 v181, v94, v95
	v_cvt_pk_bf16_f32 v182, v96, v97
	v_cvt_pk_bf16_f32 v183, v98, v99
	global_store_dwordx2 v51, v[180:181], s[8:9]
	global_store_dwordx2 v51, v[182:183], s[8:9] offset:128
	v_add_u32_e32 v51, v51, v117
	s_waitcnt vmcnt(42)
	v_pk_fma_f32 v[172:173], v[108:109], v[92:93], v[32:33]
	v_pk_fma_f32 v[176:177], v[108:109], v[96:97], v[36:37]
	v_pk_fma_f32 v[174:175], v[110:111], v[94:95], v[34:35]
	v_pk_fma_f32 v[178:179], v[110:111], v[98:99], v[38:39]
	v_pk_fma_f32 v[100:101], v[112:113], v[96:97], v[172:173] neg_lo:[1,0,0] neg_hi:[1,0,0]
	v_pk_fma_f32 v[104:105], v[112:113], v[92:93], v[176:177]
	v_pk_fma_f32 v[102:103], v[114:115], v[98:99], v[174:175] neg_lo:[1,0,0] neg_hi:[1,0,0]
	v_pk_fma_f32 v[106:107], v[114:115], v[94:95], v[178:179]
	global_load_dwordx4 v[32:35], v50, s[6:7]
	global_load_dwordx4 v[36:39], v50, s[6:7] offset:256
	v_add_u32_e32 v50, v50, v116
	v_cvt_pk_bf16_f32 v184, v100, v101
	v_cvt_pk_bf16_f32 v185, v102, v103
	v_cvt_pk_bf16_f32 v186, v104, v105
	v_cvt_pk_bf16_f32 v187, v106, v107
	global_store_dwordx2 v51, v[184:185], s[8:9]
	global_store_dwordx2 v51, v[186:187], s[8:9] offset:128
	v_add_u32_e32 v51, v51, v117
	s_waitcnt vmcnt(42)
	v_pk_fma_f32 v[172:173], v[108:109], v[100:101], v[40:41]
	v_pk_fma_f32 v[176:177], v[108:109], v[104:105], v[44:45]
	v_pk_fma_f32 v[174:175], v[110:111], v[102:103], v[42:43]
	v_pk_fma_f32 v[178:179], v[110:111], v[106:107], v[46:47]
	v_pk_fma_f32 v[92:93], v[112:113], v[104:105], v[172:173] neg_lo:[1,0,0] neg_hi:[1,0,0]
	v_pk_fma_f32 v[96:97], v[112:113], v[100:101], v[176:177]
	v_pk_fma_f32 v[94:95], v[114:115], v[106:107], v[174:175] neg_lo:[1,0,0] neg_hi:[1,0,0]
	v_pk_fma_f32 v[98:99], v[114:115], v[102:103], v[178:179]
	global_load_dwordx4 v[40:43], v50, s[6:7]
	global_load_dwordx4 v[44:47], v50, s[6:7] offset:256
	v_add_u32_e32 v50, v50, v116
	v_cvt_pk_bf16_f32 v180, v92, v93
	v_cvt_pk_bf16_f32 v181, v94, v95
	v_cvt_pk_bf16_f32 v182, v96, v97
	v_cvt_pk_bf16_f32 v183, v98, v99
	global_store_dwordx2 v51, v[180:181], s[8:9]
	global_store_dwordx2 v51, v[182:183], s[8:9] offset:128
	v_add_u32_e32 v51, v51, v117
	s_waitcnt vmcnt(42)
	v_pk_fma_f32 v[172:173], v[108:109], v[92:93], v[52:53]
	v_pk_fma_f32 v[176:177], v[108:109], v[96:97], v[56:57]
	v_pk_fma_f32 v[174:175], v[110:111], v[94:95], v[54:55]
	v_pk_fma_f32 v[178:179], v[110:111], v[98:99], v[58:59]
	v_pk_fma_f32 v[100:101], v[112:113], v[96:97], v[172:173] neg_lo:[1,0,0] neg_hi:[1,0,0]
	v_pk_fma_f32 v[104:105], v[112:113], v[92:93], v[176:177]
	v_pk_fma_f32 v[102:103], v[114:115], v[98:99], v[174:175] neg_lo:[1,0,0] neg_hi:[1,0,0]
	v_pk_fma_f32 v[106:107], v[114:115], v[94:95], v[178:179]
	global_load_dwordx4 v[52:55], v50, s[6:7]
	global_load_dwordx4 v[56:59], v50, s[6:7] offset:256
	v_add_u32_e32 v50, v50, v116
	v_cvt_pk_bf16_f32 v184, v100, v101
	v_cvt_pk_bf16_f32 v185, v102, v103
	v_cvt_pk_bf16_f32 v186, v104, v105
	v_cvt_pk_bf16_f32 v187, v106, v107
	global_store_dwordx2 v51, v[184:185], s[8:9]
	global_store_dwordx2 v51, v[186:187], s[8:9] offset:128
	v_add_u32_e32 v51, v51, v117
	s_waitcnt vmcnt(42)
	v_pk_fma_f32 v[172:173], v[108:109], v[100:101], v[60:61]
	v_pk_fma_f32 v[176:177], v[108:109], v[104:105], v[64:65]
	v_pk_fma_f32 v[174:175], v[110:111], v[102:103], v[62:63]
	v_pk_fma_f32 v[178:179], v[110:111], v[106:107], v[66:67]
	v_pk_fma_f32 v[92:93], v[112:113], v[104:105], v[172:173] neg_lo:[1,0,0] neg_hi:[1,0,0]
	v_pk_fma_f32 v[96:97], v[112:113], v[100:101], v[176:177]
	v_pk_fma_f32 v[94:95], v[114:115], v[106:107], v[174:175] neg_lo:[1,0,0] neg_hi:[1,0,0]
	v_pk_fma_f32 v[98:99], v[114:115], v[102:103], v[178:179]
	global_load_dwordx4 v[60:63], v50, s[6:7]
	global_load_dwordx4 v[64:67], v50, s[6:7] offset:256
	v_add_u32_e32 v50, v50, v116
	v_cvt_pk_bf16_f32 v180, v92, v93
	v_cvt_pk_bf16_f32 v181, v94, v95
	v_cvt_pk_bf16_f32 v182, v96, v97
	v_cvt_pk_bf16_f32 v183, v98, v99
	global_store_dwordx2 v51, v[180:181], s[8:9]
	global_store_dwordx2 v51, v[182:183], s[8:9] offset:128
	v_add_u32_e32 v51, v51, v117
	s_waitcnt vmcnt(42)
	v_pk_fma_f32 v[172:173], v[108:109], v[92:93], v[68:69]
	v_pk_fma_f32 v[176:177], v[108:109], v[96:97], v[72:73]
	v_pk_fma_f32 v[174:175], v[110:111], v[94:95], v[70:71]
	v_pk_fma_f32 v[178:179], v[110:111], v[98:99], v[74:75]
	v_pk_fma_f32 v[100:101], v[112:113], v[96:97], v[172:173] neg_lo:[1,0,0] neg_hi:[1,0,0]
	v_pk_fma_f32 v[104:105], v[112:113], v[92:93], v[176:177]
	v_pk_fma_f32 v[102:103], v[114:115], v[98:99], v[174:175] neg_lo:[1,0,0] neg_hi:[1,0,0]
	v_pk_fma_f32 v[106:107], v[114:115], v[94:95], v[178:179]
	global_load_dwordx4 v[68:71], v50, s[6:7]
	global_load_dwordx4 v[72:75], v50, s[6:7] offset:256
	v_add_u32_e32 v50, v50, v116
	v_cvt_pk_bf16_f32 v184, v100, v101
	v_cvt_pk_bf16_f32 v185, v102, v103
	v_cvt_pk_bf16_f32 v186, v104, v105
	v_cvt_pk_bf16_f32 v187, v106, v107
	global_store_dwordx2 v51, v[184:185], s[8:9]
	global_store_dwordx2 v51, v[186:187], s[8:9] offset:128
	v_add_u32_e32 v51, v51, v117
	s_waitcnt vmcnt(42)
	v_pk_fma_f32 v[172:173], v[108:109], v[100:101], v[76:77]
	v_pk_fma_f32 v[176:177], v[108:109], v[104:105], v[80:81]
	v_pk_fma_f32 v[174:175], v[110:111], v[102:103], v[78:79]
	v_pk_fma_f32 v[178:179], v[110:111], v[106:107], v[82:83]
	v_pk_fma_f32 v[92:93], v[112:113], v[104:105], v[172:173] neg_lo:[1,0,0] neg_hi:[1,0,0]
	v_pk_fma_f32 v[96:97], v[112:113], v[100:101], v[176:177]
	v_pk_fma_f32 v[94:95], v[114:115], v[106:107], v[174:175] neg_lo:[1,0,0] neg_hi:[1,0,0]
	v_pk_fma_f32 v[98:99], v[114:115], v[102:103], v[178:179]
	global_load_dwordx4 v[76:79], v50, s[6:7]
	global_load_dwordx4 v[80:83], v50, s[6:7] offset:256
	v_add_u32_e32 v50, v50, v116
	v_cvt_pk_bf16_f32 v180, v92, v93
	v_cvt_pk_bf16_f32 v181, v94, v95
	v_cvt_pk_bf16_f32 v182, v96, v97
	v_cvt_pk_bf16_f32 v183, v98, v99
	global_store_dwordx2 v51, v[180:181], s[8:9]
	global_store_dwordx2 v51, v[182:183], s[8:9] offset:128
	v_add_u32_e32 v51, v51, v117
	s_waitcnt vmcnt(42)
	v_pk_fma_f32 v[172:173], v[108:109], v[92:93], v[84:85]
	v_pk_fma_f32 v[176:177], v[108:109], v[96:97], v[88:89]
	v_pk_fma_f32 v[174:175], v[110:111], v[94:95], v[86:87]
	v_pk_fma_f32 v[178:179], v[110:111], v[98:99], v[90:91]
	v_pk_fma_f32 v[100:101], v[112:113], v[96:97], v[172:173] neg_lo:[1,0,0] neg_hi:[1,0,0]
	v_pk_fma_f32 v[104:105], v[112:113], v[92:93], v[176:177]
	v_pk_fma_f32 v[102:103], v[114:115], v[98:99], v[174:175] neg_lo:[1,0,0] neg_hi:[1,0,0]
	v_pk_fma_f32 v[106:107], v[114:115], v[94:95], v[178:179]
	global_load_dwordx4 v[84:87], v50, s[6:7]
	global_load_dwordx4 v[88:91], v50, s[6:7] offset:256
	v_add_u32_e32 v50, v50, v116
	v_cvt_pk_bf16_f32 v184, v100, v101
	v_cvt_pk_bf16_f32 v185, v102, v103
	v_cvt_pk_bf16_f32 v186, v104, v105
	v_cvt_pk_bf16_f32 v187, v106, v107
	global_store_dwordx2 v51, v[184:185], s[8:9]
	global_store_dwordx2 v51, v[186:187], s[8:9] offset:128
	v_add_u32_e32 v51, v51, v117
	s_waitcnt vmcnt(42)
	v_pk_fma_f32 v[172:173], v[108:109], v[100:101], v[0:1]
	v_pk_fma_f32 v[176:177], v[108:109], v[104:105], v[4:5]
	v_pk_fma_f32 v[174:175], v[110:111], v[102:103], v[2:3]
	v_pk_fma_f32 v[178:179], v[110:111], v[106:107], v[6:7]
	v_pk_fma_f32 v[92:93], v[112:113], v[104:105], v[172:173] neg_lo:[1,0,0] neg_hi:[1,0,0]
	v_pk_fma_f32 v[96:97], v[112:113], v[100:101], v[176:177]
	v_pk_fma_f32 v[94:95], v[114:115], v[106:107], v[174:175] neg_lo:[1,0,0] neg_hi:[1,0,0]
	v_pk_fma_f32 v[98:99], v[114:115], v[102:103], v[178:179]
	global_load_dwordx4 v[0:3], v50, s[6:7]
	global_load_dwordx4 v[4:7], v50, s[6:7] offset:256
	v_add_u32_e32 v50, v50, v116
	v_cvt_pk_bf16_f32 v180, v92, v93
	v_cvt_pk_bf16_f32 v181, v94, v95
	v_cvt_pk_bf16_f32 v182, v96, v97
	v_cvt_pk_bf16_f32 v183, v98, v99
	global_store_dwordx2 v51, v[180:181], s[8:9]
	global_store_dwordx2 v51, v[182:183], s[8:9] offset:128
	v_add_u32_e32 v51, v51, v117
	s_waitcnt vmcnt(42)
	v_pk_fma_f32 v[172:173], v[108:109], v[92:93], v[8:9]
	v_pk_fma_f32 v[176:177], v[108:109], v[96:97], v[12:13]
	v_pk_fma_f32 v[174:175], v[110:111], v[94:95], v[10:11]
	v_pk_fma_f32 v[178:179], v[110:111], v[98:99], v[14:15]
	v_pk_fma_f32 v[100:101], v[112:113], v[96:97], v[172:173] neg_lo:[1,0,0] neg_hi:[1,0,0]
	v_pk_fma_f32 v[104:105], v[112:113], v[92:93], v[176:177]
	v_pk_fma_f32 v[102:103], v[114:115], v[98:99], v[174:175] neg_lo:[1,0,0] neg_hi:[1,0,0]
	v_pk_fma_f32 v[106:107], v[114:115], v[94:95], v[178:179]
	global_load_dwordx4 v[8:11], v50, s[6:7]
	global_load_dwordx4 v[12:15], v50, s[6:7] offset:256
	v_add_u32_e32 v50, v50, v116
	v_cvt_pk_bf16_f32 v184, v100, v101
	v_cvt_pk_bf16_f32 v185, v102, v103
	v_cvt_pk_bf16_f32 v186, v104, v105
	v_cvt_pk_bf16_f32 v187, v106, v107
	global_store_dwordx2 v51, v[184:185], s[8:9]
	global_store_dwordx2 v51, v[186:187], s[8:9] offset:128
	v_add_u32_e32 v51, v51, v117
	s_waitcnt vmcnt(42)
	v_pk_fma_f32 v[172:173], v[108:109], v[100:101], v[16:17]
	v_pk_fma_f32 v[176:177], v[108:109], v[104:105], v[20:21]
	v_pk_fma_f32 v[174:175], v[110:111], v[102:103], v[18:19]
	v_pk_fma_f32 v[178:179], v[110:111], v[106:107], v[22:23]
	v_pk_fma_f32 v[92:93], v[112:113], v[104:105], v[172:173] neg_lo:[1,0,0] neg_hi:[1,0,0]
	v_pk_fma_f32 v[96:97], v[112:113], v[100:101], v[176:177]
	v_pk_fma_f32 v[94:95], v[114:115], v[106:107], v[174:175] neg_lo:[1,0,0] neg_hi:[1,0,0]
	v_pk_fma_f32 v[98:99], v[114:115], v[102:103], v[178:179]
	global_load_dwordx4 v[16:19], v50, s[6:7]
	global_load_dwordx4 v[20:23], v50, s[6:7] offset:256
	v_add_u32_e32 v50, v50, v116
	v_cvt_pk_bf16_f32 v180, v92, v93
	v_cvt_pk_bf16_f32 v181, v94, v95
	v_cvt_pk_bf16_f32 v182, v96, v97
	v_cvt_pk_bf16_f32 v183, v98, v99
	global_store_dwordx2 v51, v[180:181], s[8:9]
	global_store_dwordx2 v51, v[182:183], s[8:9] offset:128
	v_add_u32_e32 v51, v51, v117
	s_waitcnt vmcnt(42)
	v_pk_fma_f32 v[172:173], v[108:109], v[92:93], v[24:25]
	v_pk_fma_f32 v[176:177], v[108:109], v[96:97], v[28:29]
	v_pk_fma_f32 v[174:175], v[110:111], v[94:95], v[26:27]
	v_pk_fma_f32 v[178:179], v[110:111], v[98:99], v[30:31]
	v_pk_fma_f32 v[100:101], v[112:113], v[96:97], v[172:173] neg_lo:[1,0,0] neg_hi:[1,0,0]
	v_pk_fma_f32 v[104:105], v[112:113], v[92:93], v[176:177]
	v_pk_fma_f32 v[102:103], v[114:115], v[98:99], v[174:175] neg_lo:[1,0,0] neg_hi:[1,0,0]
	v_pk_fma_f32 v[106:107], v[114:115], v[94:95], v[178:179]
	global_load_dwordx4 v[24:27], v50, s[6:7]
	global_load_dwordx4 v[28:31], v50, s[6:7] offset:256
	v_add_u32_e32 v50, v50, v116
	v_cvt_pk_bf16_f32 v184, v100, v101
	v_cvt_pk_bf16_f32 v185, v102, v103
	v_cvt_pk_bf16_f32 v186, v104, v105
	v_cvt_pk_bf16_f32 v187, v106, v107
	global_store_dwordx2 v51, v[184:185], s[8:9]
	global_store_dwordx2 v51, v[186:187], s[8:9] offset:128
	v_add_u32_e32 v51, v51, v117
	s_waitcnt vmcnt(42)
	v_pk_fma_f32 v[172:173], v[108:109], v[100:101], v[32:33]
	v_pk_fma_f32 v[176:177], v[108:109], v[104:105], v[36:37]
	v_pk_fma_f32 v[174:175], v[110:111], v[102:103], v[34:35]
	v_pk_fma_f32 v[178:179], v[110:111], v[106:107], v[38:39]
	v_pk_fma_f32 v[92:93], v[112:113], v[104:105], v[172:173] neg_lo:[1,0,0] neg_hi:[1,0,0]
	v_pk_fma_f32 v[96:97], v[112:113], v[100:101], v[176:177]
	v_pk_fma_f32 v[94:95], v[114:115], v[106:107], v[174:175] neg_lo:[1,0,0] neg_hi:[1,0,0]
	v_pk_fma_f32 v[98:99], v[114:115], v[102:103], v[178:179]
	global_load_dwordx4 v[32:35], v50, s[6:7]
	global_load_dwordx4 v[36:39], v50, s[6:7] offset:256
	v_add_u32_e32 v50, v50, v116
	v_cvt_pk_bf16_f32 v180, v92, v93
	v_cvt_pk_bf16_f32 v181, v94, v95
	v_cvt_pk_bf16_f32 v182, v96, v97
	v_cvt_pk_bf16_f32 v183, v98, v99
	global_store_dwordx2 v51, v[180:181], s[8:9]
	global_store_dwordx2 v51, v[182:183], s[8:9] offset:128
	v_add_u32_e32 v51, v51, v117
	s_waitcnt vmcnt(42)
	v_pk_fma_f32 v[172:173], v[108:109], v[92:93], v[40:41]
	v_pk_fma_f32 v[176:177], v[108:109], v[96:97], v[44:45]
	v_pk_fma_f32 v[174:175], v[110:111], v[94:95], v[42:43]
	v_pk_fma_f32 v[178:179], v[110:111], v[98:99], v[46:47]
	v_pk_fma_f32 v[100:101], v[112:113], v[96:97], v[172:173] neg_lo:[1,0,0] neg_hi:[1,0,0]
	v_pk_fma_f32 v[104:105], v[112:113], v[92:93], v[176:177]
	v_pk_fma_f32 v[102:103], v[114:115], v[98:99], v[174:175] neg_lo:[1,0,0] neg_hi:[1,0,0]
	v_pk_fma_f32 v[106:107], v[114:115], v[94:95], v[178:179]
	v_cvt_pk_bf16_f32 v184, v100, v101
	v_cvt_pk_bf16_f32 v185, v102, v103
	v_cvt_pk_bf16_f32 v186, v104, v105
	v_cvt_pk_bf16_f32 v187, v106, v107
	global_store_dwordx2 v51, v[184:185], s[8:9]
	global_store_dwordx2 v51, v[186:187], s[8:9] offset:128
	v_add_u32_e32 v51, v51, v117
	s_waitcnt vmcnt(40)
	v_pk_fma_f32 v[172:173], v[108:109], v[100:101], v[52:53]
	v_pk_fma_f32 v[176:177], v[108:109], v[104:105], v[56:57]
	v_pk_fma_f32 v[174:175], v[110:111], v[102:103], v[54:55]
	v_pk_fma_f32 v[178:179], v[110:111], v[106:107], v[58:59]
	v_pk_fma_f32 v[92:93], v[112:113], v[104:105], v[172:173] neg_lo:[1,0,0] neg_hi:[1,0,0]
	v_pk_fma_f32 v[96:97], v[112:113], v[100:101], v[176:177]
	v_pk_fma_f32 v[94:95], v[114:115], v[106:107], v[174:175] neg_lo:[1,0,0] neg_hi:[1,0,0]
	v_pk_fma_f32 v[98:99], v[114:115], v[102:103], v[178:179]
	v_cvt_pk_bf16_f32 v180, v92, v93
	v_cvt_pk_bf16_f32 v181, v94, v95
	v_cvt_pk_bf16_f32 v182, v96, v97
	v_cvt_pk_bf16_f32 v183, v98, v99
	global_store_dwordx2 v51, v[180:181], s[8:9]
	global_store_dwordx2 v51, v[182:183], s[8:9] offset:128
	v_add_u32_e32 v51, v51, v117
	s_waitcnt vmcnt(38)
	v_pk_fma_f32 v[172:173], v[108:109], v[92:93], v[60:61]
	v_pk_fma_f32 v[176:177], v[108:109], v[96:97], v[64:65]
	v_pk_fma_f32 v[174:175], v[110:111], v[94:95], v[62:63]
	v_pk_fma_f32 v[178:179], v[110:111], v[98:99], v[66:67]
	v_pk_fma_f32 v[100:101], v[112:113], v[96:97], v[172:173] neg_lo:[1,0,0] neg_hi:[1,0,0]
	v_pk_fma_f32 v[104:105], v[112:113], v[92:93], v[176:177]
	v_pk_fma_f32 v[102:103], v[114:115], v[98:99], v[174:175] neg_lo:[1,0,0] neg_hi:[1,0,0]
	v_pk_fma_f32 v[106:107], v[114:115], v[94:95], v[178:179]
	v_cvt_pk_bf16_f32 v184, v100, v101
	v_cvt_pk_bf16_f32 v185, v102, v103
	v_cvt_pk_bf16_f32 v186, v104, v105
	v_cvt_pk_bf16_f32 v187, v106, v107
	global_store_dwordx2 v51, v[184:185], s[8:9]
	global_store_dwordx2 v51, v[186:187], s[8:9] offset:128
	v_add_u32_e32 v51, v51, v117
	s_waitcnt vmcnt(36)
	v_pk_fma_f32 v[172:173], v[108:109], v[100:101], v[68:69]
	v_pk_fma_f32 v[176:177], v[108:109], v[104:105], v[72:73]
	v_pk_fma_f32 v[174:175], v[110:111], v[102:103], v[70:71]
	v_pk_fma_f32 v[178:179], v[110:111], v[106:107], v[74:75]
	v_pk_fma_f32 v[92:93], v[112:113], v[104:105], v[172:173] neg_lo:[1,0,0] neg_hi:[1,0,0]
	v_pk_fma_f32 v[96:97], v[112:113], v[100:101], v[176:177]
	v_pk_fma_f32 v[94:95], v[114:115], v[106:107], v[174:175] neg_lo:[1,0,0] neg_hi:[1,0,0]
	v_pk_fma_f32 v[98:99], v[114:115], v[102:103], v[178:179]
	v_cvt_pk_bf16_f32 v180, v92, v93
	v_cvt_pk_bf16_f32 v181, v94, v95
	v_cvt_pk_bf16_f32 v182, v96, v97
	v_cvt_pk_bf16_f32 v183, v98, v99
	global_store_dwordx2 v51, v[180:181], s[8:9]
	global_store_dwordx2 v51, v[182:183], s[8:9] offset:128
	v_add_u32_e32 v51, v51, v117
	s_waitcnt vmcnt(34)
	v_pk_fma_f32 v[172:173], v[108:109], v[92:93], v[76:77]
	v_pk_fma_f32 v[176:177], v[108:109], v[96:97], v[80:81]
	v_pk_fma_f32 v[174:175], v[110:111], v[94:95], v[78:79]
	v_pk_fma_f32 v[178:179], v[110:111], v[98:99], v[82:83]
	v_pk_fma_f32 v[100:101], v[112:113], v[96:97], v[172:173] neg_lo:[1,0,0] neg_hi:[1,0,0]
	v_pk_fma_f32 v[104:105], v[112:113], v[92:93], v[176:177]
	v_pk_fma_f32 v[102:103], v[114:115], v[98:99], v[174:175] neg_lo:[1,0,0] neg_hi:[1,0,0]
	v_pk_fma_f32 v[106:107], v[114:115], v[94:95], v[178:179]
	v_cvt_pk_bf16_f32 v184, v100, v101
	v_cvt_pk_bf16_f32 v185, v102, v103
	v_cvt_pk_bf16_f32 v186, v104, v105
	v_cvt_pk_bf16_f32 v187, v106, v107
	global_store_dwordx2 v51, v[184:185], s[8:9]
	global_store_dwordx2 v51, v[186:187], s[8:9] offset:128
	v_add_u32_e32 v51, v51, v117
	s_waitcnt vmcnt(32)
	v_pk_fma_f32 v[172:173], v[108:109], v[100:101], v[84:85]
	v_pk_fma_f32 v[176:177], v[108:109], v[104:105], v[88:89]
	v_pk_fma_f32 v[174:175], v[110:111], v[102:103], v[86:87]
	v_pk_fma_f32 v[178:179], v[110:111], v[106:107], v[90:91]
	v_pk_fma_f32 v[92:93], v[112:113], v[104:105], v[172:173] neg_lo:[1,0,0] neg_hi:[1,0,0]
	v_pk_fma_f32 v[96:97], v[112:113], v[100:101], v[176:177]
	v_pk_fma_f32 v[94:95], v[114:115], v[106:107], v[174:175] neg_lo:[1,0,0] neg_hi:[1,0,0]
	v_pk_fma_f32 v[98:99], v[114:115], v[102:103], v[178:179]
	v_cvt_pk_bf16_f32 v180, v92, v93
	v_cvt_pk_bf16_f32 v181, v94, v95
	v_cvt_pk_bf16_f32 v182, v96, v97
	v_cvt_pk_bf16_f32 v183, v98, v99
	global_store_dwordx2 v51, v[180:181], s[8:9]
	global_store_dwordx2 v51, v[182:183], s[8:9] offset:128
	v_add_u32_e32 v51, v51, v117
	s_waitcnt vmcnt(30)
	v_pk_fma_f32 v[172:173], v[108:109], v[92:93], v[0:1]
	v_pk_fma_f32 v[176:177], v[108:109], v[96:97], v[4:5]
	v_pk_fma_f32 v[174:175], v[110:111], v[94:95], v[2:3]
	v_pk_fma_f32 v[178:179], v[110:111], v[98:99], v[6:7]
	v_pk_fma_f32 v[100:101], v[112:113], v[96:97], v[172:173] neg_lo:[1,0,0] neg_hi:[1,0,0]
	v_pk_fma_f32 v[104:105], v[112:113], v[92:93], v[176:177]
	v_pk_fma_f32 v[102:103], v[114:115], v[98:99], v[174:175] neg_lo:[1,0,0] neg_hi:[1,0,0]
	v_pk_fma_f32 v[106:107], v[114:115], v[94:95], v[178:179]
	v_cvt_pk_bf16_f32 v184, v100, v101
	v_cvt_pk_bf16_f32 v185, v102, v103
	v_cvt_pk_bf16_f32 v186, v104, v105
	v_cvt_pk_bf16_f32 v187, v106, v107
	global_store_dwordx2 v51, v[184:185], s[8:9]
	global_store_dwordx2 v51, v[186:187], s[8:9] offset:128
	v_add_u32_e32 v51, v51, v117
	s_waitcnt vmcnt(28)
	v_pk_fma_f32 v[172:173], v[108:109], v[100:101], v[8:9]
	v_pk_fma_f32 v[176:177], v[108:109], v[104:105], v[12:13]
	v_pk_fma_f32 v[174:175], v[110:111], v[102:103], v[10:11]
	v_pk_fma_f32 v[178:179], v[110:111], v[106:107], v[14:15]
	v_pk_fma_f32 v[92:93], v[112:113], v[104:105], v[172:173] neg_lo:[1,0,0] neg_hi:[1,0,0]
	v_pk_fma_f32 v[96:97], v[112:113], v[100:101], v[176:177]
	v_pk_fma_f32 v[94:95], v[114:115], v[106:107], v[174:175] neg_lo:[1,0,0] neg_hi:[1,0,0]
	v_pk_fma_f32 v[98:99], v[114:115], v[102:103], v[178:179]
	v_cvt_pk_bf16_f32 v180, v92, v93
	v_cvt_pk_bf16_f32 v181, v94, v95
	v_cvt_pk_bf16_f32 v182, v96, v97
	v_cvt_pk_bf16_f32 v183, v98, v99
	global_store_dwordx2 v51, v[180:181], s[8:9]
	global_store_dwordx2 v51, v[182:183], s[8:9] offset:128
	v_add_u32_e32 v51, v51, v117
	s_waitcnt vmcnt(26)
	v_pk_fma_f32 v[172:173], v[108:109], v[92:93], v[16:17]
	v_pk_fma_f32 v[176:177], v[108:109], v[96:97], v[20:21]
	v_pk_fma_f32 v[174:175], v[110:111], v[94:95], v[18:19]
	v_pk_fma_f32 v[178:179], v[110:111], v[98:99], v[22:23]
	v_pk_fma_f32 v[100:101], v[112:113], v[96:97], v[172:173] neg_lo:[1,0,0] neg_hi:[1,0,0]
	v_pk_fma_f32 v[104:105], v[112:113], v[92:93], v[176:177]
	v_pk_fma_f32 v[102:103], v[114:115], v[98:99], v[174:175] neg_lo:[1,0,0] neg_hi:[1,0,0]
	v_pk_fma_f32 v[106:107], v[114:115], v[94:95], v[178:179]
	v_cvt_pk_bf16_f32 v184, v100, v101
	v_cvt_pk_bf16_f32 v185, v102, v103
	v_cvt_pk_bf16_f32 v186, v104, v105
	v_cvt_pk_bf16_f32 v187, v106, v107
	global_store_dwordx2 v51, v[184:185], s[8:9]
	global_store_dwordx2 v51, v[186:187], s[8:9] offset:128
	v_add_u32_e32 v51, v51, v117
	s_waitcnt vmcnt(24)
	v_pk_fma_f32 v[172:173], v[108:109], v[100:101], v[24:25]
	v_pk_fma_f32 v[176:177], v[108:109], v[104:105], v[28:29]
	v_pk_fma_f32 v[174:175], v[110:111], v[102:103], v[26:27]
	v_pk_fma_f32 v[178:179], v[110:111], v[106:107], v[30:31]
	v_pk_fma_f32 v[92:93], v[112:113], v[104:105], v[172:173] neg_lo:[1,0,0] neg_hi:[1,0,0]
	v_pk_fma_f32 v[96:97], v[112:113], v[100:101], v[176:177]
	v_pk_fma_f32 v[94:95], v[114:115], v[106:107], v[174:175] neg_lo:[1,0,0] neg_hi:[1,0,0]
	v_pk_fma_f32 v[98:99], v[114:115], v[102:103], v[178:179]
	v_cvt_pk_bf16_f32 v180, v92, v93
	v_cvt_pk_bf16_f32 v181, v94, v95
	v_cvt_pk_bf16_f32 v182, v96, v97
	v_cvt_pk_bf16_f32 v183, v98, v99
	global_store_dwordx2 v51, v[180:181], s[8:9]
	global_store_dwordx2 v51, v[182:183], s[8:9] offset:128
	v_add_u32_e32 v51, v51, v117
	s_waitcnt vmcnt(22)
	v_pk_fma_f32 v[172:173], v[108:109], v[92:93], v[32:33]
	v_pk_fma_f32 v[176:177], v[108:109], v[96:97], v[36:37]
	v_pk_fma_f32 v[174:175], v[110:111], v[94:95], v[34:35]
	v_pk_fma_f32 v[178:179], v[110:111], v[98:99], v[38:39]
	v_pk_fma_f32 v[100:101], v[112:113], v[96:97], v[172:173] neg_lo:[1,0,0] neg_hi:[1,0,0]
	v_pk_fma_f32 v[104:105], v[112:113], v[92:93], v[176:177]
	v_pk_fma_f32 v[102:103], v[114:115], v[98:99], v[174:175] neg_lo:[1,0,0] neg_hi:[1,0,0]
	v_pk_fma_f32 v[106:107], v[114:115], v[94:95], v[178:179]
	v_cvt_pk_bf16_f32 v184, v100, v101
	v_cvt_pk_bf16_f32 v185, v102, v103
	v_cvt_pk_bf16_f32 v186, v104, v105
	v_cvt_pk_bf16_f32 v187, v106, v107
	global_store_dwordx2 v51, v[184:185], s[8:9]
	global_store_dwordx2 v51, v[186:187], s[8:9] offset:128
	v_add_u32_e32 v51, v51, v117

.LBB0_920:
	s_xor_b64 s[62:63], s[62:63], -1
	s_andn2_b64 vcc, exec, s[80:81]
	s_cbranch_vccnz .LBB0_855
	ds_read_b128 v[0:3], v187 offset:52224
	ds_read_b128 v[4:7], v150 offset:27648
	ds_read_b128 v[32:35], v187 offset:52256
	ds_read_b128 v[36:39], v150 offset:27680
	v_readlane_b32 s0, v254, 2
	v_readlane_b32 s1, v254, 3
	s_waitcnt lgkmcnt(2)
	v_mfma_f32_32x32x16_bf16 v[16:31], v[0:3], v[4:7], 0
	ds_read_b128 v[0:3], v188 offset:52224
	ds_read_b128 v[4:7], v152 offset:27648
	ds_read_b128 v[40:43], v187 offset:52288
	ds_read_b128 v[44:47], v150 offset:27712
	v_cmp_lt_i32_e32 vcc, v231, v230
	v_lshl_add_u64 v[182:183], s[84:85], 0, v[154:155]
	s_nop 0
	v_cndmask_b32_e32 v48, v229, v231, vcc
	s_mul_i32 vcc_lo, s16, 0x180
	s_waitcnt lgkmcnt(2)
	v_mfma_f32_32x32x16_bf16 v[0:15], v[0:3], v[4:7], 0
	v_mfma_f32_32x32x16_bf16 v[16:31], v[32:35], v[36:39], v[16:31]
	ds_read_b128 v[32:35], v188 offset:52256
	ds_read_b128 v[36:39], v152 offset:27680
	ds_read_b128 v[98:101], v188 offset:52288
	ds_read_b128 v[102:105], v152 offset:27712
	s_waitcnt lgkmcnt(2)
	v_mfma_f32_32x32x16_bf16 v[0:15], v[32:35], v[36:39], v[0:15]
	v_mfma_f32_32x32x16_bf16 v[16:31], v[40:43], v[44:47], v[16:31]
	s_waitcnt lgkmcnt(0)
	v_mfma_f32_32x32x16_bf16 v[0:15], v[98:101], v[102:105], v[0:15]
	s_nop 9
	v_cndmask_b32_e64 v16, v16, 0, s[0:1]
	v_readlane_b32 s0, v254, 4
	v_readlane_b32 s1, v254, 5
	v_cndmask_b32_e64 v0, v0, 0, s[18:19]
	s_nop 0
	v_cndmask_b32_e64 v1, v1, 0, s[0:1]
	v_readlane_b32 s0, v254, 6
	v_add_f32_e32 v16, v16, v0
	v_cndmask_b32_e64 v0, 0, v17, s[18:19]
	v_readlane_b32 s1, v254, 7
	v_add_f32_e32 v17, v0, v1
	s_nop 0
	v_cndmask_b32_e64 v1, v19, 0, s[0:1]
	v_readlane_b32 s0, v254, 8
	v_readlane_b32 s1, v254, 9
	s_nop 1
	v_cndmask_b32_e64 v0, v18, 0, s[0:1]
	v_readlane_b32 s0, v254, 10
	v_readlane_b32 s1, v254, 11
	s_nop 1
	v_cndmask_b32_e64 v3, v3, 0, s[0:1]
	v_readlane_b32 s0, v254, 12
	v_readlane_b32 s1, v254, 13
	s_nop 1
	v_cndmask_b32_e64 v2, v2, 0, s[0:1]
	v_readlane_b32 s0, v254, 14
	v_pk_add_f32 v[0:1], v[0:1], v[2:3]
	v_readlane_b32 s1, v254, 15
	v_cvt_pk_bf16_f32 v3, v0, v1
	v_cvt_pk_bf16_f32 v2, v16, v17
	v_cndmask_b32_e64 v1, v21, 0, s[0:1]
	v_readlane_b32 s0, v254, 16
	v_readlane_b32 s1, v254, 17
	s_nop 1
	v_cndmask_b32_e64 v0, v20, 0, s[0:1]
	v_readlane_b32 s0, v254, 23
	v_readlane_b32 s1, v254, 24
	s_nop 1
	v_cndmask_b32_e64 v5, v5, 0, s[0:1]
	v_readlane_b32 s0, v254, 25
	v_readlane_b32 s1, v254, 26
	s_nop 1
	v_cndmask_b32_e64 v4, v4, 0, s[0:1]
	v_readlane_b32 s0, v254, 27
	v_readlane_b32 s1, v254, 28
	v_pk_add_f32 v[0:1], v[0:1], v[4:5]
	s_nop 0
	v_cndmask_b32_e64 v5, v23, 0, s[0:1]
	v_readlane_b32 s0, v254, 29
	v_readlane_b32 s1, v254, 30
	v_cvt_pk_bf16_f32 v0, v0, v1
	s_nop 0
	v_cndmask_b32_e64 v4, v22, 0, s[0:1]
	v_readlane_b32 s0, v254, 31
	v_readlane_b32 s1, v254, 32
	s_nop 1
	v_cndmask_b32_e64 v7, v7, 0, s[0:1]
	v_readlane_b32 s0, v254, 33
	v_readlane_b32 s1, v254, 34
	s_nop 1
	v_cndmask_b32_e64 v6, v6, 0, s[0:1]
	v_pk_add_f32 v[4:5], v[4:5], v[6:7]
	v_readlane_b32 s0, v254, 35
	v_cvt_pk_bf16_f32 v1, v4, v5
	v_readlane_b32 s1, v254, 36
	ds_write2_b64 v151, v[2:3], v[0:1] offset1:2
	s_nop 0
	v_cndmask_b32_e64 v1, v25, 0, s[0:1]
	v_readlane_b32 s0, v254, 37
	v_readlane_b32 s1, v254, 38
	s_nop 1
	v_cndmask_b32_e64 v0, v24, 0, s[0:1]
	v_readlane_b32 s0, v254, 39
	v_readlane_b32 s1, v254, 40
	s_nop 1
	v_cndmask_b32_e64 v3, v9, 0, s[0:1]
	v_readlane_b32 s0, v254, 41
	v_readlane_b32 s1, v254, 42
	s_nop 1
	v_cndmask_b32_e64 v2, v8, 0, s[0:1]
	v_readlane_b32 s0, v254, 43
	v_readlane_b32 s1, v254, 44
	v_pk_add_f32 v[0:1], v[0:1], v[2:3]
	s_nop 0
	v_cndmask_b32_e64 v3, v27, 0, s[0:1]
	v_readlane_b32 s0, v254, 45
	v_readlane_b32 s1, v254, 46
	v_cvt_pk_bf16_f32 v0, v0, v1
	s_nop 0
	v_cndmask_b32_e64 v2, v26, 0, s[0:1]
	v_readlane_b32 s0, v254, 47
	v_readlane_b32 s1, v254, 48
	s_nop 1
	v_cndmask_b32_e64 v5, v11, 0, s[0:1]
	v_readlane_b32 s0, v254, 49
	v_readlane_b32 s1, v254, 50
	s_nop 1
	v_cndmask_b32_e64 v4, v10, 0, s[0:1]
	v_readlane_b32 s0, v254, 51
	v_pk_add_f32 v[2:3], v[2:3], v[4:5]
	v_readlane_b32 s1, v254, 52
	v_cvt_pk_bf16_f32 v1, v2, v3
	s_nop 0
	v_cndmask_b32_e64 v3, v29, 0, s[0:1]
	v_readlane_b32 s0, v254, 53
	v_readlane_b32 s1, v254, 54
	s_nop 1
	v_cndmask_b32_e64 v2, v28, 0, s[0:1]
	v_readlane_b32 s0, v254, 55
	v_readlane_b32 s1, v254, 56
	s_nop 1
	v_cndmask_b32_e64 v5, v13, 0, s[0:1]
	v_readlane_b32 s0, v254, 57
	v_readlane_b32 s1, v254, 58
	s_nop 1
	v_cndmask_b32_e64 v4, v12, 0, s[0:1]
	v_readlane_b32 s0, v254, 59
	v_readlane_b32 s1, v254, 60
	v_pk_add_f32 v[2:3], v[2:3], v[4:5]
	s_nop 0
	v_cndmask_b32_e64 v5, v31, 0, s[0:1]
	v_readlane_b32 s0, v254, 61
	v_readlane_b32 s1, v254, 62
	v_cvt_pk_bf16_f32 v2, v2, v3
	s_nop 0
	v_cndmask_b32_e64 v4, v30, 0, s[0:1]
	v_readlane_b32 s0, v254, 63
	v_readlane_b32 s1, v255, 0
	s_nop 1
	v_cndmask_b32_e64 v7, v15, 0, s[0:1]
	v_readlane_b32 s0, v255, 1
	v_readlane_b32 s1, v255, 2
	s_nop 1
	v_cndmask_b32_e64 v6, v14, 0, s[0:1]
	v_pk_add_f32 v[4:5], v[4:5], v[6:7]
	v_readlane_b32 s0, v255, 3
	v_cvt_pk_bf16_f32 v3, v4, v5
	ds_write2_b64 v151, v[0:1], v[2:3] offset0:4 offset1:6
	ds_read_b128 v[0:3], v187 offset:55296
	ds_read_b128 v[4:7], v150 offset:27648
	ds_read_b128 v[32:35], v187 offset:55328
	ds_read_b128 v[36:39], v150 offset:27680
	s_waitcnt lgkmcnt(2)
	v_mfma_f32_32x32x16_bf16 v[0:15], v[0:3], v[4:7], 0
	ds_read_b128 v[16:19], v187 offset:61440
	ds_read_b128 v[20:23], v152 offset:27648
	ds_read_b128 v[40:43], v187 offset:55360
	ds_read_b128 v[44:47], v150 offset:27712
	v_readlane_b32 s1, v255, 4
	s_waitcnt lgkmcnt(2)
	v_mfma_f32_32x32x16_bf16 v[16:31], v[16:19], v[20:23], 0
	v_mfma_f32_32x32x16_bf16 v[0:15], v[32:35], v[36:39], v[0:15]
	ds_read_b128 v[32:35], v187 offset:61472
	ds_read_b128 v[36:39], v152 offset:27680
	ds_read_b128 v[98:101], v187 offset:61504
	ds_read_b128 v[102:105], v152 offset:27712
	s_waitcnt lgkmcnt(2)
	v_mfma_f32_32x32x16_bf16 v[16:31], v[32:35], v[36:39], v[16:31]
	v_mfma_f32_32x32x16_bf16 v[0:15], v[40:43], v[44:47], v[0:15]
	s_waitcnt lgkmcnt(0)
	v_mfma_f32_32x32x16_bf16 v[16:31], v[98:101], v[102:105], v[16:31]
	s_nop 9
	v_cndmask_b32_e64 v1, v1, 0, s[0:1]
	v_readlane_b32 s0, v255, 5
	v_readlane_b32 s1, v255, 6
	s_nop 1
	v_cndmask_b32_e64 v0, v0, 0, s[0:1]
	v_readlane_b32 s0, v255, 7
	v_readlane_b32 s1, v255, 8
	s_nop 1
	v_cndmask_b32_e64 v17, v17, 0, s[0:1]
	v_readlane_b32 s0, v255, 9
	v_readlane_b32 s1, v255, 10
	s_nop 1
	v_cndmask_b32_e64 v16, v16, 0, s[0:1]
	v_readlane_b32 s0, v255, 11
	v_readlane_b32 s1, v255, 12
	v_pk_add_f32 v[0:1], v[0:1], v[16:17]
	s_nop 0
	v_cndmask_b32_e64 v3, v3, 0, s[0:1]
	v_readlane_b32 s0, v255, 13
	v_readlane_b32 s1, v255, 14
	v_cvt_pk_bf16_f32 v0, v0, v1
	s_nop 0
	v_cndmask_b32_e64 v2, v2, 0, s[0:1]
	v_readlane_b32 s0, v255, 15
	v_readlane_b32 s1, v255, 16
	s_nop 1
	v_cndmask_b32_e64 v17, v19, 0, s[0:1]
	v_readlane_b32 s0, v255, 17
	v_readlane_b32 s1, v255, 18
	s_nop 1
	v_cndmask_b32_e64 v16, v18, 0, s[0:1]
	v_readlane_b32 s0, v255, 19
	v_pk_add_f32 v[2:3], v[2:3], v[16:17]
	v_readlane_b32 s1, v255, 20
	v_cvt_pk_bf16_f32 v1, v2, v3
	s_nop 0
	v_cndmask_b32_e64 v3, v5, 0, s[0:1]
	v_readlane_b32 s0, v255, 21
	v_readlane_b32 s1, v255, 22
	s_nop 1
	v_cndmask_b32_e64 v2, v4, 0, s[0:1]
	v_readlane_b32 s0, v255, 23
	v_readlane_b32 s1, v255, 24
	s_nop 1
	v_cndmask_b32_e64 v5, v21, 0, s[0:1]
	v_readlane_b32 s0, v255, 25
	v_readlane_b32 s1, v255, 26
	s_nop 1
	v_cndmask_b32_e64 v4, v20, 0, s[0:1]
	v_readlane_b32 s0, v255, 27
	v_readlane_b32 s1, v255, 28
	v_pk_add_f32 v[2:3], v[2:3], v[4:5]
	s_nop 0
	v_cndmask_b32_e64 v5, v7, 0, s[0:1]
	v_readlane_b32 s0, v255, 29
	v_readlane_b32 s1, v255, 30
	v_cvt_pk_bf16_f32 v2, v2, v3
	s_nop 0
	v_cndmask_b32_e64 v4, v6, 0, s[0:1]
	v_readlane_b32 s0, v255, 31
	v_readlane_b32 s1, v255, 32
	v_cndmask_b32_e64 v6, v22, 0, s[24:25]
	s_nop 0
	v_cndmask_b32_e64 v7, v23, 0, s[0:1]
	v_pk_add_f32 v[4:5], v[4:5], v[6:7]
	v_cndmask_b32_e64 v7, v31, 0, s[56:57]
	v_cvt_pk_bf16_f32 v3, v4, v5
	ds_write2_b64 v151, v[0:1], v[2:3] offset0:8 offset1:10
	v_cndmask_b32_e64 v1, v9, 0, s[26:27]
	v_cndmask_b32_e64 v0, v8, 0, s[28:29]
	v_cndmask_b32_e64 v3, v25, 0, s[30:31]
	v_cndmask_b32_e64 v2, v24, 0, s[34:35]
	v_pk_add_f32 v[0:1], v[0:1], v[2:3]
	v_cndmask_b32_e64 v3, v11, 0, s[36:37]
	v_cndmask_b32_e64 v2, v10, 0, s[38:39]
	v_cndmask_b32_e64 v5, v27, 0, s[40:41]
	v_cndmask_b32_e64 v4, v26, 0, s[42:43]
	v_pk_add_f32 v[2:3], v[2:3], v[4:5]
	v_cvt_pk_bf16_f32 v0, v0, v1
	v_cvt_pk_bf16_f32 v1, v2, v3
	v_cndmask_b32_e64 v3, v13, 0, s[44:45]
	v_cndmask_b32_e64 v2, v12, 0, s[46:47]
	v_cndmask_b32_e64 v5, v29, 0, s[48:49]
	v_cndmask_b32_e64 v4, v28, 0, s[50:51]
	v_pk_add_f32 v[2:3], v[2:3], v[4:5]
	v_cndmask_b32_e64 v5, v15, 0, s[52:53]
	v_cndmask_b32_e64 v4, v14, 0, s[54:55]
	v_cndmask_b32_e64 v6, v30, 0, s[58:59]
	v_pk_add_f32 v[4:5], v[4:5], v[6:7]
	v_cvt_pk_bf16_f32 v2, v2, v3
	v_cvt_pk_bf16_f32 v3, v4, v5
	ds_write2_b64 v151, v[0:1], v[2:3] offset0:12 offset1:14
	s_waitcnt lgkmcnt(0)
	ds_read_b128 v[0:3], v189
	v_add_u32_e32 v12, v151, v186
	ds_read_b128 v[4:7], v12
	ds_read_b128 v[8:11], v189 offset:32
	ds_read_b128 v[130:133], v12 offset:32
	s_waitcnt lgkmcnt(2)
	v_mfma_f32_32x32x16_bf16 v[32:47], v[0:3], v[4:7], 0
	s_lshl_b32 s0, s17, 1
	s_add_i32 s0, s0, s6
	s_lshl_b32 s1, vcc_lo, 2
	s_mul_i32 s84, s0, 0x60
	s_add_i32 s16, s1, 0
	s_lshl_b32 s0, s84, 2
	s_add_i32 s16, s16, s0
	s_waitcnt lgkmcnt(0)
	v_mfma_f32_32x32x16_bf16 v[32:47], v[8:11], v[130:133], v[32:47]
	ds_read_b128 v[0:3], v189 offset:64
	ds_read_b128 v[126:129], v12 offset:64
	ds_read_b128 v[8:11], v189 offset:96
	ds_read_b128 v[118:121], v12 offset:96
	s_add_i32 s16, s16, 0x20400
	s_and_b64 s[0:1], s[60:61], exec
	v_readlane_b32 s0, v253, 42
	v_readlane_b32 s1, v253, 43
	s_movk_i32 s17, 0x140
	s_waitcnt lgkmcnt(2)
	v_mfma_f32_32x32x16_bf16 v[32:47], v[0:3], v[126:129], v[32:47]
	s_waitcnt lgkmcnt(0)
	v_mfma_f32_32x32x16_bf16 v[32:47], v[8:11], v[118:121], v[32:47]
	ds_read_b128 v[0:3], v190
	ds_read_b128 v[122:125], v191 offset:27648
	ds_read_b128 v[8:11], v190 offset:32
	ds_read_b128 v[12:15], v190 offset:64
	ds_read_b128 v[114:117], v191 offset:27680
	ds_read_b128 v[110:113], v191 offset:27712
	s_waitcnt lgkmcnt(4)
	v_mfma_f32_32x32x16_bf16 v[32:47], v[0:3], v[122:125], v[32:47]
	s_waitcnt lgkmcnt(1)
	v_mfma_f32_32x32x16_bf16 v[32:47], v[8:11], v[114:117], v[32:47]
	s_waitcnt lgkmcnt(0)
	v_mfma_f32_32x32x16_bf16 v[32:47], v[12:15], v[110:113], v[32:47]
	ds_read_b128 v[0:3], v192
	ds_read_b128 v[106:109], v193 offset:27648
	ds_read_b128 v[8:11], v192 offset:32
	ds_read_b128 v[12:15], v192 offset:64
	ds_read_b128 v[102:105], v193 offset:27680
	ds_read_b128 v[98:101], v193 offset:27712
	s_waitcnt lgkmcnt(4)
	v_mfma_f32_32x32x16_bf16 v[32:47], v[0:3], v[106:109], v[32:47]
	s_waitcnt lgkmcnt(1)
	v_mfma_f32_32x32x16_bf16 v[32:47], v[8:11], v[102:105], v[32:47]
	ds_read_b128 v[0:3], v189 offset:4608
	ds_read_b128 v[8:11], v189 offset:4640
	s_waitcnt lgkmcnt(1)
	v_mfma_f32_32x32x16_bf16 v[16:31], v[0:3], v[4:7], 0
	s_waitcnt lgkmcnt(0)
	v_mfma_f32_32x32x16_bf16 v[16:31], v[8:11], v[130:133], v[16:31]
	ds_read_b128 v[0:3], v189 offset:4672
	ds_read_b128 v[8:11], v189 offset:4704
	s_waitcnt lgkmcnt(1)
	v_mfma_f32_32x32x16_bf16 v[16:31], v[0:3], v[126:129], v[16:31]
	s_waitcnt lgkmcnt(0)
	v_mfma_f32_32x32x16_bf16 v[16:31], v[8:11], v[118:121], v[16:31]
	ds_read_b128 v[0:3], v198
	ds_read_b128 v[8:11], v198 offset:32
	s_waitcnt lgkmcnt(1)
	v_mfma_f32_32x32x16_bf16 v[16:31], v[0:3], v[122:125], v[16:31]
	s_waitcnt lgkmcnt(0)
	v_mfma_f32_32x32x16_bf16 v[16:31], v[8:11], v[114:117], v[16:31]
	ds_read_b128 v[0:3], v198 offset:64
	ds_read_b128 v[8:11], v199
	s_waitcnt lgkmcnt(1)
	v_mfma_f32_32x32x16_bf16 v[16:31], v[0:3], v[110:113], v[16:31]
	s_waitcnt lgkmcnt(0)
	v_mfma_f32_32x32x16_bf16 v[16:31], v[8:11], v[106:109], v[16:31]
	ds_read_b128 v[0:3], v199 offset:32
	ds_read_b128 v[8:11], v199 offset:64
	s_waitcnt lgkmcnt(1)
	v_mfma_f32_32x32x16_bf16 v[16:31], v[0:3], v[102:105], v[16:31]
	ds_read_b128 v[0:3], v189 offset:9216
	ds_read_b128 v[134:137], v189 offset:9248
	v_mfma_f32_32x32x16_bf16 v[32:47], v[12:15], v[98:101], v[32:47]
	s_waitcnt lgkmcnt(2)
	v_mfma_f32_32x32x16_bf16 v[16:31], v[8:11], v[98:101], v[16:31]
	s_nop 9
	v_add_f32_e32 v202, 0, v32
	v_add_f32_e32 v202, v33, v202
	v_add_f32_e32 v202, v34, v202
	v_add_f32_e32 v202, v35, v202
	s_waitcnt lgkmcnt(1)
	v_mfma_f32_32x32x16_bf16 v[0:15], v[0:3], v[4:7], 0
	s_waitcnt lgkmcnt(0)
	v_mfma_f32_32x32x16_bf16 v[0:15], v[134:137], v[130:133], v[0:15]
	ds_read_b128 v[130:133], v189 offset:9280
	ds_read_b128 v[134:137], v189 offset:9312
	s_waitcnt lgkmcnt(1)
	v_mfma_f32_32x32x16_bf16 v[0:15], v[130:133], v[126:129], v[0:15]
	s_waitcnt lgkmcnt(0)
	v_mfma_f32_32x32x16_bf16 v[0:15], v[134:137], v[118:121], v[0:15]
	ds_read_b128 v[118:121], v200
	ds_read_b128 v[126:129], v200 offset:32
	s_waitcnt lgkmcnt(1)
	v_mfma_f32_32x32x16_bf16 v[0:15], v[118:121], v[122:125], v[0:15]
	ds_read_b128 v[118:121], v200 offset:64
	ds_read_b128 v[122:125], v201
	ds_read_b128 v[130:133], v201 offset:32
	ds_read_b128 v[134:137], v201 offset:64
	s_waitcnt lgkmcnt(4)
	v_mfma_f32_32x32x16_bf16 v[0:15], v[126:129], v[114:117], v[0:15]
	v_add_f32_e32 v114, v36, v202
	v_add_f32_e32 v114, v37, v114
	v_add_f32_e32 v114, v38, v114
	v_add_f32_e32 v114, v39, v114
	v_add_f32_e32 v114, v40, v114
	v_add_f32_e32 v114, v41, v114
	v_add_f32_e32 v114, v42, v114
	s_waitcnt lgkmcnt(3)
	v_mfma_f32_32x32x16_bf16 v[0:15], v[118:121], v[110:113], v[0:15]
	v_add_f32_e32 v110, v43, v114
	v_add_f32_e32 v110, v44, v110
	v_add_f32_e32 v110, v45, v110
	v_add_f32_e32 v110, v46, v110
	v_add_f32_e32 v110, v47, v110
	v_add_f32_e32 v110, v110, v16
	v_add_f32_e32 v110, v17, v110
	s_waitcnt lgkmcnt(2)
	v_mfma_f32_32x32x16_bf16 v[0:15], v[122:125], v[106:109], v[0:15]
	v_add_f32_e32 v106, v18, v110
	v_add_f32_e32 v106, v19, v106
	v_add_f32_e32 v106, v20, v106
	v_add_f32_e32 v106, v21, v106
	v_add_f32_e32 v106, v22, v106
	v_add_f32_e32 v106, v23, v106
	v_add_f32_e32 v106, v24, v106
	s_waitcnt lgkmcnt(1)
	v_mfma_f32_32x32x16_bf16 v[0:15], v[130:133], v[102:105], v[0:15]
	v_add_f32_e32 v102, v25, v106
	v_add_f32_e32 v102, v26, v102
	v_add_f32_e32 v102, v27, v102
	v_add_f32_e32 v102, v28, v102
	v_add_f32_e32 v102, v29, v102
	v_add_f32_e32 v102, v30, v102
	v_add_f32_e32 v102, v31, v102
	s_waitcnt lgkmcnt(0)
	v_mfma_f32_32x32x16_bf16 v[0:15], v[134:137], v[98:101], v[0:15]
	v_lshlrev_b32_e32 v121, 2, v48
	s_nop 10
	v_add_f32_e32 v98, v102, v0
	v_add_f32_e32 v98, v1, v98
	v_add_f32_e32 v98, v2, v98
	v_add_f32_e32 v98, v3, v98
	v_add_f32_e32 v98, v4, v98
	v_add_f32_e32 v98, v5, v98
	v_add_f32_e32 v98, v6, v98
	v_add_f32_e32 v98, v7, v98
	v_add_f32_e32 v98, v8, v98
	v_add_f32_e32 v98, v9, v98
	v_add_f32_e32 v98, v10, v98
	v_add_f32_e32 v98, v11, v98
	v_add_f32_e32 v98, v12, v98
	v_add_f32_e32 v98, v13, v98
	v_add_f32_e32 v98, v14, v98
	v_add_f32_e32 v98, v15, v98
	ds_bpermute_b32 v48, v121, v98
	s_waitcnt lgkmcnt(0)
	v_add_f32_e32 v48, v98, v48
	v_lshlrev_b64 v[98:99], 11, v[182:183]
	v_lshl_add_u64 v[98:99], s[0:1], 0, v[98:99]
	s_movk_i32 s0, 0x780
	s_cselect_b32 s0, 0x300, s0
	s_ashr_i32 vcc_hi, vcc_lo, 31
	s_add_i32 s0, s84, s0
	v_lshl_add_u64 v[98:99], vcc, 1, v[98:99]
	s_ashr_i32 s85, s84, 31
	s_ashr_i32 s0, s0, 3
	v_mul_f32_e32 v48, 0x3c2aaaab, v48
	v_lshl_add_u64 v[114:115], s[84:85], 1, v[98:99]
	v_mov_b32_e32 v98, s0
	s_ashr_i32 s0, s0, 31
	v_cndmask_b32_e64 v120, 0, v48, s[60:61]
	v_mov_b32_e32 v99, s0
	v_alignbit_b32 v48, v183, v182, 6
	v_mad_u64_u32 v[98:99], s[0:1], v48, s17, v[98:99]
	v_mov_b32_e32 v48, v99
	v_lshrrev_b32_e32 v99, 6, v183
	v_mad_u64_u32 v[100:101], s[0:1], v99, s17, v[48:49]
	v_mov_b32_e32 v99, v100
	v_lshlrev_b64 v[98:99], 10, v[98:99]
	v_lshlrev_b32_e32 v48, 4, v182
	v_lshl_add_u64 v[98:99], s[70:71], 0, v[98:99]
	v_and_b32_e32 v48, 0x3f0, v48
	v_lshl_add_u64 v[98:99], v[98:99], 0, v[48:49]
	v_lshlrev_b32_e32 v48, 1, v156
	v_lshl_add_u64 v[102:103], v[98:99], 0, v[48:49]
	s_waitcnt vmcnt(0)
	v_lshrrev_b32_e32 v98, 6, v224
	v_mul_u32_u24_e32 v98, 0x1400, v98
	v_and_b32_e32 v100, 63, v224
	v_lshl_add_u32 v98, v100, 4, v98
	v_add_u32_e32 v98, 0x21000, v98
	ds_write_b128 v98, v[50:53]
	ds_write_b128 v98, v[54:57] offset:1024
	ds_write_b128 v98, v[58:61] offset:2048
	ds_write_b128 v98, v[62:65] offset:3072
	ds_write_b128 v98, v[66:69] offset:4096
	v_add_co_u32_e32 v104, vcc, 0x1000, v102
	s_nop 1
	v_addc_co_u32_e32 v105, vcc, 0, v103, vcc
	v_add_co_u32_e32 v106, vcc, 0x2000, v102
	s_nop 1
	v_addc_co_u32_e32 v107, vcc, 0, v103, vcc
	global_load_dwordx2 v[98:99], v[102:103], off
	global_load_dwordx2 v[100:101], v[102:103], off offset:1024
	global_load_dwordx2 v[50:51], v[102:103], off offset:2048
	global_load_dwordx2 v[52:53], v[102:103], off offset:3072
	global_load_dwordx2 v[54:55], v[104:105], off
	global_load_dwordx2 v[56:57], v[104:105], off offset:1024
	global_load_dwordx2 v[58:59], v[104:105], off offset:2048
	global_load_dwordx2 v[60:61], v[104:105], off offset:3072
	global_load_dwordx2 v[62:63], v[106:107], off
	global_load_dwordx2 v[64:65], v[106:107], off offset:1024
	global_load_dwordx2 v[66:67], v[106:107], off offset:2048
	global_load_dwordx2 v[68:69], v[106:107], off offset:3072
	v_pk_add_f32 v[204:205], v[32:33], v[120:121] op_sel_hi:[1,0] neg_lo:[0,1] neg_hi:[0,1]
	v_pk_add_f32 v[110:111], v[38:39], v[120:121] op_sel_hi:[1,0] neg_lo:[0,1] neg_hi:[0,1]
	v_pk_mul_f32 v[206:207], v[204:205], v[204:205]
	v_pk_add_f32 v[118:119], v[36:37], v[120:121] op_sel_hi:[1,0] neg_lo:[0,1] neg_hi:[0,1]
	v_pk_add_f32 v[108:109], v[40:41], v[120:121] op_sel_hi:[1,0] neg_lo:[0,1] neg_hi:[0,1]
	v_pk_add_f32 v[46:47], v[46:47], v[120:121] op_sel_hi:[1,0] neg_lo:[0,1] neg_hi:[0,1]
	v_pk_add_f32 v[38:39], v[22:23], v[120:121] op_sel_hi:[1,0] neg_lo:[0,1] neg_hi:[0,1]
	v_pk_add_f32 v[40:41], v[20:21], v[120:121] op_sel_hi:[1,0] neg_lo:[0,1] neg_hi:[0,1]
	v_pk_add_f32 v[32:33], v[26:27], v[120:121] op_sel_hi:[1,0] neg_lo:[0,1] neg_hi:[0,1]
	v_pk_add_f32 v[30:31], v[30:31], v[120:121] op_sel_hi:[1,0] neg_lo:[0,1] neg_hi:[0,1]
	v_pk_add_f32 v[28:29], v[28:29], v[120:121] op_sel_hi:[1,0] neg_lo:[0,1] neg_hi:[0,1]
	v_pk_add_f32 v[26:27], v[0:1], v[120:121] op_sel_hi:[1,0] neg_lo:[0,1] neg_hi:[0,1]
	v_pk_add_f32 v[20:21], v[6:7], v[120:121] op_sel_hi:[1,0] neg_lo:[0,1] neg_hi:[0,1]
	v_pk_add_f32 v[22:23], v[4:5], v[120:121] op_sel_hi:[1,0] neg_lo:[0,1] neg_hi:[0,1]
	v_pk_mul_f32 v[36:37], v[118:119], v[118:119]
	v_pk_mul_f32 v[208:209], v[110:111], v[110:111]
	v_pk_mul_f32 v[212:213], v[108:109], v[108:109]
	v_pk_mul_f32 v[214:215], v[46:47], v[46:47]
	v_pk_mul_f32 v[220:221], v[40:41], v[40:41]
	v_pk_mul_f32 v[218:219], v[38:39], v[38:39]
	v_pk_mul_f32 v[222:223], v[32:33], v[32:33]
	v_pk_mul_f32 v[246:247], v[28:29], v[28:29]
	v_pk_mul_f32 v[244:245], v[30:31], v[30:31]
	v_pk_mul_f32 v[0:1], v[26:27], v[26:27]
	v_pk_mul_f32 v[4:5], v[22:23], v[22:23]
	v_pk_mul_f32 v[6:7], v[20:21], v[20:21]
	s_waitcnt vmcnt(11)
	v_lshlrev_b32_e32 v234, 16, v98
	v_and_b32_e32 v235, 0xffff0000, v98
	v_mul_f32_e32 v98, 0xbfb8aa3b, v234
	v_exp_f32_e32 v104, v98
	v_mul_f32_e32 v98, 0xbfb8aa3b, v235
	v_exp_f32_e32 v105, v98
	v_lshlrev_b32_e32 v250, 16, v99
	v_and_b32_e32 v251, 0xffff0000, v99
	v_mul_f32_e32 v99, 0xbfb8aa3b, v251
	v_pk_add_f32 v[122:123], v[104:105], 1.0 op_sel_hi:[1,0]
	v_exp_f32_e32 v99, v99
	s_waitcnt vmcnt(10)
	v_lshlrev_b32_e32 v126, 16, v100
	v_and_b32_e32 v127, 0xffff0000, v100
	v_lshlrev_b32_e32 v130, 16, v101
	v_and_b32_e32 v131, 0xffff0000, v101
	v_mul_f32_e32 v98, 0xbfb8aa3b, v250
	v_exp_f32_e32 v98, v98
	s_nop 0
	v_pk_add_f32 v[124:125], v[98:99], 1.0 op_sel_hi:[1,0]
	s_nop 0
	s_nop 0
	s_nop 0
	v_mul_f32_e32 v98, 0xbfb8aa3b, v126
	v_mul_f32_e32 v99, 0xbfb8aa3b, v127
	v_exp_f32_e32 v98, v98
	v_exp_f32_e32 v99, v99
	v_pk_add_f32 v[106:107], v[42:43], v[120:121] op_sel_hi:[1,0] neg_lo:[0,1] neg_hi:[0,1]
	v_pk_add_f32 v[42:43], v[18:19], v[120:121] op_sel_hi:[1,0] neg_lo:[0,1] neg_hi:[0,1]
	v_pk_mul_f32 v[210:211], v[106:107], v[106:107]
	v_pk_add_f32 v[112:113], v[98:99], 1.0 op_sel_hi:[1,0]
	v_pk_mul_f32 v[18:19], v[42:43], v[42:43]
	s_nop 0
	v_rcp_f32_e32 v128, v113
	s_nop 0
	v_mul_f32_e32 v127, v127, v128
	v_mul_f32_e32 v98, 0xbfb8aa3b, v130
	v_mul_f32_e32 v99, 0xbfb8aa3b, v131
	v_exp_f32_e32 v98, v98
	v_exp_f32_e32 v99, v99
	v_rcp_f32_e32 v129, v112
	s_nop 0
	v_mul_f32_e32 v126, v126, v129
	v_pk_add_f32 v[116:117], v[98:99], 1.0 op_sel_hi:[1,0]
	s_nop 0
	s_nop 0
	s_mov_b64 s[0:1], 0x2db14200
	v_rcp_f32_e32 v132, v117
	s_nop 0
	v_mul_f32_e32 v117, v131, v132
	v_pk_add_f32 v[100:101], v[10:11], v[120:121] op_sel_hi:[1,0] neg_lo:[0,1] neg_hi:[0,1]
	v_pk_add_f32 v[10:11], v[34:35], v[120:121] op_sel_hi:[1,0] neg_lo:[0,1] neg_hi:[0,1]
	v_pk_add_f32 v[98:99], v[12:13], v[120:121] op_sel_hi:[1,0] neg_lo:[0,1] neg_hi:[0,1]
	v_pk_add_f32 v[12:13], v[14:15], v[120:121] op_sel_hi:[1,0] neg_lo:[0,1] neg_hi:[0,1]
	v_pk_mul_f32 v[202:203], v[10:11], v[10:11]
	v_pk_add_f32 v[104:105], v[44:45], v[120:121] op_sel_hi:[1,0] neg_lo:[0,1] neg_hi:[0,1]
	v_pk_add_f32 v[44:45], v[16:17], v[120:121] op_sel_hi:[1,0] neg_lo:[0,1] neg_hi:[0,1]
	v_pk_add_f32 v[34:35], v[24:25], v[120:121] op_sel_hi:[1,0] neg_lo:[0,1] neg_hi:[0,1]
	v_pk_add_f32 v[24:25], v[2:3], v[120:121] op_sel_hi:[1,0] neg_lo:[0,1] neg_hi:[0,1]
	v_pk_add_f32 v[14:15], v[8:9], v[120:121] op_sel_hi:[1,0] neg_lo:[0,1] neg_hi:[0,1]
	v_add_f32_e32 v120, v206, v207
	v_add_f32_e32 v120, v202, v120
	v_add_f32_e32 v120, v203, v120
	v_add_f32_e32 v36, v36, v120
	v_add_f32_e32 v36, v37, v36
	v_add_f32_e32 v36, v208, v36
	v_add_f32_e32 v36, v209, v36
	v_add_f32_e32 v36, v212, v36
	v_add_f32_e32 v36, v213, v36
	v_add_f32_e32 v36, v210, v36
	v_pk_mul_f32 v[216:217], v[104:105], v[104:105]
	v_add_f32_e32 v36, v211, v36
	v_add_f32_e32 v36, v216, v36
	v_add_f32_e32 v36, v217, v36
	v_add_f32_e32 v36, v214, v36
	v_pk_mul_f32 v[16:17], v[44:45], v[44:45]
	v_add_f32_e32 v36, v215, v36
	v_add_f32_e32 v16, v16, v36
	v_add_f32_e32 v16, v17, v16
	v_add_f32_e32 v16, v18, v16
	v_add_f32_e32 v16, v19, v16
	v_add_f32_e32 v16, v220, v16
	v_add_f32_e32 v16, v221, v16
	v_add_f32_e32 v16, v218, v16
	v_pk_mul_f32 v[242:243], v[34:35], v[34:35]
	v_add_f32_e32 v16, v219, v16
	v_add_f32_e32 v16, v242, v16
	v_add_f32_e32 v16, v243, v16
	v_add_f32_e32 v16, v222, v16
	v_add_f32_e32 v16, v223, v16
	v_add_f32_e32 v16, v246, v16
	v_add_f32_e32 v16, v247, v16
	v_add_f32_e32 v16, v244, v16
	v_add_f32_e32 v16, v245, v16
	v_add_f32_e32 v0, v0, v16
	v_pk_mul_f32 v[2:3], v[24:25], v[24:25]
	v_add_f32_e32 v0, v1, v0
	v_add_f32_e32 v0, v2, v0
	v_add_f32_e32 v0, v3, v0
	v_add_f32_e32 v0, v4, v0
	v_add_f32_e32 v0, v5, v0
	v_add_f32_e32 v0, v6, v0
	v_pk_mul_f32 v[8:9], v[14:15], v[14:15]
	v_add_f32_e32 v0, v7, v0
	v_add_f32_e32 v0, v8, v0
	v_pk_mul_f32 v[134:135], v[100:101], v[100:101]
	v_add_f32_e32 v0, v9, v0
	v_add_f32_e32 v0, v134, v0
	v_pk_mul_f32 v[136:137], v[98:99], v[98:99]
	v_add_f32_e32 v0, v135, v0
	v_add_f32_e32 v0, v136, v0
	v_pk_mul_f32 v[182:183], v[12:13], v[12:13]
	v_add_f32_e32 v0, v137, v0
	v_add_f32_e32 v0, v182, v0
	v_add_f32_e32 v0, v183, v0
	ds_bpermute_b32 v1, v121, v0
	v_lshl_add_u32 v19, v156, 2, s16
	ds_read_b128 v[4:7], v19
	v_lshl_add_u64 v[36:37], v[114:115], 0, s[0:1]
	v_rcp_f32_e32 v248, v123
	s_nop 0
	v_mul_f32_e32 v115, v235, v248
	s_waitcnt lgkmcnt(1)
	v_add_f32_e32 v0, v0, v1
	v_fmamk_f32 v0, v0, 0x3c2aaaab, v232
	v_mul_f32_e32 v1, 0x4b800000, v0
	v_cmp_gt_f32_e32 vcc, s92, v0
	v_rcp_f32_e32 v249, v122
	s_nop 0
	v_mul_f32_e32 v114, v234, v249
	v_rcp_f32_e32 v233, v125
	s_nop 0
	v_mul_f32_e32 v9, v251, v233
	v_cndmask_b32_e32 v0, v0, v1, vcc
	v_rsq_f32_e32 v0, v0
	v_rcp_f32_e32 v238, v124
	s_nop 0
	v_mul_f32_e32 v8, v250, v238
	v_lshl_add_u64 v[16:17], v[36:37], 0, v[48:49]
	v_rcp_f32_e32 v133, v116
	s_nop 0
	v_mul_f32_e32 v116, v130, v133
	v_mul_f32_e32 v1, 0x45800000, v0
	v_cndmask_b32_e32 v18, v0, v1, vcc
	v_pk_mul_f32 v[120:121], v[204:205], v[18:19] op_sel_hi:[1,0]
	v_pk_mul_f32 v[10:11], v[10:11], v[18:19] op_sel_hi:[1,0]
	s_waitcnt lgkmcnt(0)
	v_pk_mul_f32 v[4:5], v[4:5], v[120:121]
	v_pk_mul_f32 v[6:7], v[6:7], v[10:11]
	v_pk_mul_f32 v[4:5], v[114:115], v[4:5]
	v_pk_mul_f32 v[6:7], v[8:9], v[6:7]
	v_cvt_pk_bf16_f32 v4, v4, v5
	v_cvt_pk_bf16_f32 v5, v6, v7
	v_and_b32_e32 v214, 32, v224
	v_lshrrev_b32_e32 v214, 2, v214
	v_mov_b32_e32 v215, 0
	v_mov_b32_e32 v208, v4
	v_mov_b32_e32 v209, v5
	v_lshl_add_u64 v[212:213], v[16:17], 0, v[214:215]
	ds_read_b128 v[0:3], v19 offset:256
	v_pk_mul_f32 v[118:119], v[118:119], v[18:19] op_sel_hi:[1,0]
	v_pk_mul_f32 v[110:111], v[110:111], v[18:19] op_sel_hi:[1,0]
	v_lshlrev_b32_e32 v48, 1, v158
	v_lshl_add_u64 v[112:113], v[36:37], 0, v[48:49]
	v_pk_mul_f32 v[108:109], v[108:109], v[18:19] op_sel_hi:[1,0]
	v_pk_mul_f32 v[106:107], v[106:107], v[18:19] op_sel_hi:[1,0]
	v_pk_mul_f32 v[46:47], v[46:47], v[18:19] op_sel_hi:[1,0]
	v_pk_mul_f32 v[44:45], v[44:45], v[18:19] op_sel_hi:[1,0]
	v_pk_mul_f32 v[42:43], v[42:43], v[18:19] op_sel_hi:[1,0]
	v_pk_mul_f32 v[38:39], v[38:39], v[18:19] op_sel_hi:[1,0]
	v_pk_mul_f32 v[34:35], v[34:35], v[18:19] op_sel_hi:[1,0]
	v_pk_mul_f32 v[32:33], v[32:33], v[18:19] op_sel_hi:[1,0]
	v_pk_mul_f32 v[28:29], v[28:29], v[18:19] op_sel_hi:[1,0]
	v_pk_mul_f32 v[30:31], v[30:31], v[18:19] op_sel_hi:[1,0]
	v_pk_mul_f32 v[26:27], v[26:27], v[18:19] op_sel_hi:[1,0]
	v_pk_mul_f32 v[22:23], v[22:23], v[18:19] op_sel_hi:[1,0]
	v_pk_mul_f32 v[20:21], v[20:21], v[18:19] op_sel_hi:[1,0]
	s_waitcnt vmcnt(9)
	v_mov_b32_e32 v4, v50
	v_mov_b32_e32 v5, v51
	v_lshlrev_b32_e32 v134, 16, v4
	v_and_b32_e32 v135, 0xffff0000, v4
	v_mul_f32_e32 v4, 0xbfb8aa3b, v134
	v_exp_f32_e32 v6, v4
	v_mul_f32_e32 v4, 0xbfb8aa3b, v135
	v_exp_f32_e32 v7, v4
	v_lshlrev_b32_e32 v182, 16, v5
	v_and_b32_e32 v183, 0xffff0000, v5
	v_mul_f32_e32 v5, 0xbfb8aa3b, v183
	v_pk_add_f32 v[122:123], v[6:7], 1.0 op_sel_hi:[1,0]
	v_exp_f32_e32 v5, v5
	s_nop 0
	s_nop 0
	v_mul_f32_e32 v4, 0xbfb8aa3b, v182
	v_exp_f32_e32 v4, v4
	s_nop 0
	v_pk_add_f32 v[124:125], v[4:5], 1.0 op_sel_hi:[1,0]
	s_nop 0
	s_nop 0
	s_movk_i32 s0, 0x1000
	v_lshl_add_u32 v4, v158, 2, s16
	ds_read_b128 v[8:11], v4
	v_add_co_u32_e32 v120, vcc, s0, v102
	s_movk_i32 s0, 0x2000
	s_nop 0
	v_addc_co_u32_e32 v121, vcc, 0, v103, vcc
	s_waitcnt lgkmcnt(0)
	v_pk_mul_f32 v[8:9], v[8:9], v[118:119]
	v_pk_mul_f32 v[10:11], v[10:11], v[110:111]
	v_pk_mul_f32 v[8:9], v[126:127], v[8:9]
	v_pk_mul_f32 v[10:11], v[116:117], v[10:11]
	v_cvt_pk_bf16_f32 v8, v8, v9
	v_cvt_pk_bf16_f32 v9, v10, v11
	v_mov_b32_e32 v210, v8
	v_mov_b32_e32 v211, v9
	s_nop 1
	v_permlane32_swap_b32 v208, v210
	v_permlane32_swap_b32 v209, v211
	s_nop 1
	global_store_dwordx4 v[212:213], v[208:211], off
	v_add_co_u32_e32 v114, vcc, s0, v102
	ds_read_b128 v[4:7], v19 offset:352
	s_nop 0
	v_addc_co_u32_e32 v115, vcc, 0, v103, vcc
	v_pk_mul_f32 v[0:1], v[0:1], v[26:27]
	s_waitcnt vmcnt(9)
	v_mov_b32_e32 v8, v52
	v_mov_b32_e32 v9, v53
	v_lshlrev_b32_e32 v126, 16, v8
	v_and_b32_e32 v127, 0xffff0000, v8
	v_mul_f32_e32 v8, 0xbfb8aa3b, v126
	v_exp_f32_e32 v10, v8
	v_mul_f32_e32 v8, 0xbfb8aa3b, v127
	v_exp_f32_e32 v11, v8
	v_lshlrev_b32_e32 v130, 16, v9
	v_and_b32_e32 v131, 0xffff0000, v9
	v_mul_f32_e32 v9, 0xbfb8aa3b, v131
	v_pk_add_f32 v[102:103], v[10:11], 1.0 op_sel_hi:[1,0]
	v_exp_f32_e32 v9, v9
	s_nop 0
	v_rcp_f32_e32 v128, v103
	s_nop 0
	v_mul_f32_e32 v103, v127, v128
	v_mul_f32_e32 v8, 0xbfb8aa3b, v130
	v_exp_f32_e32 v8, v8
	v_rcp_f32_e32 v129, v102
	s_nop 0
	v_mul_f32_e32 v102, v126, v129
	v_pk_add_f32 v[116:117], v[8:9], 1.0 op_sel_hi:[1,0]
	s_nop 0
	s_nop 0
	s_nop 0
	v_lshl_add_u32 v8, v160, 2, s16
	ds_read_b128 v[8:11], v8
	v_lshlrev_b32_e32 v48, 1, v160
	v_lshl_add_u64 v[118:119], v[36:37], 0, v[48:49]
	v_lshl_add_u32 v48, v162, 2, s16
	ds_read_b128 v[110:113], v48
	s_waitcnt lgkmcnt(1)
	v_pk_mul_f32 v[8:9], v[8:9], v[108:109]
	v_rcp_f32_e32 v136, v123
	s_nop 0
	v_mul_f32_e32 v109, v135, v136
	v_rcp_f32_e32 v137, v122
	s_nop 0
	v_mul_f32_e32 v108, v134, v137
	v_pk_mul_f32 v[10:11], v[10:11], v[106:107]
	v_rcp_f32_e32 v202, v125
	s_nop 0
	v_mul_f32_e32 v107, v183, v202
	v_rcp_f32_e32 v203, v124
	s_nop 0
	v_mul_f32_e32 v106, v182, v203
	v_pk_mul_f32 v[8:9], v[108:109], v[8:9]
	v_pk_mul_f32 v[10:11], v[106:107], v[10:11]
	v_cvt_pk_bf16_f32 v8, v8, v9
	v_cvt_pk_bf16_f32 v9, v10, v11
	v_mov_b32_e32 v208, v8
	v_mov_b32_e32 v209, v9
	v_lshl_add_u64 v[212:213], v[118:119], 0, v[214:215]
	s_waitcnt lgkmcnt(0)
	v_pk_mul_f32 v[46:47], v[112:113], v[46:47]
	s_waitcnt vmcnt(8)
	v_mov_b32_e32 v8, v54
	v_mov_b32_e32 v9, v55
	v_lshlrev_b32_e32 v118, 16, v8
	v_and_b32_e32 v119, 0xffff0000, v8
	v_mul_f32_e32 v8, 0xbfb8aa3b, v118
	v_exp_f32_e32 v10, v8
	v_mul_f32_e32 v8, 0xbfb8aa3b, v119
	v_exp_f32_e32 v11, v8
	v_lshlrev_b32_e32 v124, 16, v9
	v_and_b32_e32 v125, 0xffff0000, v9
	v_mul_f32_e32 v9, 0xbfb8aa3b, v125
	v_pk_add_f32 v[106:107], v[10:11], 1.0 op_sel_hi:[1,0]
	v_exp_f32_e32 v9, v9
	s_nop 0
	s_nop 0
	v_mul_f32_e32 v8, 0xbfb8aa3b, v124
	v_exp_f32_e32 v8, v8
	s_nop 0
	v_pk_add_f32 v[108:109], v[8:9], 1.0 op_sel_hi:[1,0]
	s_nop 0
	s_nop 0
	s_nop 0
	v_pk_mul_f32 v[10:11], v[104:105], v[18:19] op_sel_hi:[1,0]
	v_lshlrev_b32_e32 v48, 1, v162
	v_pk_mul_f32 v[10:11], v[110:111], v[10:11]
	v_lshl_add_u64 v[8:9], v[36:37], 0, v[48:49]
	v_pk_mul_f32 v[10:11], v[102:103], v[10:11]
	v_rcp_f32_e32 v132, v117
	s_nop 0
	v_mul_f32_e32 v103, v131, v132
	v_rcp_f32_e32 v133, v116
	s_nop 0
	v_mul_f32_e32 v102, v130, v133
	v_pk_mul_f32 v[46:47], v[102:103], v[46:47]
	v_cvt_pk_bf16_f32 v10, v10, v11
	v_cvt_pk_bf16_f32 v11, v46, v47
	v_mov_b32_e32 v210, v10
	v_mov_b32_e32 v211, v11
	s_nop 1
	v_permlane32_swap_b32 v208, v210
	v_permlane32_swap_b32 v209, v211
	s_nop 1
	global_store_dwordx4 v[212:213], v[208:211], off
	s_waitcnt vmcnt(8)
	v_mov_b32_e32 v8, v56
	v_mov_b32_e32 v9, v57
	v_lshlrev_b32_e32 v116, 16, v8
	v_and_b32_e32 v117, 0xffff0000, v8
	v_mul_f32_e32 v8, 0xbfb8aa3b, v116
	v_exp_f32_e32 v10, v8
	v_mul_f32_e32 v8, 0xbfb8aa3b, v117
	v_exp_f32_e32 v11, v8
	v_lshlrev_b32_e32 v128, 16, v9
	v_and_b32_e32 v129, 0xffff0000, v9
	v_mul_f32_e32 v9, 0xbfb8aa3b, v129
	v_pk_add_f32 v[46:47], v[10:11], 1.0 op_sel_hi:[1,0]
	v_exp_f32_e32 v9, v9
	s_nop 0
	s_nop 0
	v_mul_f32_e32 v8, 0xbfb8aa3b, v128
	v_exp_f32_e32 v8, v8
	s_nop 0
	v_pk_add_f32 v[110:111], v[8:9], 1.0 op_sel_hi:[1,0]
	s_nop 0
	s_nop 0
	s_nop 0
	v_lshl_add_u32 v8, v174, 2, s16
	ds_read_b128 v[8:11], v8
	v_lshlrev_b32_e32 v48, 1, v174
	v_lshl_add_u64 v[112:113], v[36:37], 0, v[48:49]
	v_lshl_add_u32 v48, v176, 2, s16
	ds_read_b128 v[102:105], v48
	s_waitcnt lgkmcnt(1)
	v_pk_mul_f32 v[8:9], v[8:9], v[44:45]
	v_rcp_f32_e32 v122, v107
	s_nop 0
	v_mul_f32_e32 v45, v119, v122
	v_rcp_f32_e32 v123, v106
	s_nop 0
	v_mul_f32_e32 v44, v118, v123
	v_pk_mul_f32 v[10:11], v[10:11], v[42:43]
	v_rcp_f32_e32 v134, v109
	s_nop 0
	v_mul_f32_e32 v43, v125, v134
	v_rcp_f32_e32 v135, v108
	s_nop 0
	v_mul_f32_e32 v42, v124, v135
	v_pk_mul_f32 v[8:9], v[44:45], v[8:9]
	v_pk_mul_f32 v[10:11], v[42:43], v[10:11]
	v_cvt_pk_bf16_f32 v8, v8, v9
	v_cvt_pk_bf16_f32 v9, v10, v11
	v_mov_b32_e32 v208, v8
	v_mov_b32_e32 v209, v9
	v_lshl_add_u64 v[212:213], v[112:113], 0, v[214:215]
	s_waitcnt lgkmcnt(0)
	v_pk_mul_f32 v[38:39], v[104:105], v[38:39]
	s_waitcnt vmcnt(7)
	v_mov_b32_e32 v8, v58
	v_mov_b32_e32 v9, v59
	v_lshlrev_b32_e32 v106, 16, v8
	v_and_b32_e32 v107, 0xffff0000, v8
	v_mul_f32_e32 v8, 0xbfb8aa3b, v106
	v_exp_f32_e32 v10, v8
	v_mul_f32_e32 v8, 0xbfb8aa3b, v107
	v_exp_f32_e32 v11, v8
	v_lshlrev_b32_e32 v112, 16, v9
	v_and_b32_e32 v113, 0xffff0000, v9
	v_mul_f32_e32 v9, 0xbfb8aa3b, v113
	v_pk_add_f32 v[42:43], v[10:11], 1.0 op_sel_hi:[1,0]
	v_exp_f32_e32 v9, v9
	s_nop 0
	s_nop 0
	v_mul_f32_e32 v8, 0xbfb8aa3b, v112
	v_exp_f32_e32 v8, v8
	s_nop 0
	v_pk_add_f32 v[44:45], v[8:9], 1.0 op_sel_hi:[1,0]
	s_nop 0
	s_nop 0
	s_nop 0
	v_pk_mul_f32 v[10:11], v[40:41], v[18:19] op_sel_hi:[1,0]
	v_rcp_f32_e32 v126, v47
	s_nop 0
	v_mul_f32_e32 v41, v117, v126
	v_pk_mul_f32 v[10:11], v[102:103], v[10:11]
	v_rcp_f32_e32 v127, v46
	s_nop 0
	v_mul_f32_e32 v40, v116, v127
	v_pk_mul_f32 v[10:11], v[40:41], v[10:11]
	v_rcp_f32_e32 v130, v111
	s_nop 0
	v_mul_f32_e32 v41, v129, v130
	v_rcp_f32_e32 v131, v110
	s_nop 0
	v_mul_f32_e32 v40, v128, v131
	v_lshlrev_b32_e32 v48, 1, v176
	v_pk_mul_f32 v[38:39], v[40:41], v[38:39]
	v_lshl_add_u64 v[8:9], v[36:37], 0, v[48:49]
	v_cvt_pk_bf16_f32 v10, v10, v11
	v_cvt_pk_bf16_f32 v11, v38, v39
	v_mov_b32_e32 v210, v10
	v_mov_b32_e32 v211, v11
	s_nop 1
	v_permlane32_swap_b32 v208, v210
	v_permlane32_swap_b32 v209, v211
	s_nop 1
	global_store_dwordx4 v[212:213], v[208:211], off
	v_lshlrev_b32_e32 v48, 1, v178
	v_lshl_add_u64 v[104:105], v[36:37], 0, v[48:49]
	s_waitcnt vmcnt(7)
	v_mov_b32_e32 v8, v60
	v_mov_b32_e32 v9, v61
	v_lshlrev_b32_e32 v110, 16, v8
	v_and_b32_e32 v111, 0xffff0000, v8
	v_mul_f32_e32 v8, 0xbfb8aa3b, v110
	v_exp_f32_e32 v10, v8
	v_mul_f32_e32 v8, 0xbfb8aa3b, v111
	v_exp_f32_e32 v11, v8
	v_lshlrev_b32_e32 v120, 16, v9
	v_and_b32_e32 v121, 0xffff0000, v9
	v_mul_f32_e32 v9, 0xbfb8aa3b, v121
	v_pk_add_f32 v[46:47], v[10:11], 1.0 op_sel_hi:[1,0]
	v_exp_f32_e32 v9, v9
	s_nop 0
	s_nop 0
	v_mul_f32_e32 v8, 0xbfb8aa3b, v120
	v_exp_f32_e32 v8, v8
	s_nop 0
	v_pk_add_f32 v[102:103], v[8:9], 1.0 op_sel_hi:[1,0]
	s_nop 0
	s_nop 0
	s_nop 0
	v_lshl_add_u32 v8, v178, 2, s16
	ds_read_b128 v[8:11], v8
	v_lshl_add_u32 v38, v180, 2, s16
	ds_read_b128 v[38:41], v38
	s_waitcnt lgkmcnt(1)
	v_pk_mul_f32 v[8:9], v[8:9], v[34:35]
	v_rcp_f32_e32 v108, v43
	s_nop 0
	v_mul_f32_e32 v35, v107, v108
	v_rcp_f32_e32 v109, v42
	s_nop 0
	v_mul_f32_e32 v34, v106, v109
	v_pk_mul_f32 v[10:11], v[10:11], v[32:33]
	v_rcp_f32_e32 v118, v45
	s_nop 0
	v_mul_f32_e32 v33, v113, v118
	v_rcp_f32_e32 v119, v44
	s_nop 0
	v_mul_f32_e32 v32, v112, v119
	v_pk_mul_f32 v[8:9], v[34:35], v[8:9]
	v_pk_mul_f32 v[10:11], v[32:33], v[10:11]
	v_cvt_pk_bf16_f32 v8, v8, v9
	v_cvt_pk_bf16_f32 v9, v10, v11
	v_mov_b32_e32 v208, v8
	v_mov_b32_e32 v209, v9
	v_lshl_add_u64 v[212:213], v[104:105], 0, v[214:215]
	s_waitcnt lgkmcnt(0)
	v_pk_mul_f32 v[28:29], v[38:39], v[28:29]
	v_pk_mul_f32 v[30:31], v[40:41], v[30:31]
	s_waitcnt vmcnt(6)
	v_mov_b32_e32 v8, v62
	v_mov_b32_e32 v9, v63
	v_lshlrev_b32_e32 v42, 16, v8
	v_and_b32_e32 v43, 0xffff0000, v8
	v_mul_f32_e32 v8, 0xbfb8aa3b, v42
	v_exp_f32_e32 v10, v8
	v_mul_f32_e32 v8, 0xbfb8aa3b, v43
	v_exp_f32_e32 v11, v8
	v_lshlrev_b32_e32 v104, 16, v9
	v_and_b32_e32 v105, 0xffff0000, v9
	v_mul_f32_e32 v9, 0xbfb8aa3b, v105
	v_pk_add_f32 v[10:11], v[10:11], 1.0 op_sel_hi:[1,0]
	v_exp_f32_e32 v9, v9
	s_nop 0
	v_rcp_f32_e32 v44, v11
	s_nop 0
	v_mul_f32_e32 v11, v43, v44
	v_mul_f32_e32 v8, 0xbfb8aa3b, v104
	v_exp_f32_e32 v8, v8
	v_rcp_f32_e32 v45, v10
	s_nop 0
	v_mul_f32_e32 v10, v42, v45
	v_pk_mul_f32 v[0:1], v[10:11], v[0:1]
	v_pk_mul_f32 v[10:11], v[24:25], v[18:19] op_sel_hi:[1,0]
	v_pk_add_f32 v[8:9], v[8:9], 1.0 op_sel_hi:[1,0]
	v_pk_mul_f32 v[2:3], v[2:3], v[10:11]
	v_cvt_pk_bf16_f32 v0, v0, v1
	v_rcp_f32_e32 v106, v9
	s_nop 0
	v_mul_f32_e32 v9, v105, v106
	v_rcp_f32_e32 v116, v47
	s_nop 0
	v_mul_f32_e32 v35, v111, v116
	v_rcp_f32_e32 v117, v46
	s_nop 0
	v_mul_f32_e32 v34, v110, v117
	v_pk_mul_f32 v[28:29], v[34:35], v[28:29]
	v_rcp_f32_e32 v122, v103
	s_nop 0
	v_mul_f32_e32 v35, v121, v122
	v_rcp_f32_e32 v123, v102
	s_nop 0
	v_mul_f32_e32 v34, v120, v123
	v_lshlrev_b32_e32 v48, 1, v180
	v_pk_mul_f32 v[30:31], v[34:35], v[30:31]
	v_lshl_add_u64 v[32:33], v[36:37], 0, v[48:49]
	v_cvt_pk_bf16_f32 v28, v28, v29
	v_cvt_pk_bf16_f32 v29, v30, v31
	v_mov_b32_e32 v210, v28
	v_mov_b32_e32 v211, v29
	s_nop 1
	v_permlane32_swap_b32 v208, v210
	v_permlane32_swap_b32 v209, v211
	s_nop 1
	global_store_dwordx4 v[212:213], v[208:211], off
	v_rcp_f32_e32 v107, v8
	s_nop 0
	v_mul_f32_e32 v8, v104, v107
	v_pk_mul_f32 v[2:3], v[8:9], v[2:3]
	s_waitcnt vmcnt(6)
	v_mov_b32_e32 v28, v64
	v_mov_b32_e32 v29, v65
	v_lshlrev_b32_e32 v32, 16, v28
	v_cvt_pk_bf16_f32 v1, v2, v3
	v_mov_b32_e32 v208, v0
	v_mov_b32_e32 v209, v1
	v_lshl_add_u64 v[212:213], v[16:17], 0, v[214:215]
	v_and_b32_e32 v33, 0xffff0000, v28
	v_mul_f32_e32 v28, 0xbfb8aa3b, v32
	v_exp_f32_e32 v30, v28
	v_mul_f32_e32 v28, 0xbfb8aa3b, v33
	v_exp_f32_e32 v31, v28
	s_waitcnt vmcnt(5)
	v_mov_b32_e32 v0, v66
	v_mov_b32_e32 v1, v67
	v_lshlrev_b32_e32 v44, 16, v1
	v_pk_add_f32 v[30:31], v[30:31], 1.0 op_sel_hi:[1,0]
	v_and_b32_e32 v45, 0xffff0000, v1
	v_mul_f32_e32 v1, 0xbfb8aa3b, v45
	v_exp_f32_e32 v1, v1
	s_nop 0
	v_lshlrev_b32_e32 v36, 16, v29
	v_and_b32_e32 v37, 0xffff0000, v29
	v_mul_f32_e32 v28, 0xbfb8aa3b, v36
	v_mul_f32_e32 v29, 0xbfb8aa3b, v37
	v_exp_f32_e32 v28, v28
	v_exp_f32_e32 v29, v29
	s_nop 0
	v_pk_add_f32 v[28:29], v[28:29], 1.0 op_sel_hi:[1,0]
	s_nop 0
	s_nop 0
	s_nop 0
	v_lshlrev_b32_e32 v40, 16, v0
	v_and_b32_e32 v41, 0xffff0000, v0
	v_mul_f32_e32 v0, 0xbfb8aa3b, v40
	v_exp_f32_e32 v2, v0
	v_mul_f32_e32 v0, 0xbfb8aa3b, v41
	v_exp_f32_e32 v3, v0
	s_nop 0
	v_pk_add_f32 v[24:25], v[2:3], 1.0 op_sel_hi:[1,0]
	s_nop 0
	s_nop 0
	s_nop 0
	v_mul_f32_e32 v0, 0xbfb8aa3b, v44
	v_exp_f32_e32 v0, v0
	s_nop 0
	v_pk_add_f32 v[26:27], v[0:1], 1.0 op_sel_hi:[1,0]
	s_nop 0
	s_nop 0
	s_nop 0
	ds_read_b128 v[0:3], v19 offset:288
	ds_read_b128 v[8:11], v19 offset:320
	s_waitcnt lgkmcnt(1)
	v_pk_mul_f32 v[0:1], v[0:1], v[22:23]
	v_rcp_f32_e32 v34, v31
	s_nop 0
	v_mul_f32_e32 v23, v33, v34
	v_rcp_f32_e32 v35, v30
	s_nop 0
	v_mul_f32_e32 v22, v32, v35
	v_pk_mul_f32 v[2:3], v[2:3], v[20:21]
	v_rcp_f32_e32 v38, v29
	s_nop 0
	v_mul_f32_e32 v21, v37, v38
	v_rcp_f32_e32 v39, v28
	s_nop 0
	v_mul_f32_e32 v20, v36, v39
	v_pk_mul_f32 v[0:1], v[22:23], v[0:1]
	v_pk_mul_f32 v[2:3], v[20:21], v[2:3]
	v_cvt_pk_bf16_f32 v0, v0, v1
	v_cvt_pk_bf16_f32 v1, v2, v3
	v_mov_b32_e32 v210, v0
	v_mov_b32_e32 v211, v1
	s_nop 1
	v_permlane32_swap_b32 v208, v210
	v_permlane32_swap_b32 v209, v211
	s_nop 1
	global_store_dwordx4 v[212:213], v[208:211], off offset:128
	s_waitcnt vmcnt(5)
	v_mov_b32_e32 v0, v68
	v_mov_b32_e32 v1, v69
	v_lshrrev_b32_e32 v124, 6, v224
	v_mul_u32_u24_e32 v124, 0x1400, v124
	v_and_b32_e32 v126, 63, v224
	v_lshl_add_u32 v124, v126, 4, v124
	v_add_u32_e32 v124, 0x21000, v124
	ds_read_b128 v[50:53], v124
	ds_read_b128 v[54:57], v124 offset:1024
	ds_read_b128 v[58:61], v124 offset:2048
	ds_read_b128 v[62:65], v124 offset:3072
	ds_read_b128 v[66:69], v124 offset:4096
	v_lshlrev_b32_e32 v19, 16, v0
	v_and_b32_e32 v20, 0xffff0000, v0
	v_mul_f32_e32 v0, 0xbfb8aa3b, v19
	v_exp_f32_e32 v2, v0
	v_mul_f32_e32 v0, 0xbfb8aa3b, v20
	v_exp_f32_e32 v3, v0
	v_pk_mul_f32 v[14:15], v[14:15], v[18:19] op_sel_hi:[1,0]
	v_pk_add_f32 v[2:3], v[2:3], 1.0 op_sel_hi:[1,0]
	s_nop 0
	s_waitcnt lgkmcnt(0)
	v_pk_mul_f32 v[8:9], v[8:9], v[14:15]
	v_rcp_f32_e32 v42, v25
	s_nop 0
	v_mul_f32_e32 v15, v41, v42
	v_rcp_f32_e32 v43, v24
	s_nop 0
	v_mul_f32_e32 v14, v40, v43
	v_pk_mul_f32 v[8:9], v[14:15], v[8:9]
	v_pk_mul_f32 v[14:15], v[100:101], v[18:19] op_sel_hi:[1,0]
	v_cvt_pk_bf16_f32 v8, v8, v9
	v_lshlrev_b32_e32 v23, 16, v1
	v_and_b32_e32 v28, 0xffff0000, v1
	v_mul_f32_e32 v0, 0xbfb8aa3b, v23
	v_mul_f32_e32 v1, 0xbfb8aa3b, v28
	v_exp_f32_e32 v0, v0
	v_exp_f32_e32 v1, v1
	v_pk_mul_f32 v[10:11], v[10:11], v[14:15]
	v_rcp_f32_e32 v46, v27
	s_nop 0
	v_mul_f32_e32 v15, v45, v46
	v_rcp_f32_e32 v47, v26
	s_nop 0
	v_mul_f32_e32 v14, v44, v47
	v_pk_add_f32 v[0:1], v[0:1], 1.0 op_sel_hi:[1,0]
	v_pk_mul_f32 v[10:11], v[14:15], v[10:11]
	v_cvt_pk_bf16_f32 v9, v10, v11
	v_mov_b32_e32 v208, v8
	v_mov_b32_e32 v209, v9
	v_lshl_add_u64 v[212:213], v[16:17], 0, v[214:215]
	v_pk_mul_f32 v[8:9], v[98:99], v[18:19] op_sel_hi:[1,0]
	v_pk_mul_f32 v[4:5], v[4:5], v[8:9]
	v_rcp_f32_e32 v21, v3
	s_nop 0
	v_mul_f32_e32 v3, v20, v21
	v_rcp_f32_e32 v22, v2
	s_nop 0
	v_mul_f32_e32 v2, v19, v22
	v_pk_mul_f32 v[2:3], v[2:3], v[4:5]
	v_pk_mul_f32 v[4:5], v[12:13], v[18:19] op_sel_hi:[1,0]
	v_rcp_f32_e32 v29, v1
	s_nop 0
	v_mul_f32_e32 v1, v28, v29
	v_pk_mul_f32 v[4:5], v[6:7], v[4:5]
	v_rcp_f32_e32 v30, v0
	s_nop 0
	v_mul_f32_e32 v0, v23, v30
	v_pk_mul_f32 v[0:1], v[0:1], v[4:5]
	v_cvt_pk_bf16_f32 v2, v2, v3
	v_cvt_pk_bf16_f32 v3, v0, v1
	v_mov_b32_e32 v210, v2
	v_mov_b32_e32 v211, v3
	s_nop 1
	v_permlane32_swap_b32 v208, v210
	v_permlane32_swap_b32 v209, v211
	s_nop 1
	global_store_dwordx4 v[212:213], v[208:211], off offset:160
	s_branch .LBB0_855

.LBB0_1048:
	s_waitcnt lgkmcnt(0)
	s_add_u32 s43, s12, 0x85b4000
	s_addc_u32 s44, s13, 0
	s_add_u32 s1, s16, s10
	s_addc_u32 s12, s17, s11
	s_add_u32 s45, s1, 0x580000
	s_addc_u32 s46, s12, 0
	v_readlane_b32 s12, v252, 41
	v_readlane_b32 s13, v252, 42
	s_add_u32 s1, s14, s12
	s_addc_u32 s13, s15, s13
	s_add_u32 s12, s1, 0x12b14000
	s_addc_u32 s13, s13, 0
	v_bfe_u32 v215, v8, 4, 2
	s_add_u32 s14, s6, 0x16b14000
	v_and_b32_e32 v214, 15, v8
	v_lshlrev_b32_e32 v15, 4, v215
	v_lshlrev_b32_e32 v8, 2, v8
	s_addc_u32 s15, s7, 0
	v_lshl_or_b32 v15, v214, 6, v15
	s_lshl_b32 s6, s9, 13
	v_and_b32_e32 v8, 32, v8
	v_bitop3_b32 v16, v15, s6, v8 bitop3:0xde
	s_lshl_b32 s6, s18, 5
	s_and_b32 s48, s6, 0x60
	s_add_i32 m0, s39, 0x18000
	v_lshl_add_u64 v[6:7], v[6:7], 0, s[66:67]
	s_lshl_b32 s47, s9, 6
	s_lshl_b32 s6, s48, 7
	s_waitcnt vmcnt(4)
	s_barrier
	global_load_lds_dwordx4 v[6:7], off
	v_lshl_add_u64 v[4:5], v[4:5], 0, s[66:67]
	s_add_i32 m0, s39, 0x1a000
	s_add_i32 s49, s39, 0x8000
	s_add_i32 s50, s39, 0xa000
	v_bitop3_b32 v216, v15, s6, v8 bitop3:0xde
	global_load_lds_dwordx4 v[4:5], off
	v_lshl_add_u64 v[2:3], v[2:3], 0, s[66:67]
	s_mov_b32 m0, s49
	s_add_u32 s6, s28, 0x40080
	global_load_lds_dwordx4 v[2:3], off
	v_lshl_add_u64 v[0:1], v[0:1], 0, s[66:67]
	s_mov_b32 m0, s50
	s_addc_u32 s7, s29, 0
	global_load_lds_dwordx4 v[0:1], off
	s_add_i32 m0, s39, 0x1c000
	v_lshl_add_u64 v[0:1], s[6:7], 0, v[48:49]
	global_load_lds_dwordx4 v[0:1], off
	v_lshl_add_u64 v[0:1], s[6:7], 0, v[202:203]
	s_add_i32 m0, s39, 0x1e000
	s_mov_b32 s1, 4
	global_load_lds_dwordx4 v[0:1], off
	v_lshlrev_b32_e32 v0, 14, v9
	v_and_b32_e32 v0, 0xffff8000, v0
	v_lshl_add_u32 v0, v10, 11, v0
	v_and_b32_e32 v1, 1, v9
	v_lshl_or_b32 v0, v1, 6, v0
	v_lshl_add_u32 v204, v11, 1, v0
	v_lshlrev_b32_e32 v0, 14, v12
	v_and_b32_e32 v0, 0xffff8000, v0
	s_waitcnt vmcnt(6)
	v_lshl_add_u32 v0, v13, 11, v0
	v_and_b32_e32 v1, 1, v12
	v_lshl_or_b32 v0, v1, 6, v0
	s_mov_b32 s9, s57
	s_lshr_b32 s51, s4, 1
	v_mov_b32_e32 v205, v49
	v_lshl_add_u32 v206, v14, 1, v0
	v_mov_b32_e32 v207, v49
	s_mov_b32 s55, 0
	v_add_u32_e32 v217, 0, v16
	s_mov_b32 s17, 0
	s_mov_b64 s[22:23], s[28:29]
	s_mov_b64 s[20:21], s[24:25]
	s_barrier
	v_lshlrev_b32_e32 v222, 2, v224
	v_add_u32_e32 v222, 0x20000, v222
	ds_write_b32 v222, v196
	ds_write_b32 v222, v197 offset:2048
	ds_write_b32 v222, v225 offset:4096
	ds_write_b32 v222, v226 offset:6144
	ds_write_b32 v222, v227 offset:8192
	ds_write_b32 v222, v228 offset:10240
	ds_write_b32 v222, v229 offset:12288
	ds_write_b32 v222, v230 offset:14336
	ds_write_b32 v222, v231 offset:16384
	ds_write_b32 v222, v232 offset:18432
	ds_write_b32 v222, v236 offset:20480
	ds_write_b32 v222, v237 offset:22528
	ds_write_b32 v222, v239 offset:24576
	ds_write_b32 v222, v240 offset:26624
	s_waitcnt lgkmcnt(0)
	s_branch .LBB0_1050

.LBB0_1060:
	s_mov_b64 exec, 1
	global_load_dwordx4 v[190:193], v[208:209], off
	s_mov_b64 exec, -1
	s_cmp_gt_u32 s55, 1
	s_cselect_b64 s[26:27], -1, 0
	s_cmp_lt_u32 s55, 2
	v_mov_b32_e32 v178, 0
	v_mov_b32_e32 v186, 0
	v_mov_b32_e32 v187, 0
	v_mov_b32_e32 v188, 0
	v_mov_b32_e32 v189, 0
	s_cbranch_scc1 .LBB0_1062
	global_load_dwordx4 v[186:189], v[130:131], off
.LBB0_1062:
	s_mov_b64 exec, 1
	global_load_dwordx4 v[182:185], v[208:209], off offset:256
	s_mov_b64 exec, -1
	v_cndmask_b32_e64 v130, 0, 1, s[26:27]
	v_cmp_ne_u32_e64 s[0:1], 1, v130
	s_andn2_b64 vcc, exec, s[26:27]
	v_mov_b32_e32 v179, 0
	v_mov_b32_e32 v180, 0
	v_mov_b32_e32 v181, 0
	s_cbranch_vccnz .LBB0_1064
	v_add_co_u32_e32 v130, vcc, 0x20000, v208
	s_nop 1
	v_addc_co_u32_e32 v131, vcc, 0, v209, vcc
	global_load_dwordx4 v[178:181], v[130:131], off offset:256
.LBB0_1064:
	v_add_co_u32_e32 v130, vcc, 0x2000, v208
	v_mov_b32_e32 v162, 0
	s_nop 0
	v_addc_co_u32_e32 v131, vcc, 0, v209, vcc
	s_mov_b64 exec, 1
	global_load_dwordx4 v[174:177], v[130:131], off
	s_mov_b64 exec, -1
	s_and_b64 vcc, exec, s[0:1]
	v_mov_b32_e32 v170, 0
	v_mov_b32_e32 v171, 0
	v_mov_b32_e32 v172, 0
	v_mov_b32_e32 v173, 0
	s_cbranch_vccnz .LBB0_1066
	v_add_co_u32_e32 v130, vcc, 0x22000, v208
	s_nop 1
	v_addc_co_u32_e32 v131, vcc, 0, v209, vcc
	global_load_dwordx4 v[170:173], v[130:131], off
.LBB0_1066:
	v_add_co_u32_e32 v130, vcc, 0x2000, v208
	v_mov_b32_e32 v163, 0
	s_nop 0
	v_addc_co_u32_e32 v131, vcc, 0, v209, vcc
	s_mov_b64 exec, 1
	global_load_dwordx4 v[166:169], v[130:131], off offset:256
	s_mov_b64 exec, -1
	s_and_b64 vcc, exec, s[0:1]
	v_mov_b32_e32 v164, 0
	v_mov_b32_e32 v165, 0
	s_cbranch_vccnz .LBB0_1068
	v_add_co_u32_e32 v130, vcc, 0x22000, v208
	s_nop 1
	v_addc_co_u32_e32 v131, vcc, 0, v209, vcc
	global_load_dwordx4 v[162:165], v[130:131], off offset:256
.LBB0_1068:
	v_add_co_u32_e32 v130, vcc, 0x4000, v208
	v_mov_b32_e32 v146, 0
	s_nop 0
	v_addc_co_u32_e32 v131, vcc, 0, v209, vcc
	s_mov_b64 exec, 1
	global_load_dwordx4 v[158:161], v[130:131], off
	s_mov_b64 exec, -1
	s_and_b64 vcc, exec, s[0:1]
	v_mov_b32_e32 v154, 0
	v_mov_b32_e32 v155, 0
	v_mov_b32_e32 v156, 0
	v_mov_b32_e32 v157, 0
	s_cbranch_vccnz .LBB0_1070
	v_add_co_u32_e32 v130, vcc, 0x24000, v208
	s_nop 1
	v_addc_co_u32_e32 v131, vcc, 0, v209, vcc
	global_load_dwordx4 v[154:157], v[130:131], off
.LBB0_1070:
	v_add_co_u32_e32 v130, vcc, 0x4000, v208
	v_mov_b32_e32 v147, 0
	s_nop 0
	v_addc_co_u32_e32 v131, vcc, 0, v209, vcc
	s_mov_b64 exec, 1
	global_load_dwordx4 v[150:153], v[130:131], off offset:256
	s_mov_b64 exec, -1
	s_and_b64 vcc, exec, s[0:1]
	v_mov_b32_e32 v148, 0
	v_mov_b32_e32 v149, 0
	s_cbranch_vccnz .LBB0_1072
	v_add_co_u32_e32 v130, vcc, 0x24000, v208
	s_nop 1
	v_addc_co_u32_e32 v131, vcc, 0, v209, vcc
	global_load_dwordx4 v[146:149], v[130:131], off offset:256
.LBB0_1072:
	v_add_co_u32_e32 v130, vcc, 0x6000, v208
	v_mov_b32_e32 v138, 0
	s_nop 0
	v_addc_co_u32_e32 v131, vcc, 0, v209, vcc
	s_mov_b64 exec, 1
	global_load_dwordx4 v[142:145], v[130:131], off
	s_mov_b64 exec, -1
	v_mov_b32_e32 v130, 0
	s_and_b64 vcc, exec, s[0:1]
	v_mov_b32_e32 v139, 0
	v_mov_b32_e32 v140, 0
	v_mov_b32_e32 v141, 0
	s_cbranch_vccnz .LBB0_1074
	v_add_co_u32_e32 v132, vcc, 0x26000, v208
	s_nop 1
	v_addc_co_u32_e32 v133, vcc, 0, v209, vcc
	global_load_dwordx4 v[138:141], v[132:133], off
.LBB0_1074:
	v_add_co_u32_e32 v132, vcc, 0x6000, v208
	v_mov_b32_e32 v131, 0
	s_nop 0
	v_addc_co_u32_e32 v133, vcc, 0, v209, vcc
	s_mov_b64 exec, 1
	global_load_dwordx4 v[134:137], v[132:133], off offset:256
	s_mov_b64 exec, -1
	s_and_b64 vcc, exec, s[0:1]
	v_mov_b32_e32 v132, 0
	v_mov_b32_e32 v133, 0
	s_cbranch_vccnz .LBB0_1076
	v_add_co_u32_e32 v130, vcc, 0x26000, v208
	s_nop 1
	v_addc_co_u32_e32 v131, vcc, 0, v209, vcc
	global_load_dwordx4 v[130:133], v[130:131], off offset:256
.LBB0_1076:
	s_waitcnt vmcnt(0)
	v_mov_b32_e32 v190, v222
	v_mov_b32_e32 v191, v223
	v_mov_b32_e32 v192, v233
	v_mov_b32_e32 v193, v234
	v_mov_b32_e32 v182, v235
	v_mov_b32_e32 v183, v238
	v_mov_b32_e32 v184, v242
	v_mov_b32_e32 v185, v243
	v_mov_b32_e32 v174, v244
	v_mov_b32_e32 v175, v245
	v_mov_b32_e32 v176, v246
	v_mov_b32_e32 v177, v247
	v_mov_b32_e32 v166, v248
	v_mov_b32_e32 v167, v249
	v_mov_b32_e32 v168, v250
	v_mov_b32_e32 v169, v251
	v_mov_b32_e32 v158, v194
	v_mov_b32_e32 v159, v195
	v_mov_b32_e32 v160, v196
	v_mov_b32_e32 v161, v197
	v_mov_b32_e32 v150, v225
	v_mov_b32_e32 v151, v226
	v_mov_b32_e32 v152, v227
	v_mov_b32_e32 v153, v228
	v_mov_b32_e32 v142, v229
	v_mov_b32_e32 v143, v230
	v_mov_b32_e32 v144, v231
	v_mov_b32_e32 v145, v232
	v_mov_b32_e32 v134, v236
	v_mov_b32_e32 v135, v237
	v_mov_b32_e32 v136, v239
	v_mov_b32_e32 v137, v240
	v_lshlrev_b32_e32 v212, 16, v190
	v_and_b32_e32 v213, 0xffff0000, v190
	v_mul_f32_e32 v190, 0xbfb8aa3b, v126
	v_exp_f32_e32 v218, v190
	v_mul_f32_e32 v190, 0xbfb8aa3b, v127
	v_exp_f32_e32 v219, v190
	s_lshl_b32 s56, s24, 5
	v_pk_add_f32 v[218:219], v[218:219], 1.0 op_sel_hi:[1,0]
	s_nop 0
	s_nop 0
	v_rcp_f32_e32 v219, v219
	s_nop 0
	s_nop 0
	v_rcp_f32_e32 v218, v218
	s_nop 0
	v_lshlrev_b32_e32 v220, 16, v186
	v_and_b32_e32 v221, 0xffff0000, v186
	v_mul_f32_e32 v186, 0xbfb8aa3b, v128
	v_pk_fma_f32 v[212:213], v[218:219], v[212:213], v[220:221]
	v_exp_f32_e32 v218, v186
	v_mul_f32_e32 v186, 0xbfb8aa3b, v129
	v_exp_f32_e32 v219, v186
	v_lshlrev_b32_e32 v190, 16, v191
	v_and_b32_e32 v191, 0xffff0000, v191
	v_pk_add_f32 v[218:219], v[218:219], 1.0 op_sel_hi:[1,0]
	s_nop 0
	s_nop 0
	v_rcp_f32_e32 v219, v219
	s_nop 0
	s_nop 0
	v_rcp_f32_e32 v218, v218
	s_nop 0
	v_lshlrev_b32_e32 v186, 16, v187
	v_and_b32_e32 v187, 0xffff0000, v187
	v_pk_fma_f32 v[190:191], v[218:219], v[190:191], v[186:187]
	v_lshlrev_b32_e32 v186, 16, v192
	v_and_b32_e32 v187, 0xffff0000, v192
	v_mul_f32_e32 v192, 0xbfb8aa3b, v122
	v_exp_f32_e32 v218, v192
	v_mul_f32_e32 v192, 0xbfb8aa3b, v123
	v_exp_f32_e32 v219, v192
	s_nop 0
	v_pk_add_f32 v[218:219], v[218:219], 1.0 op_sel_hi:[1,0]
	s_nop 0
	s_nop 0
	v_rcp_f32_e32 v219, v219
	s_nop 0
	s_nop 0
	v_lshlrev_b32_e32 v220, 16, v188
	v_and_b32_e32 v221, 0xffff0000, v188
	v_mul_f32_e32 v188, 0xbfb8aa3b, v124
	v_rcp_f32_e32 v218, v218
	s_nop 0
	v_exp_f32_e32 v192, v188
	v_mul_f32_e32 v188, 0xbfb8aa3b, v125
	v_pk_fma_f32 v[218:219], v[218:219], v[186:187], v[220:221]
	v_lshlrev_b32_e32 v186, 16, v193
	v_and_b32_e32 v187, 0xffff0000, v193
	v_exp_f32_e32 v193, v188
	s_nop 0
	v_pk_add_f32 v[192:193], v[192:193], 1.0 op_sel_hi:[1,0]
	s_nop 0
	s_nop 0
	v_rcp_f32_e32 v193, v193
	s_nop 0
	s_nop 0
	v_rcp_f32_e32 v192, v192
	s_nop 0
	v_lshlrev_b32_e32 v188, 16, v189
	v_and_b32_e32 v189, 0xffff0000, v189
	v_pk_fma_f32 v[192:193], v[192:193], v[186:187], v[188:189]
	v_cvt_pk_bf16_f32 v186, v212, v213
	v_cvt_pk_bf16_f32 v187, v190, v191
	v_cvt_pk_bf16_f32 v188, v218, v219
	v_cvt_pk_bf16_f32 v189, v192, v193
	global_store_dwordx4 v[210:211], v[186:189], off
	s_nop 1
	v_lshlrev_b32_e32 v186, 16, v182
	v_and_b32_e32 v187, 0xffff0000, v182
	v_mul_f32_e32 v182, 0xbfb8aa3b, v110
	v_exp_f32_e32 v188, v182
	v_mul_f32_e32 v182, 0xbfb8aa3b, v111
	v_exp_f32_e32 v189, v182
	s_nop 0
	v_pk_add_f32 v[188:189], v[188:189], 1.0 op_sel_hi:[1,0]
	s_nop 0
	s_nop 0
	v_rcp_f32_e32 v189, v189
	s_nop 0
	s_nop 0
	v_rcp_f32_e32 v188, v188
	s_nop 0
	v_lshlrev_b32_e32 v190, 16, v178
	v_and_b32_e32 v191, 0xffff0000, v178
	v_mul_f32_e32 v178, 0xbfb8aa3b, v112
	v_pk_fma_f32 v[186:187], v[188:189], v[186:187], v[190:191]
	v_exp_f32_e32 v188, v178
	v_mul_f32_e32 v178, 0xbfb8aa3b, v113
	v_exp_f32_e32 v189, v178
	v_lshlrev_b32_e32 v182, 16, v183
	v_and_b32_e32 v183, 0xffff0000, v183
	v_pk_add_f32 v[188:189], v[188:189], 1.0 op_sel_hi:[1,0]
	s_nop 0
	s_nop 0
	v_rcp_f32_e32 v189, v189
	s_nop 0
	s_nop 0
	v_rcp_f32_e32 v188, v188
	s_nop 0
	v_lshlrev_b32_e32 v178, 16, v179
	v_and_b32_e32 v179, 0xffff0000, v179
	v_pk_fma_f32 v[182:183], v[188:189], v[182:183], v[178:179]
	v_lshlrev_b32_e32 v178, 16, v184
	v_and_b32_e32 v179, 0xffff0000, v184
	v_mul_f32_e32 v184, 0xbfb8aa3b, v106
	v_exp_f32_e32 v188, v184
	v_mul_f32_e32 v184, 0xbfb8aa3b, v107
	v_exp_f32_e32 v189, v184
	s_nop 0
	v_pk_add_f32 v[188:189], v[188:189], 1.0 op_sel_hi:[1,0]
	s_nop 0
	s_nop 0
	v_rcp_f32_e32 v189, v189
	s_nop 0
	s_nop 0
	v_lshlrev_b32_e32 v190, 16, v180
	v_and_b32_e32 v191, 0xffff0000, v180
	v_mul_f32_e32 v180, 0xbfb8aa3b, v108
	v_rcp_f32_e32 v188, v188
	s_nop 0
	v_exp_f32_e32 v184, v180
	v_mul_f32_e32 v180, 0xbfb8aa3b, v109
	v_pk_fma_f32 v[188:189], v[188:189], v[178:179], v[190:191]
	v_lshlrev_b32_e32 v178, 16, v185
	v_and_b32_e32 v179, 0xffff0000, v185
	v_exp_f32_e32 v185, v180
	s_nop 0
	v_pk_add_f32 v[184:185], v[184:185], 1.0 op_sel_hi:[1,0]
	s_nop 0
	s_nop 0
	v_rcp_f32_e32 v185, v185
	s_nop 0
	s_nop 0
	v_rcp_f32_e32 v184, v184
	s_nop 0
	v_lshlrev_b32_e32 v180, 16, v181
	v_and_b32_e32 v181, 0xffff0000, v181
	v_pk_fma_f32 v[184:185], v[184:185], v[178:179], v[180:181]
	v_cvt_pk_bf16_f32 v178, v186, v187
	v_cvt_pk_bf16_f32 v179, v182, v183
	v_cvt_pk_bf16_f32 v180, v188, v189
	v_cvt_pk_bf16_f32 v181, v184, v185
	global_store_dwordx4 v[210:211], v[178:181], off offset:256
	v_mov_b32_e32 v188, 0
	v_mov_b32_e32 v189, 0
	v_lshlrev_b32_e32 v180, 16, v174
	v_and_b32_e32 v181, 0xffff0000, v174
	v_mul_f32_e32 v174, 0xbfb8aa3b, v118
	v_exp_f32_e32 v182, v174
	v_mul_f32_e32 v174, 0xbfb8aa3b, v119
	v_exp_f32_e32 v183, v174
	v_lshl_add_u64 v[178:179], v[210:211], 0, s[56:57]
	v_pk_add_f32 v[182:183], v[182:183], 1.0 op_sel_hi:[1,0]
	s_nop 0
	s_nop 0
	v_rcp_f32_e32 v183, v183
	s_nop 0
	s_nop 0
	v_rcp_f32_e32 v182, v182
	s_nop 0
	v_lshlrev_b32_e32 v184, 16, v170
	v_and_b32_e32 v185, 0xffff0000, v170
	v_mul_f32_e32 v170, 0xbfb8aa3b, v120
	v_pk_fma_f32 v[180:181], v[182:183], v[180:181], v[184:185]
	v_exp_f32_e32 v182, v170
	v_mul_f32_e32 v170, 0xbfb8aa3b, v121
	v_exp_f32_e32 v183, v170
	v_lshlrev_b32_e32 v174, 16, v175
	v_and_b32_e32 v175, 0xffff0000, v175
	v_pk_add_f32 v[182:183], v[182:183], 1.0 op_sel_hi:[1,0]
	s_nop 0
	s_nop 0
	v_rcp_f32_e32 v183, v183
	s_nop 0
	s_nop 0
	v_rcp_f32_e32 v182, v182
	s_nop 0
	v_lshlrev_b32_e32 v170, 16, v171
	v_and_b32_e32 v171, 0xffff0000, v171
	v_pk_fma_f32 v[174:175], v[182:183], v[174:175], v[170:171]
	v_lshlrev_b32_e32 v170, 16, v176
	v_and_b32_e32 v171, 0xffff0000, v176
	v_mul_f32_e32 v176, 0xbfb8aa3b, v114
	v_exp_f32_e32 v182, v176
	v_mul_f32_e32 v176, 0xbfb8aa3b, v115
	v_exp_f32_e32 v183, v176
	s_nop 0
	v_pk_add_f32 v[182:183], v[182:183], 1.0 op_sel_hi:[1,0]
	s_nop 0
	s_nop 0
	v_rcp_f32_e32 v183, v183
	s_nop 0
	s_nop 0
	v_lshlrev_b32_e32 v184, 16, v172
	v_and_b32_e32 v185, 0xffff0000, v172
	v_mul_f32_e32 v172, 0xbfb8aa3b, v116
	v_rcp_f32_e32 v182, v182
	s_nop 0
	v_exp_f32_e32 v176, v172
	v_mul_f32_e32 v172, 0xbfb8aa3b, v117
	v_pk_fma_f32 v[182:183], v[182:183], v[170:171], v[184:185]
	v_lshlrev_b32_e32 v170, 16, v177
	v_and_b32_e32 v171, 0xffff0000, v177
	v_exp_f32_e32 v177, v172
	s_nop 0
	v_pk_add_f32 v[176:177], v[176:177], 1.0 op_sel_hi:[1,0]
	s_nop 0
	s_nop 0
	v_rcp_f32_e32 v177, v177
	s_nop 0
	s_nop 0
	v_rcp_f32_e32 v176, v176
	s_nop 0
	v_lshlrev_b32_e32 v172, 16, v173
	v_and_b32_e32 v173, 0xffff0000, v173
	v_pk_fma_f32 v[176:177], v[176:177], v[170:171], v[172:173]
	v_cvt_pk_bf16_f32 v170, v180, v181
	v_cvt_pk_bf16_f32 v171, v174, v175
	v_cvt_pk_bf16_f32 v172, v182, v183
	v_cvt_pk_bf16_f32 v173, v176, v177
	global_store_dwordx4 v[178:179], v[170:173], off
	v_mov_b32_e32 v186, 0
	v_mov_b32_e32 v187, 0
	v_lshlrev_b32_e32 v170, 16, v166
	v_and_b32_e32 v171, 0xffff0000, v166
	v_mul_f32_e32 v166, 0xbfb8aa3b, v94
	v_exp_f32_e32 v172, v166
	v_mul_f32_e32 v166, 0xbfb8aa3b, v95
	v_exp_f32_e32 v173, v166
	s_nop 0
	v_pk_add_f32 v[172:173], v[172:173], 1.0 op_sel_hi:[1,0]
	s_nop 0
	s_nop 0
	v_rcp_f32_e32 v173, v173
	s_nop 0
	s_nop 0
	v_rcp_f32_e32 v172, v172
	s_nop 0
	v_lshlrev_b32_e32 v174, 16, v162
	v_and_b32_e32 v175, 0xffff0000, v162
	v_mul_f32_e32 v162, 0xbfb8aa3b, v96
	v_pk_fma_f32 v[170:171], v[172:173], v[170:171], v[174:175]
	v_exp_f32_e32 v172, v162
	v_mul_f32_e32 v162, 0xbfb8aa3b, v97
	v_exp_f32_e32 v173, v162
	v_lshlrev_b32_e32 v166, 16, v167
	v_and_b32_e32 v167, 0xffff0000, v167
	v_pk_add_f32 v[172:173], v[172:173], 1.0 op_sel_hi:[1,0]
	s_nop 0
	s_nop 0
	v_rcp_f32_e32 v173, v173
	s_nop 0
	s_nop 0
	v_rcp_f32_e32 v172, v172
	s_nop 0
	v_lshlrev_b32_e32 v162, 16, v163
	v_and_b32_e32 v163, 0xffff0000, v163
	v_pk_fma_f32 v[166:167], v[172:173], v[166:167], v[162:163]
	v_lshlrev_b32_e32 v162, 16, v168
	v_and_b32_e32 v163, 0xffff0000, v168
	v_mul_f32_e32 v168, 0xbfb8aa3b, v90
	v_exp_f32_e32 v172, v168
	v_mul_f32_e32 v168, 0xbfb8aa3b, v91
	v_exp_f32_e32 v173, v168
	s_nop 0
	v_pk_add_f32 v[172:173], v[172:173], 1.0 op_sel_hi:[1,0]
	s_nop 0
	s_nop 0
	v_rcp_f32_e32 v173, v173
	s_nop 0
	s_nop 0
	v_lshlrev_b32_e32 v174, 16, v164
	v_and_b32_e32 v175, 0xffff0000, v164
	v_mul_f32_e32 v164, 0xbfb8aa3b, v92
	v_rcp_f32_e32 v172, v172
	s_nop 0
	v_exp_f32_e32 v168, v164
	v_mul_f32_e32 v164, 0xbfb8aa3b, v93
	v_pk_fma_f32 v[172:173], v[172:173], v[162:163], v[174:175]
	v_lshlrev_b32_e32 v162, 16, v169
	v_and_b32_e32 v163, 0xffff0000, v169
	v_exp_f32_e32 v169, v164
	s_nop 0
	v_pk_add_f32 v[168:169], v[168:169], 1.0 op_sel_hi:[1,0]
	s_nop 0
	s_nop 0
	v_rcp_f32_e32 v169, v169
	s_nop 0
	s_nop 0
	v_rcp_f32_e32 v168, v168
	s_nop 0
	v_lshlrev_b32_e32 v164, 16, v165
	v_and_b32_e32 v165, 0xffff0000, v165
	v_pk_fma_f32 v[168:169], v[168:169], v[162:163], v[164:165]
	v_cvt_pk_bf16_f32 v162, v170, v171
	v_cvt_pk_bf16_f32 v163, v166, v167
	v_cvt_pk_bf16_f32 v164, v172, v173
	v_cvt_pk_bf16_f32 v165, v168, v169
	global_store_dwordx4 v[178:179], v[162:165], off offset:256
	s_nop 1
	v_lshlrev_b32_e32 v164, 16, v158
	v_and_b32_e32 v165, 0xffff0000, v158
	v_mul_f32_e32 v158, 0xbfb8aa3b, v102
	v_exp_f32_e32 v166, v158
	v_mul_f32_e32 v158, 0xbfb8aa3b, v103
	v_exp_f32_e32 v167, v158
	v_lshl_add_u64 v[162:163], v[178:179], 0, s[56:57]
	v_lshl_add_u64 v[210:211], v[162:163], 0, s[56:57]
	v_mov_b32_e32 v178, 0
	v_pk_add_f32 v[166:167], v[166:167], 1.0 op_sel_hi:[1,0]
	s_nop 0
	s_nop 0
	v_rcp_f32_e32 v167, v167
	s_nop 0
	s_nop 0
	v_rcp_f32_e32 v166, v166
	s_nop 0
	v_lshlrev_b32_e32 v168, 16, v154
	v_and_b32_e32 v169, 0xffff0000, v154
	v_mul_f32_e32 v154, 0xbfb8aa3b, v104
	v_pk_fma_f32 v[164:165], v[166:167], v[164:165], v[168:169]
	v_exp_f32_e32 v166, v154
	v_mul_f32_e32 v154, 0xbfb8aa3b, v105
	v_exp_f32_e32 v167, v154
	v_lshlrev_b32_e32 v158, 16, v159
	v_and_b32_e32 v159, 0xffff0000, v159
	v_pk_add_f32 v[166:167], v[166:167], 1.0 op_sel_hi:[1,0]
	s_nop 0
	s_nop 0
	v_rcp_f32_e32 v167, v167
	s_nop 0
	s_nop 0
	v_rcp_f32_e32 v166, v166
	s_nop 0
	v_lshlrev_b32_e32 v154, 16, v155
	v_and_b32_e32 v155, 0xffff0000, v155
	v_pk_fma_f32 v[158:159], v[166:167], v[158:159], v[154:155]
	v_lshlrev_b32_e32 v154, 16, v160
	v_and_b32_e32 v155, 0xffff0000, v160
	v_mul_f32_e32 v160, 0xbfb8aa3b, v98
	v_exp_f32_e32 v166, v160
	v_mul_f32_e32 v160, 0xbfb8aa3b, v99
	v_exp_f32_e32 v167, v160
	s_nop 0
	v_pk_add_f32 v[166:167], v[166:167], 1.0 op_sel_hi:[1,0]
	s_nop 0
	s_nop 0
	v_rcp_f32_e32 v167, v167
	s_nop 0
	s_nop 0
	v_lshlrev_b32_e32 v168, 16, v156
	v_and_b32_e32 v169, 0xffff0000, v156
	v_mul_f32_e32 v156, 0xbfb8aa3b, v100
	v_rcp_f32_e32 v166, v166
	s_nop 0
	v_exp_f32_e32 v160, v156
	v_mul_f32_e32 v156, 0xbfb8aa3b, v101
	v_pk_fma_f32 v[166:167], v[166:167], v[154:155], v[168:169]
	v_lshlrev_b32_e32 v154, 16, v161
	v_and_b32_e32 v155, 0xffff0000, v161
	v_exp_f32_e32 v161, v156
	s_nop 0
	v_pk_add_f32 v[160:161], v[160:161], 1.0 op_sel_hi:[1,0]
	s_nop 0
	s_nop 0
	v_rcp_f32_e32 v161, v161
	s_nop 0
	s_nop 0
	v_rcp_f32_e32 v160, v160
	s_nop 0
	v_lshlrev_b32_e32 v156, 16, v157
	v_and_b32_e32 v157, 0xffff0000, v157
	v_pk_fma_f32 v[160:161], v[160:161], v[154:155], v[156:157]
	v_cvt_pk_bf16_f32 v154, v164, v165
	v_cvt_pk_bf16_f32 v155, v158, v159
	v_cvt_pk_bf16_f32 v156, v166, v167
	v_cvt_pk_bf16_f32 v157, v160, v161
	global_store_dwordx4 v[162:163], v[154:157], off
	s_nop 1
	v_lshlrev_b32_e32 v154, 16, v150
	v_and_b32_e32 v155, 0xffff0000, v150
	v_mul_f32_e32 v150, 0xbfb8aa3b, v78
	v_exp_f32_e32 v156, v150
	v_mul_f32_e32 v150, 0xbfb8aa3b, v79
	v_exp_f32_e32 v157, v150
	s_nop 0
	v_pk_add_f32 v[156:157], v[156:157], 1.0 op_sel_hi:[1,0]
	s_nop 0
	s_nop 0
	v_rcp_f32_e32 v157, v157
	s_nop 0
	s_nop 0
	v_rcp_f32_e32 v156, v156
	s_nop 0
	v_lshlrev_b32_e32 v158, 16, v146
	v_and_b32_e32 v159, 0xffff0000, v146
	v_mul_f32_e32 v146, 0xbfb8aa3b, v80
	v_pk_fma_f32 v[154:155], v[156:157], v[154:155], v[158:159]
	v_exp_f32_e32 v156, v146
	v_mul_f32_e32 v146, 0xbfb8aa3b, v81
	v_exp_f32_e32 v157, v146
	v_lshlrev_b32_e32 v150, 16, v151
	v_and_b32_e32 v151, 0xffff0000, v151
	v_pk_add_f32 v[156:157], v[156:157], 1.0 op_sel_hi:[1,0]
	s_nop 0
	s_nop 0
	v_rcp_f32_e32 v157, v157
	s_nop 0
	s_nop 0
	v_rcp_f32_e32 v156, v156
	s_nop 0
	v_lshlrev_b32_e32 v146, 16, v147
	v_and_b32_e32 v147, 0xffff0000, v147
	v_pk_fma_f32 v[150:151], v[156:157], v[150:151], v[146:147]
	v_lshlrev_b32_e32 v146, 16, v152
	v_and_b32_e32 v147, 0xffff0000, v152
	v_mul_f32_e32 v152, 0xbfb8aa3b, v74
	v_exp_f32_e32 v156, v152
	v_mul_f32_e32 v152, 0xbfb8aa3b, v75
	v_exp_f32_e32 v157, v152
	s_nop 0
	v_pk_add_f32 v[156:157], v[156:157], 1.0 op_sel_hi:[1,0]
	s_nop 0
	s_nop 0
	v_rcp_f32_e32 v157, v157
	s_nop 0
	s_nop 0
	v_lshlrev_b32_e32 v158, 16, v148
	v_and_b32_e32 v159, 0xffff0000, v148
	v_mul_f32_e32 v148, 0xbfb8aa3b, v76
	v_rcp_f32_e32 v156, v156
	s_nop 0
	v_exp_f32_e32 v152, v148
	v_mul_f32_e32 v148, 0xbfb8aa3b, v77
	v_pk_fma_f32 v[156:157], v[156:157], v[146:147], v[158:159]
	v_lshlrev_b32_e32 v146, 16, v153
	v_and_b32_e32 v147, 0xffff0000, v153
	v_exp_f32_e32 v153, v148
	s_nop 0
	v_pk_add_f32 v[152:153], v[152:153], 1.0 op_sel_hi:[1,0]
	s_nop 0
	s_nop 0
	v_rcp_f32_e32 v153, v153
	s_nop 0
	s_nop 0
	v_rcp_f32_e32 v152, v152
	s_nop 0
	v_lshlrev_b32_e32 v148, 16, v149
	v_and_b32_e32 v149, 0xffff0000, v149
	v_pk_fma_f32 v[152:153], v[152:153], v[146:147], v[148:149]
	v_cvt_pk_bf16_f32 v146, v154, v155
	v_cvt_pk_bf16_f32 v147, v150, v151
	v_cvt_pk_bf16_f32 v148, v156, v157
	v_cvt_pk_bf16_f32 v149, v152, v153
	global_store_dwordx4 v[162:163], v[146:149], off offset:256
	s_nop 1
	v_lshlrev_b32_e32 v146, 16, v142
	v_and_b32_e32 v147, 0xffff0000, v142
	v_mul_f32_e32 v142, 0xbfb8aa3b, v86
	v_exp_f32_e32 v148, v142
	v_mul_f32_e32 v142, 0xbfb8aa3b, v87
	v_exp_f32_e32 v149, v142
	s_nop 0
	v_pk_add_f32 v[148:149], v[148:149], 1.0 op_sel_hi:[1,0]
	s_nop 0
	s_nop 0
	v_rcp_f32_e32 v149, v149
	s_nop 0
	s_nop 0
	v_rcp_f32_e32 v148, v148
	s_nop 0
	v_lshlrev_b32_e32 v150, 16, v138
	v_and_b32_e32 v151, 0xffff0000, v138
	v_mul_f32_e32 v138, 0xbfb8aa3b, v88
	v_pk_fma_f32 v[146:147], v[148:149], v[146:147], v[150:151]
	v_exp_f32_e32 v148, v138
	v_mul_f32_e32 v138, 0xbfb8aa3b, v89
	v_exp_f32_e32 v149, v138
	v_lshlrev_b32_e32 v142, 16, v143
	v_and_b32_e32 v143, 0xffff0000, v143
	v_pk_add_f32 v[148:149], v[148:149], 1.0 op_sel_hi:[1,0]
	s_nop 0
	s_nop 0
	v_rcp_f32_e32 v149, v149
	s_nop 0
	s_nop 0
	v_rcp_f32_e32 v148, v148
	s_nop 0
	v_lshlrev_b32_e32 v138, 16, v139
	v_and_b32_e32 v139, 0xffff0000, v139
	v_pk_fma_f32 v[142:143], v[148:149], v[142:143], v[138:139]
	v_lshlrev_b32_e32 v138, 16, v144
	v_and_b32_e32 v139, 0xffff0000, v144
	v_mul_f32_e32 v144, 0xbfb8aa3b, v82
	v_exp_f32_e32 v148, v144
	v_mul_f32_e32 v144, 0xbfb8aa3b, v83
	v_exp_f32_e32 v149, v144
	s_nop 0
	v_pk_add_f32 v[148:149], v[148:149], 1.0 op_sel_hi:[1,0]
	s_nop 0
	s_nop 0
	v_rcp_f32_e32 v149, v149
	s_nop 0
	s_nop 0
	v_lshlrev_b32_e32 v150, 16, v140
	v_and_b32_e32 v151, 0xffff0000, v140
	v_mul_f32_e32 v140, 0xbfb8aa3b, v84
	v_rcp_f32_e32 v148, v148
	s_nop 0
	v_exp_f32_e32 v144, v140
	v_mul_f32_e32 v140, 0xbfb8aa3b, v85
	v_pk_fma_f32 v[148:149], v[148:149], v[138:139], v[150:151]
	v_lshlrev_b32_e32 v138, 16, v145
	v_and_b32_e32 v139, 0xffff0000, v145
	v_exp_f32_e32 v145, v140
	s_nop 0
	v_pk_add_f32 v[144:145], v[144:145], 1.0 op_sel_hi:[1,0]
	s_nop 0
	s_nop 0
	v_rcp_f32_e32 v145, v145
	s_nop 0
	s_nop 0
	v_rcp_f32_e32 v144, v144
	s_nop 0
	v_lshlrev_b32_e32 v140, 16, v141
	v_and_b32_e32 v141, 0xffff0000, v141
	v_pk_fma_f32 v[144:145], v[144:145], v[138:139], v[140:141]
	v_cvt_pk_bf16_f32 v138, v146, v147
	v_cvt_pk_bf16_f32 v139, v142, v143
	v_cvt_pk_bf16_f32 v140, v148, v149
	v_cvt_pk_bf16_f32 v141, v144, v145
	global_store_dwordx4 v[210:211], v[138:141], off
	s_nop 1
	v_lshlrev_b32_e32 v138, 16, v134
	v_and_b32_e32 v139, 0xffff0000, v134
	v_mul_f32_e32 v134, 0xbfb8aa3b, v70
	v_exp_f32_e32 v140, v134
	v_mul_f32_e32 v134, 0xbfb8aa3b, v71
	v_exp_f32_e32 v141, v134
	s_nop 0
	v_pk_add_f32 v[140:141], v[140:141], 1.0 op_sel_hi:[1,0]
	s_nop 0
	s_nop 0
	v_rcp_f32_e32 v141, v141
	s_nop 0
	s_nop 0
	v_rcp_f32_e32 v140, v140
	s_nop 0
	v_lshlrev_b32_e32 v142, 16, v130
	v_and_b32_e32 v143, 0xffff0000, v130
	v_mul_f32_e32 v130, 0xbfb8aa3b, v72
	v_pk_fma_f32 v[138:139], v[140:141], v[138:139], v[142:143]
	v_exp_f32_e32 v140, v130
	v_mul_f32_e32 v130, 0xbfb8aa3b, v73
	v_exp_f32_e32 v141, v130
	v_lshlrev_b32_e32 v134, 16, v135
	v_and_b32_e32 v135, 0xffff0000, v135
	v_pk_add_f32 v[140:141], v[140:141], 1.0 op_sel_hi:[1,0]
	s_nop 0
	s_nop 0
	v_rcp_f32_e32 v141, v141
	s_nop 0
	s_nop 0
	v_rcp_f32_e32 v140, v140
	s_nop 0
	v_lshlrev_b32_e32 v130, 16, v131
	v_and_b32_e32 v131, 0xffff0000, v131
	v_pk_fma_f32 v[134:135], v[140:141], v[134:135], v[130:131]
	v_lshlrev_b32_e32 v130, 16, v136
	v_and_b32_e32 v131, 0xffff0000, v136
	v_mul_f32_e32 v136, 0xbfb8aa3b, v66
	v_exp_f32_e32 v140, v136
	v_mul_f32_e32 v136, 0xbfb8aa3b, v67
	v_exp_f32_e32 v141, v136
	s_nop 0
	v_pk_add_f32 v[140:141], v[140:141], 1.0 op_sel_hi:[1,0]
	s_nop 0
	s_nop 0
	v_rcp_f32_e32 v141, v141
	s_nop 0
	s_nop 0
	v_lshlrev_b32_e32 v142, 16, v132
	v_and_b32_e32 v143, 0xffff0000, v132
	v_mul_f32_e32 v132, 0xbfb8aa3b, v68
	v_rcp_f32_e32 v140, v140
	s_nop 0
	v_exp_f32_e32 v136, v132
	v_mul_f32_e32 v132, 0xbfb8aa3b, v69
	v_pk_fma_f32 v[140:141], v[140:141], v[130:131], v[142:143]
	v_lshlrev_b32_e32 v130, 16, v137
	v_and_b32_e32 v131, 0xffff0000, v137
	v_exp_f32_e32 v137, v132
	s_nop 0
	v_pk_add_f32 v[136:137], v[136:137], 1.0 op_sel_hi:[1,0]
	s_nop 0
	s_nop 0
	v_rcp_f32_e32 v137, v137
	s_nop 0
	s_nop 0
	v_rcp_f32_e32 v136, v136
	s_nop 0
	v_lshlrev_b32_e32 v132, 16, v133
	v_and_b32_e32 v133, 0xffff0000, v133
	v_pk_fma_f32 v[136:137], v[136:137], v[130:131], v[132:133]
	v_cvt_pk_bf16_f32 v130, v138, v139
	v_cvt_pk_bf16_f32 v131, v134, v135
	v_cvt_pk_bf16_f32 v132, v140, v141
	v_cvt_pk_bf16_f32 v133, v136, v137
	global_store_dwordx4 v[210:211], v[130:133], off offset:256
	s_nop 1
	v_add_co_u32_e32 v130, vcc, 0x10000, v208
	s_nop 1
	v_addc_co_u32_e32 v131, vcc, 0, v209, vcc
	global_load_dwordx4 v[190:193], v[130:131], off
	s_and_b64 vcc, exec, s[0:1]
	s_cbranch_vccnz .LBB0_1078
	v_add_co_u32_e32 v130, vcc, 0x30000, v208
	s_nop 1
	v_addc_co_u32_e32 v131, vcc, 0, v209, vcc
	global_load_dwordx4 v[186:189], v[130:131], off

.LBB0_1093:
	s_and_b64 vcc, exec, s[24:25]
	s_cbranch_vccz .LBB0_1049
	v_cvt_pk_bf16_f32 v110, v110, v111
	v_cvt_pk_bf16_f32 v111, v112, v113
	v_cvt_pk_bf16_f32 v112, v106, v107
	v_cvt_pk_bf16_f32 v113, v108, v109
	s_movk_i32 s0, 0x2000
	v_mov_b32_e32 v235, v110
	v_mov_b32_e32 v238, v111
	v_mov_b32_e32 v242, v112
	v_mov_b32_e32 v243, v113
	s_mov_b64 exec, 1
	global_store_dwordx4 v[208:209], v[110:113], off offset:256
	s_mov_b64 exec, -1
	v_cvt_pk_bf16_f32 v94, v94, v95
	v_cvt_pk_bf16_f32 v95, v96, v97
	v_add_co_u32_e32 v110, vcc, s0, v208
	v_cvt_pk_bf16_f32 v96, v90, v91
	s_nop 0
	v_addc_co_u32_e32 v111, vcc, 0, v209, vcc
	v_cvt_pk_bf16_f32 v97, v92, v93
	s_movk_i32 s0, 0x4000
	v_mov_b32_e32 v248, v94
	v_mov_b32_e32 v249, v95
	v_mov_b32_e32 v250, v96
	v_mov_b32_e32 v251, v97
	s_mov_b64 exec, 1
	global_store_dwordx4 v[110:111], v[94:97], off offset:256
	s_mov_b64 exec, -1
	v_cvt_pk_bf16_f32 v78, v78, v79
	v_cvt_pk_bf16_f32 v79, v80, v81
	v_add_co_u32_e32 v94, vcc, s0, v208
	v_cvt_pk_bf16_f32 v80, v74, v75
	s_nop 0
	v_addc_co_u32_e32 v95, vcc, 0, v209, vcc
	v_cvt_pk_bf16_f32 v81, v76, v77
	s_movk_i32 s0, 0x6000
	v_mov_b32_e32 v225, v78
	v_mov_b32_e32 v226, v79
	v_mov_b32_e32 v227, v80
	v_mov_b32_e32 v228, v81
	s_mov_b64 exec, 1
	global_store_dwordx4 v[94:95], v[78:81], off offset:256
	s_mov_b64 exec, -1
	v_cvt_pk_bf16_f32 v62, v62, v63
	v_cvt_pk_bf16_f32 v63, v64, v65
	v_add_co_u32_e32 v78, vcc, s0, v208
	v_cvt_pk_bf16_f32 v64, v58, v59
	s_nop 0
	v_addc_co_u32_e32 v79, vcc, 0, v209, vcc
	v_add_co_u32_e32 v58, vcc, s89, v208
	v_cvt_pk_bf16_f32 v44, v44, v45
	s_nop 0
	v_addc_co_u32_e32 v59, vcc, 0, v209, vcc
	v_cvt_pk_bf16_f32 v45, v46, v47
	v_cvt_pk_bf16_f32 v46, v40, v41
	v_cvt_pk_bf16_f32 v47, v42, v43
	s_mov_b32 s0, 0x12000
	global_store_dwordx4 v[58:59], v[44:47], off offset:256
	v_cvt_pk_bf16_f32 v28, v28, v29
	v_cvt_pk_bf16_f32 v29, v30, v31
	v_add_co_u32_e32 v44, vcc, s0, v208
	v_cvt_pk_bf16_f32 v30, v24, v25
	s_nop 0
	v_addc_co_u32_e32 v45, vcc, 0, v209, vcc
	v_cvt_pk_bf16_f32 v31, v26, v27
	s_mov_b32 s0, 0x14000
	global_store_dwordx4 v[44:45], v[28:31], off offset:256
	v_cvt_pk_bf16_f32 v12, v12, v13
	v_cvt_pk_bf16_f32 v13, v14, v15
	v_add_co_u32_e32 v28, vcc, s0, v208
	v_cvt_pk_bf16_f32 v14, v8, v9
	s_nop 0
	v_addc_co_u32_e32 v29, vcc, 0, v209, vcc
	v_cvt_pk_bf16_f32 v15, v10, v11
	s_mov_b32 s0, 0x16000
	global_store_dwordx4 v[28:29], v[12:15], off offset:256
	v_cvt_pk_bf16_f32 v126, v126, v127
	v_cvt_pk_bf16_f32 v127, v128, v129
	v_add_co_u32_e32 v12, vcc, s0, v208
	v_cvt_pk_bf16_f32 v128, v122, v123
	v_cvt_pk_bf16_f32 v129, v124, v125
	v_cvt_pk_bf16_f32 v106, v118, v119
	v_cvt_pk_bf16_f32 v107, v120, v121
	v_cvt_pk_bf16_f32 v108, v114, v115
	v_cvt_pk_bf16_f32 v109, v116, v117
	v_cvt_pk_bf16_f32 v90, v102, v103
	v_cvt_pk_bf16_f32 v91, v104, v105
	v_cvt_pk_bf16_f32 v92, v98, v99
	v_cvt_pk_bf16_f32 v93, v100, v101
	v_cvt_pk_bf16_f32 v74, v86, v87
	v_cvt_pk_bf16_f32 v75, v88, v89
	v_cvt_pk_bf16_f32 v76, v82, v83
	v_cvt_pk_bf16_f32 v77, v84, v85
	v_cvt_pk_bf16_f32 v70, v70, v71
	v_cvt_pk_bf16_f32 v71, v72, v73
	v_cvt_pk_bf16_f32 v72, v66, v67
	v_cvt_pk_bf16_f32 v73, v68, v69
	v_cvt_pk_bf16_f32 v65, v60, v61
	v_cvt_pk_bf16_f32 v40, v54, v55
	v_cvt_pk_bf16_f32 v41, v56, v57
	v_cvt_pk_bf16_f32 v42, v50, v51
	v_cvt_pk_bf16_f32 v43, v52, v53
	v_cvt_pk_bf16_f32 v24, v36, v37
	v_cvt_pk_bf16_f32 v25, v38, v39
	v_cvt_pk_bf16_f32 v26, v32, v33
	v_cvt_pk_bf16_f32 v27, v34, v35
	v_cvt_pk_bf16_f32 v8, v20, v21
	v_cvt_pk_bf16_f32 v9, v22, v23
	v_cvt_pk_bf16_f32 v10, v16, v17
	v_cvt_pk_bf16_f32 v11, v18, v19
	v_addc_co_u32_e32 v13, vcc, 0, v209, vcc
	v_cvt_pk_bf16_f32 v4, v4, v5
	v_cvt_pk_bf16_f32 v5, v6, v7
	v_cvt_pk_bf16_f32 v6, v0, v1
	v_cvt_pk_bf16_f32 v7, v2, v3
	v_mov_b32_e32 v222, v126
	v_mov_b32_e32 v223, v127
	v_mov_b32_e32 v233, v128
	v_mov_b32_e32 v234, v129
	s_mov_b64 exec, 1
	global_store_dwordx4 v[208:209], v[126:129], off
	s_mov_b64 exec, -1
	v_mov_b32_e32 v244, v106
	v_mov_b32_e32 v245, v107
	v_mov_b32_e32 v246, v108
	v_mov_b32_e32 v247, v109
	s_mov_b64 exec, 1
	global_store_dwordx4 v[110:111], v[106:109], off
	s_mov_b64 exec, -1
	v_mov_b32_e32 v194, v90
	v_mov_b32_e32 v195, v91
	v_mov_b32_e32 v196, v92
	v_mov_b32_e32 v197, v93
	s_mov_b64 exec, 1
	global_store_dwordx4 v[94:95], v[90:93], off
	s_mov_b64 exec, -1
	v_mov_b32_e32 v229, v74
	v_mov_b32_e32 v230, v75
	v_mov_b32_e32 v231, v76
	v_mov_b32_e32 v232, v77
	s_mov_b64 exec, 1
	global_store_dwordx4 v[78:79], v[74:77], off
	s_mov_b64 exec, -1
	v_mov_b32_e32 v236, v70
	v_mov_b32_e32 v237, v71
	v_mov_b32_e32 v239, v72
	v_mov_b32_e32 v240, v73
	s_mov_b64 exec, 1
	global_store_dwordx4 v[78:79], v[70:73], off offset:256
	s_mov_b64 exec, -1
	global_store_dwordx4 v[58:59], v[62:65], off
	global_store_dwordx4 v[44:45], v[40:43], off
	global_store_dwordx4 v[28:29], v[24:27], off
	global_store_dwordx4 v[12:13], v[8:11], off
	global_store_dwordx4 v[12:13], v[4:7], off offset:256
	s_branch .LBB0_1049
.LBB0_1095:
	s_waitcnt vmcnt(0)
	v_lshlrev_b32_e32 v222, 2, v224
	v_add_u32_e32 v222, 0x20000, v222
	ds_read_b32 v196, v222
	ds_read_b32 v197, v222 offset:2048
	ds_read_b32 v225, v222 offset:4096
	ds_read_b32 v226, v222 offset:6144
	ds_read_b32 v227, v222 offset:8192
	ds_read_b32 v228, v222 offset:10240
	ds_read_b32 v229, v222 offset:12288
	ds_read_b32 v230, v222 offset:14336
	ds_read_b32 v231, v222 offset:16384
	ds_read_b32 v232, v222 offset:18432
	ds_read_b32 v236, v222 offset:20480
	ds_read_b32 v237, v222 offset:22528
	ds_read_b32 v239, v222 offset:24576
	ds_read_b32 v240, v222 offset:26624
	s_waitcnt lgkmcnt(0)
	s_cmpk_gt_u32 s37, 0xff
	s_movk_i32 s55, 0x900
	s_cbranch_scc1 .LBB0_1097
	s_barrier
